# LDS-DMA loads use SGPR base + 32-bit VGPR offset (no 64-bit VALU address adds in the loader role), on top of v9
# speedup vs baseline: 1.0081x; 1.0081x over previous
; #define PG8_STAGE(bufoff, gbase, voff) do { _Pragma("unroll") for (int _i = 0; _i < 2; ++_i) \
;         __builtin_amdgcn_global_load_lds((const unsigned*)((const char*)(gbase) + (voff)[_i]), (PG8_LAS unsigned*)(lds + (bufoff) + ldsw + _i * 8192), 16, 0, 0); } while (0)
; #define PG8_LDA(dst, b, h) do { _Pragma("unroll") for (int m = 0; m < 4; ++m) _Pragma("unroll") for (int k = 0; k < 2; ++k) dst[m][k] = *(const PG8_LAS bf16x8*)(lds + PG8_SA(b, h) + aoff + m * 2048 + k * 1024); } while (0)
; #define PG8_LDB(dst, b, h) do { _Pragma("unroll") for (int n = 0; n < 2; ++n) _Pragma("unroll") for (int k = 0; k < 2; ++k) dst[n][k] = *(const PG8_LAS bf16x8*)(lds + PG8_SB(b, h) + boff + n * 2048 + k * 1024); } while (0)
; #define PG8_MMA(ai, bj, At, Bt) do { __builtin_amdgcn_s_setprio(1); _Pragma("unroll") for (int m = 0; m < 4; ++m) _Pragma("unroll") for (int n = 0; n < 2; ++n) _Pragma("unroll") for (int k = 0; k < 2; ++k) \
;         acc[ai][bj][m][n] = __builtin_amdgcn_mfma_f32_16x16x32_bf16(Bt[n][k], At[m][k], acc[ai][bj][m][n], 0, 0, 0); __builtin_amdgcn_s_setprio(0); } while (0)
; #define PG8_WAIT_V(n) asm volatile("s_waitcnt vmcnt(" #n ")" ::: "memory")
; #define PG8_WAIT_L(n) asm volatile("s_waitcnt lgkmcnt(" #n ")" ::: "memory")
; #define PG8_BAR __builtin_amdgcn_s_barrier()
; #define PG8_SCHED __builtin_amdgcn_sched_barrier(0)
; template <class Epi, class Sched, bool ALIGN_EPI = false, bool SP2 = true>
; __device__ __forceinline__ void gemm_phase(PG8_LAS unsigned char* lds, const Gemm g, const Sched& S, const Epi& E) {
;     ...
;             PG8_LDB(B0, 0, 0); PG8_LDB(B1, 0, 1); PG8_SCHED; PG8_LDA(At, 0, 0); PG8_STAGE(PG8_SA(1, 1), a1 + hstep, voffA);
;             PG8_WAIT_V(8); PG8_WAIT_L(0); PG8_BAR; PG8_MMA(0, 0, At, B0); PG8_MMA(0, 1, At, B1); PG8_BAR; PG8_SCHED;
;             if (full) { PG8_LDA(At, 0, 1); } PG8_STAGE(PG8_SB(0, 0), b2, voffB); PG8_STAGE(PG8_SB(0, 1), b2 + hstep, voffB); PG8_STAGE(PG8_SA(0, 0), a2, voffA);
;             PG8_WAIT_V(8); PG8_WAIT_L(0); PG8_BAR; if (full) { PG8_MMA(1, 0, At, B0); PG8_MMA(1, 1, At, B1); } PG8_BAR; PG8_SCHED;
.LBB0_152:
	v_add_u32_e32 v3, 0x10000, v217
	ds_read_b128 v[150:153], v3
	ds_read_b128 v[154:157], v3 offset:1024
	ds_read_b128 v[158:161], v3 offset:2048
	ds_read_b128 v[162:165], v3 offset:3072
	v_add_u32_e32 v3, 0x14000, v217
	ds_read_b128 v[134:137], v3
	ds_read_b128 v[138:141], v3 offset:1024
	ds_read_b128 v[142:145], v3 offset:2048
	ds_read_b128 v[146:149], v3 offset:3072
	s_or_b32 s10, s66, 1
	s_lshl_b64 s[4:5], s[10:11], 7
	s_add_u32 s4, s30, s4
	s_addc_u32 s5, s31, s5
	s_add_u32 s4, s4, 0x100000
	s_addc_u32 s5, s5, 0
	s_add_i32 m0, s44, 0xc000
	s_waitcnt lgkmcnt(0)
	ds_read_b128 v[178:181], v218
	ds_read_b128 v[194:197], v218 offset:1024
	ds_read_b128 v[174:177], v218 offset:2048
	ds_read_b128 v[190:193], v218 offset:3072
	ds_read_b128 v[170:173], v218 offset:4096
	ds_read_b128 v[186:189], v218 offset:5120
	ds_read_b128 v[166:169], v218 offset:6144
	ds_read_b128 v[182:185], v218 offset:7168
	global_load_lds_dwordx4 v200, s[4:5]
	s_add_i32 m0, s44, 0xe000
	s_nop 0
	global_load_lds_dwordx4 v204, s[4:5]
	s_waitcnt vmcnt(8)
	s_waitcnt lgkmcnt(0)
	s_setprio 1
	s_barrier
	v_mfma_f32_16x16x32_bf16 v[130:133], v[150:153], v[178:181], v[130:133]
	v_mfma_f32_16x16x32_bf16 v[122:125], v[158:161], v[178:181], v[122:125]
	v_mfma_f32_16x16x32_bf16 v[114:117], v[150:153], v[174:177], v[114:117]
	v_mfma_f32_16x16x32_bf16 v[106:109], v[158:161], v[174:177], v[106:109]
	v_mfma_f32_16x16x32_bf16 v[98:101], v[150:153], v[170:173], v[98:101]
	v_mfma_f32_16x16x32_bf16 v[90:93], v[158:161], v[170:173], v[90:93]
	v_mfma_f32_16x16x32_bf16 v[82:85], v[150:153], v[166:169], v[82:85]
	v_mfma_f32_16x16x32_bf16 v[74:77], v[158:161], v[166:169], v[74:77]
	v_mfma_f32_16x16x32_bf16 v[130:133], v[154:157], v[194:197], v[130:133]
	v_mfma_f32_16x16x32_bf16 v[122:125], v[162:165], v[194:197], v[122:125]
	v_mfma_f32_16x16x32_bf16 v[114:117], v[154:157], v[190:193], v[114:117]
	v_mfma_f32_16x16x32_bf16 v[106:109], v[162:165], v[190:193], v[106:109]
	v_mfma_f32_16x16x32_bf16 v[98:101], v[154:157], v[186:189], v[98:101]
	v_mfma_f32_16x16x32_bf16 v[90:93], v[162:165], v[186:189], v[90:93]
	v_mfma_f32_16x16x32_bf16 v[82:85], v[154:157], v[182:185], v[82:85]
	v_mfma_f32_16x16x32_bf16 v[74:77], v[162:165], v[182:185], v[74:77]
	v_mfma_f32_16x16x32_bf16 v[126:129], v[134:137], v[178:181], v[126:129]
	v_mfma_f32_16x16x32_bf16 v[118:121], v[142:145], v[178:181], v[118:121]
	v_mfma_f32_16x16x32_bf16 v[110:113], v[134:137], v[174:177], v[110:113]
	v_mfma_f32_16x16x32_bf16 v[102:105], v[142:145], v[174:177], v[102:105]
	v_mfma_f32_16x16x32_bf16 v[94:97], v[134:137], v[170:173], v[94:97]
	v_mfma_f32_16x16x32_bf16 v[86:89], v[142:145], v[170:173], v[86:89]
	v_mfma_f32_16x16x32_bf16 v[78:81], v[134:137], v[166:169], v[78:81]
	v_mfma_f32_16x16x32_bf16 v[70:73], v[142:145], v[166:169], v[70:73]
	v_mfma_f32_16x16x32_bf16 v[126:129], v[138:141], v[194:197], v[126:129]
	v_mfma_f32_16x16x32_bf16 v[118:121], v[146:149], v[194:197], v[118:121]
	v_mfma_f32_16x16x32_bf16 v[110:113], v[138:141], v[190:193], v[110:113]
	v_mfma_f32_16x16x32_bf16 v[102:105], v[146:149], v[190:193], v[102:105]
	v_mfma_f32_16x16x32_bf16 v[94:97], v[138:141], v[186:189], v[94:97]
	v_mfma_f32_16x16x32_bf16 v[86:89], v[146:149], v[186:189], v[86:89]
	v_mfma_f32_16x16x32_bf16 v[78:81], v[138:141], v[182:185], v[78:81]
	v_mfma_f32_16x16x32_bf16 v[70:73], v[146:149], v[182:185], v[70:73]
	s_barrier
	s_setprio 0
	v_cndmask_b32_e64 v3, 0, 1, s[36:37]
	v_cmp_ne_u32_e64 s[4:5], 1, v3
	s_andn2_b64 vcc, exec, s[36:37]
	s_cbranch_vccnz .LBB0_154
	ds_read_b128 v[178:181], v218 offset:16384
	ds_read_b128 v[194:197], v218 offset:17408
	ds_read_b128 v[174:177], v218 offset:18432
	ds_read_b128 v[190:193], v218 offset:19456
	ds_read_b128 v[170:173], v218 offset:20480
	ds_read_b128 v[186:189], v218 offset:21504
	ds_read_b128 v[166:169], v218 offset:22528
	ds_read_b128 v[182:185], v218 offset:23552
.LBB0_154:
	s_add_i32 s10, s66, 2
	s_lshl_b64 s[68:69], s[10:11], 7
	s_add_u32 s33, s30, s68
	s_addc_u32 s67, s31, s69
	s_and_b64 s[40:41], s[38:39], exec
	s_cselect_b32 s41, s3, s67
	s_cselect_b32 s40, s19, s33
	s_add_u32 s33, s34, s68
	s_addc_u32 s67, s35, s69
	s_and_b64 s[38:39], s[38:39], exec
	s_cselect_b32 s39, s21, s67
	s_cselect_b32 s38, s23, s33
	s_mov_b32 m0, s45
	s_add_u32 s68, s38, 0x100000
	global_load_lds_dwordx4 v202, s[38:39]
	s_mov_b32 m0, s47
	s_addc_u32 s69, s39, 0
	global_load_lds_dwordx4 v206, s[38:39]
	s_mov_b32 m0, s48
	s_nop 0
	global_load_lds_dwordx4 v202, s[68:69]
	s_mov_b32 m0, s49
	s_and_b64 vcc, exec, s[4:5]
	global_load_lds_dwordx4 v206, s[68:69]
	s_mov_b32 m0, s44
	s_nop 0
	global_load_lds_dwordx4 v200, s[40:41]
	s_mov_b32 m0, s50
	s_nop 0
	global_load_lds_dwordx4 v204, s[40:41]
	s_waitcnt vmcnt(8)
	s_waitcnt lgkmcnt(0)
	s_setprio 1
	s_barrier
	s_cbranch_vccnz .LBB0_156
	v_mfma_f32_16x16x32_bf16 v[62:65], v[150:153], v[178:181], v[62:65]
	v_mfma_f32_16x16x32_bf16 v[54:57], v[158:161], v[178:181], v[54:57]
	v_mfma_f32_16x16x32_bf16 v[46:49], v[150:153], v[174:177], v[46:49]
	v_mfma_f32_16x16x32_bf16 v[38:41], v[158:161], v[174:177], v[38:41]
	v_mfma_f32_16x16x32_bf16 v[30:33], v[150:153], v[170:173], v[30:33]
	v_mfma_f32_16x16x32_bf16 v[22:25], v[158:161], v[170:173], v[22:25]
	v_mfma_f32_16x16x32_bf16 v[14:17], v[150:153], v[166:169], v[14:17]
	v_mfma_f32_16x16x32_bf16 v[6:9], v[158:161], v[166:169], v[6:9]
	v_mfma_f32_16x16x32_bf16 v[62:65], v[154:157], v[194:197], v[62:65]
	v_mfma_f32_16x16x32_bf16 v[54:57], v[162:165], v[194:197], v[54:57]
	v_mfma_f32_16x16x32_bf16 v[46:49], v[154:157], v[190:193], v[46:49]
	v_mfma_f32_16x16x32_bf16 v[38:41], v[162:165], v[190:193], v[38:41]
	v_mfma_f32_16x16x32_bf16 v[30:33], v[154:157], v[186:189], v[30:33]
	v_mfma_f32_16x16x32_bf16 v[22:25], v[162:165], v[186:189], v[22:25]
	v_mfma_f32_16x16x32_bf16 v[14:17], v[154:157], v[182:185], v[14:17]
	v_mfma_f32_16x16x32_bf16 v[6:9], v[162:165], v[182:185], v[6:9]
	v_mfma_f32_16x16x32_bf16 v[66:69], v[134:137], v[178:181], v[66:69]
	v_mfma_f32_16x16x32_bf16 v[58:61], v[142:145], v[178:181], v[58:61]
	v_mfma_f32_16x16x32_bf16 v[50:53], v[134:137], v[174:177], v[50:53]
	v_mfma_f32_16x16x32_bf16 v[42:45], v[142:145], v[174:177], v[42:45]
	v_mfma_f32_16x16x32_bf16 v[34:37], v[134:137], v[170:173], v[34:37]
	v_mfma_f32_16x16x32_bf16 v[26:29], v[142:145], v[170:173], v[26:29]
	v_mfma_f32_16x16x32_bf16 v[18:21], v[134:137], v[166:169], v[18:21]
	v_mfma_f32_16x16x32_bf16 v[10:13], v[142:145], v[166:169], v[10:13]
	v_mfma_f32_16x16x32_bf16 v[66:69], v[138:141], v[194:197], v[66:69]
	v_mfma_f32_16x16x32_bf16 v[58:61], v[146:149], v[194:197], v[58:61]
	v_mfma_f32_16x16x32_bf16 v[50:53], v[138:141], v[190:193], v[50:53]
	v_mfma_f32_16x16x32_bf16 v[42:45], v[146:149], v[190:193], v[42:45]
	v_mfma_f32_16x16x32_bf16 v[34:37], v[138:141], v[186:189], v[34:37]
	v_mfma_f32_16x16x32_bf16 v[26:29], v[146:149], v[186:189], v[26:29]
	v_mfma_f32_16x16x32_bf16 v[18:21], v[138:141], v[182:185], v[18:21]
	v_mfma_f32_16x16x32_bf16 v[10:13], v[146:149], v[182:185], v[10:13]
; #define PG8_STAGE(bufoff, gbase, voff) do { _Pragma("unroll") for (int _i = 0; _i < 2; ++_i) \
;         __builtin_amdgcn_global_load_lds((const unsigned*)((const char*)(gbase) + (voff)[_i]), (PG8_LAS unsigned*)(lds + (bufoff) + ldsw + _i * 8192), 16, 0, 0); } while (0)
; #define PG8_LDA(dst, b, h) do { _Pragma("unroll") for (int m = 0; m < 4; ++m) _Pragma("unroll") for (int k = 0; k < 2; ++k) dst[m][k] = *(const PG8_LAS bf16x8*)(lds + PG8_SA(b, h) + aoff + m * 2048 + k * 1024); } while (0)
; #define PG8_LDB(dst, b, h) do { _Pragma("unroll") for (int n = 0; n < 2; ++n) _Pragma("unroll") for (int k = 0; k < 2; ++k) dst[n][k] = *(const PG8_LAS bf16x8*)(lds + PG8_SB(b, h) + boff + n * 2048 + k * 1024); } while (0)
; #define PG8_MMA(ai, bj, At, Bt) do { __builtin_amdgcn_s_setprio(1); _Pragma("unroll") for (int m = 0; m < 4; ++m) _Pragma("unroll") for (int n = 0; n < 2; ++n) _Pragma("unroll") for (int k = 0; k < 2; ++k) \
;         acc[ai][bj][m][n] = __builtin_amdgcn_mfma_f32_16x16x32_bf16(Bt[n][k], At[m][k], acc[ai][bj][m][n], 0, 0, 0); __builtin_amdgcn_s_setprio(0); } while (0)
; #define PG8_WAIT_V(n) asm volatile("s_waitcnt vmcnt(" #n ")" ::: "memory")
; #define PG8_WAIT_L(n) asm volatile("s_waitcnt lgkmcnt(" #n ")" ::: "memory")
; #define PG8_BAR __builtin_amdgcn_s_barrier()
; #define PG8_SCHED __builtin_amdgcn_sched_barrier(0)
; template <class Epi, class Sched, bool ALIGN_EPI = false, bool SP2 = true>
; __device__ __forceinline__ void gemm_phase(PG8_LAS unsigned char* lds, const Gemm g, const Sched& S, const Epi& E) {
;     ...
;             PG8_LDB(B0, 1, 0); PG8_LDB(B1, 1, 1); PG8_SCHED; PG8_LDA(At, 1, 0); PG8_STAGE(PG8_SA(0, 1), a2 + hstep, voffA);
;             PG8_WAIT_V(8); PG8_WAIT_L(0); PG8_BAR; PG8_MMA(0, 0, At, B0); PG8_MMA(0, 1, At, B1); PG8_BAR; PG8_SCHED;
;             if (full) { PG8_LDA(At, 1, 1); } PG8_STAGE(PG8_SB(1, 0), b3, voffB); PG8_STAGE(PG8_SB(1, 1), b3 + hstep, voffB); PG8_STAGE(PG8_SA(1, 0), a3, voffA);
;             PG8_WAIT_V(8); PG8_WAIT_L(0); PG8_BAR; if (full) { PG8_MMA(1, 0, At, B0); PG8_MMA(1, 1, At, B1); } PG8_BAR; PG8_SCHED;
.LBB0_156:
	s_barrier
	s_setprio 0
	v_add_u32_e32 v3, 0x18000, v217
	ds_read_b128 v[150:153], v3
	ds_read_b128 v[154:157], v3 offset:1024
	ds_read_b128 v[158:161], v3 offset:2048
	ds_read_b128 v[162:165], v3 offset:3072
	v_add_u32_e32 v3, 0x1c000, v217
	ds_read_b128 v[134:137], v3
	ds_read_b128 v[138:141], v3 offset:1024
	ds_read_b128 v[142:145], v3 offset:2048
	ds_read_b128 v[146:149], v3 offset:3072
	s_add_u32 s40, s40, 0x100000
	s_addc_u32 s41, s41, 0
	s_mov_b32 m0, s51
	s_waitcnt lgkmcnt(0)
	ds_read_b128 v[178:181], v218 offset:32768
	ds_read_b128 v[194:197], v218 offset:33792
	ds_read_b128 v[174:177], v218 offset:34816
	ds_read_b128 v[190:193], v218 offset:35840
	ds_read_b128 v[170:173], v218 offset:36864
	ds_read_b128 v[186:189], v218 offset:37888
	ds_read_b128 v[166:169], v218 offset:38912
	ds_read_b128 v[182:185], v218 offset:39936
	global_load_lds_dwordx4 v200, s[40:41]
	s_mov_b32 m0, s52
	s_nop 0
	global_load_lds_dwordx4 v204, s[40:41]
	s_waitcnt vmcnt(8)
	s_waitcnt lgkmcnt(0)
	s_setprio 1
	s_barrier
	v_mfma_f32_16x16x32_bf16 v[130:133], v[150:153], v[178:181], v[130:133]
	v_mfma_f32_16x16x32_bf16 v[122:125], v[158:161], v[178:181], v[122:125]
	v_mfma_f32_16x16x32_bf16 v[114:117], v[150:153], v[174:177], v[114:117]
	v_mfma_f32_16x16x32_bf16 v[106:109], v[158:161], v[174:177], v[106:109]
	v_mfma_f32_16x16x32_bf16 v[98:101], v[150:153], v[170:173], v[98:101]
	v_mfma_f32_16x16x32_bf16 v[90:93], v[158:161], v[170:173], v[90:93]
	v_mfma_f32_16x16x32_bf16 v[82:85], v[150:153], v[166:169], v[82:85]
	v_mfma_f32_16x16x32_bf16 v[74:77], v[158:161], v[166:169], v[74:77]
	v_mfma_f32_16x16x32_bf16 v[130:133], v[154:157], v[194:197], v[130:133]
	v_mfma_f32_16x16x32_bf16 v[122:125], v[162:165], v[194:197], v[122:125]
	v_mfma_f32_16x16x32_bf16 v[114:117], v[154:157], v[190:193], v[114:117]
	v_mfma_f32_16x16x32_bf16 v[106:109], v[162:165], v[190:193], v[106:109]
	v_mfma_f32_16x16x32_bf16 v[98:101], v[154:157], v[186:189], v[98:101]
	v_mfma_f32_16x16x32_bf16 v[90:93], v[162:165], v[186:189], v[90:93]
	v_mfma_f32_16x16x32_bf16 v[82:85], v[154:157], v[182:185], v[82:85]
	v_mfma_f32_16x16x32_bf16 v[74:77], v[162:165], v[182:185], v[74:77]
	v_mfma_f32_16x16x32_bf16 v[126:129], v[134:137], v[178:181], v[126:129]
	v_mfma_f32_16x16x32_bf16 v[118:121], v[142:145], v[178:181], v[118:121]
	v_mfma_f32_16x16x32_bf16 v[110:113], v[134:137], v[174:177], v[110:113]
	v_mfma_f32_16x16x32_bf16 v[102:105], v[142:145], v[174:177], v[102:105]
	v_mfma_f32_16x16x32_bf16 v[94:97], v[134:137], v[170:173], v[94:97]
	v_mfma_f32_16x16x32_bf16 v[86:89], v[142:145], v[170:173], v[86:89]
	v_mfma_f32_16x16x32_bf16 v[78:81], v[134:137], v[166:169], v[78:81]
	v_mfma_f32_16x16x32_bf16 v[70:73], v[142:145], v[166:169], v[70:73]
	v_mfma_f32_16x16x32_bf16 v[126:129], v[138:141], v[194:197], v[126:129]
	v_mfma_f32_16x16x32_bf16 v[118:121], v[146:149], v[194:197], v[118:121]
	v_mfma_f32_16x16x32_bf16 v[110:113], v[138:141], v[190:193], v[110:113]
	v_mfma_f32_16x16x32_bf16 v[102:105], v[146:149], v[190:193], v[102:105]
	v_mfma_f32_16x16x32_bf16 v[94:97], v[138:141], v[186:189], v[94:97]
	v_mfma_f32_16x16x32_bf16 v[86:89], v[146:149], v[186:189], v[86:89]
	v_mfma_f32_16x16x32_bf16 v[78:81], v[138:141], v[182:185], v[78:81]
	v_mfma_f32_16x16x32_bf16 v[70:73], v[146:149], v[182:185], v[70:73]
	s_barrier
	s_setprio 0
	s_and_b64 vcc, exec, s[4:5]
	s_cbranch_vccnz .LBB0_158
	ds_read_b128 v[178:181], v218 offset:49152
	ds_read_b128 v[194:197], v218 offset:50176
	ds_read_b128 v[174:177], v218 offset:51200
	ds_read_b128 v[190:193], v218 offset:52224
	ds_read_b128 v[170:173], v218 offset:53248
	ds_read_b128 v[186:189], v218 offset:54272
	ds_read_b128 v[166:169], v218 offset:55296
	ds_read_b128 v[182:185], v218 offset:56320
.LBB0_158:
	s_mov_b32 m0, s54
	s_add_u32 s98, s38, 0x80
	s_addc_u32 s99, s39, 0
	s_add_u32 s38, s38, 0x100080
	global_load_lds_dwordx4 v202, s[98:99]
	s_mov_b32 m0, s55
	s_addc_u32 s39, s39, 0
	global_load_lds_dwordx4 v206, s[98:99]
	s_mov_b32 m0, s58
	s_and_b64 vcc, exec, s[4:5]
	global_load_lds_dwordx4 v202, s[38:39]
	s_mov_b32 m0, s59
	s_nop 0
	global_load_lds_dwordx4 v206, s[38:39]
	s_mov_b32 m0, s56
	s_nop 0
	s_add_u32 s100, s40, 0xfff00080
	s_addc_u32 s101, s41, -1
	global_load_lds_dwordx4 v200, s[100:101]
	s_mov_b32 m0, s57
	s_nop 0
	global_load_lds_dwordx4 v204, s[100:101]
	s_waitcnt vmcnt(8)
	s_waitcnt lgkmcnt(0)
	s_setprio 1
	s_barrier
	s_cbranch_vccnz .LBB0_160
	v_mfma_f32_16x16x32_bf16 v[62:65], v[150:153], v[178:181], v[62:65]
	v_mfma_f32_16x16x32_bf16 v[54:57], v[158:161], v[178:181], v[54:57]
	v_mfma_f32_16x16x32_bf16 v[46:49], v[150:153], v[174:177], v[46:49]
	v_mfma_f32_16x16x32_bf16 v[38:41], v[158:161], v[174:177], v[38:41]
	v_mfma_f32_16x16x32_bf16 v[30:33], v[150:153], v[170:173], v[30:33]
	v_mfma_f32_16x16x32_bf16 v[22:25], v[158:161], v[170:173], v[22:25]
	v_mfma_f32_16x16x32_bf16 v[14:17], v[150:153], v[166:169], v[14:17]
	v_mfma_f32_16x16x32_bf16 v[4:7], v[158:161], v[166:169], v[6:9]
	v_mfma_f32_16x16x32_bf16 v[62:65], v[154:157], v[194:197], v[62:65]
	v_mfma_f32_16x16x32_bf16 v[54:57], v[162:165], v[194:197], v[54:57]
	v_mfma_f32_16x16x32_bf16 v[46:49], v[154:157], v[190:193], v[46:49]
	v_mfma_f32_16x16x32_bf16 v[38:41], v[162:165], v[190:193], v[38:41]
	v_mfma_f32_16x16x32_bf16 v[30:33], v[154:157], v[186:189], v[30:33]
	v_mfma_f32_16x16x32_bf16 v[22:25], v[162:165], v[186:189], v[22:25]
	v_mfma_f32_16x16x32_bf16 v[14:17], v[154:157], v[182:185], v[14:17]
	v_mfma_f32_16x16x32_bf16 v[6:9], v[162:165], v[182:185], v[4:7]
	v_mfma_f32_16x16x32_bf16 v[66:69], v[134:137], v[178:181], v[66:69]
	v_mfma_f32_16x16x32_bf16 v[58:61], v[142:145], v[178:181], v[58:61]
	v_mfma_f32_16x16x32_bf16 v[50:53], v[134:137], v[174:177], v[50:53]
	v_mfma_f32_16x16x32_bf16 v[42:45], v[142:145], v[174:177], v[42:45]
	v_mfma_f32_16x16x32_bf16 v[34:37], v[134:137], v[170:173], v[34:37]
	v_mfma_f32_16x16x32_bf16 v[26:29], v[142:145], v[170:173], v[26:29]
	v_mfma_f32_16x16x32_bf16 v[18:21], v[134:137], v[166:169], v[18:21]
	v_mfma_f32_16x16x32_bf16 v[10:13], v[142:145], v[166:169], v[10:13]
	v_mfma_f32_16x16x32_bf16 v[66:69], v[138:141], v[194:197], v[66:69]
	v_mfma_f32_16x16x32_bf16 v[58:61], v[146:149], v[194:197], v[58:61]
	v_mfma_f32_16x16x32_bf16 v[50:53], v[138:141], v[190:193], v[50:53]
	v_mfma_f32_16x16x32_bf16 v[42:45], v[146:149], v[190:193], v[42:45]
	v_mfma_f32_16x16x32_bf16 v[34:37], v[138:141], v[186:189], v[34:37]
	v_mfma_f32_16x16x32_bf16 v[26:29], v[146:149], v[186:189], v[26:29]
	v_mfma_f32_16x16x32_bf16 v[18:21], v[138:141], v[182:185], v[18:21]
	v_mfma_f32_16x16x32_bf16 v[10:13], v[146:149], v[182:185], v[10:13]

; #define PG8_STAGE(bufoff, gbase, voff) do { _Pragma("unroll") for (int _i = 0; _i < 2; ++_i) \
;         __builtin_amdgcn_global_load_lds((const unsigned*)((const char*)(gbase) + (voff)[_i]), (PG8_LAS unsigned*)(lds + (bufoff) + ldsw + _i * 8192), 16, 0, 0); } while (0)
; #define PG8_LDA(dst, b, h) do { _Pragma("unroll") for (int m = 0; m < 4; ++m) _Pragma("unroll") for (int k = 0; k < 2; ++k) dst[m][k] = *(const PG8_LAS bf16x8*)(lds + PG8_SA(b, h) + aoff + m * 2048 + k * 1024); } while (0)
; #define PG8_LDB(dst, b, h) do { _Pragma("unroll") for (int n = 0; n < 2; ++n) _Pragma("unroll") for (int k = 0; k < 2; ++k) dst[n][k] = *(const PG8_LAS bf16x8*)(lds + PG8_SB(b, h) + boff + n * 2048 + k * 1024); } while (0)
; #define PG8_MMA(ai, bj, At, Bt) do { __builtin_amdgcn_s_setprio(1); _Pragma("unroll") for (int m = 0; m < 4; ++m) _Pragma("unroll") for (int n = 0; n < 2; ++n) _Pragma("unroll") for (int k = 0; k < 2; ++k) \
;         acc[ai][bj][m][n] = __builtin_amdgcn_mfma_f32_16x16x32_bf16(Bt[n][k], At[m][k], acc[ai][bj][m][n], 0, 0, 0); __builtin_amdgcn_s_setprio(0); } while (0)
; #define PG8_WAIT_V(n) asm volatile("s_waitcnt vmcnt(" #n ")" ::: "memory")
; #define PG8_WAIT_L(n) asm volatile("s_waitcnt lgkmcnt(" #n ")" ::: "memory")
; #define PG8_BAR __builtin_amdgcn_s_barrier()
; #define PG8_SCHED __builtin_amdgcn_sched_barrier(0)
; template <class Epi, class Sched, bool ALIGN_EPI = false, bool SP2 = true>
; __device__ __forceinline__ void gemm_phase(PG8_LAS unsigned char* lds, const Gemm g, const Sched& S, const Epi& E) {
;     ...
;             PG8_LDB(B0, 0, 0); PG8_LDB(B1, 0, 1); PG8_SCHED; PG8_LDA(At, 0, 0); PG8_STAGE(PG8_SA(1, 1), a1 + hstep, voffA);
;             PG8_WAIT_V(8); PG8_WAIT_L(0); PG8_BAR; PG8_MMA(0, 0, At, B0); PG8_MMA(0, 1, At, B1); PG8_BAR; PG8_SCHED;
;             if (full) { PG8_LDA(At, 0, 1); } PG8_STAGE(PG8_SB(0, 0), b2, voffB); PG8_STAGE(PG8_SB(0, 1), b2 + hstep, voffB); PG8_STAGE(PG8_SA(0, 0), a2, voffA);
;             PG8_WAIT_V(8); PG8_WAIT_L(0); PG8_BAR; if (full) { PG8_MMA(1, 0, At, B0); PG8_MMA(1, 1, At, B1); } PG8_BAR; PG8_SCHED;
.LBB0_260:
	ds_read_b128 v[150:153], v209
	ds_read_b128 v[154:157], v209 offset:1024
	ds_read_b128 v[158:161], v209 offset:2048
	ds_read_b128 v[162:165], v209 offset:3072
	ds_read_b128 v[134:137], v226
	ds_read_b128 v[138:141], v226 offset:1024
	ds_read_b128 v[142:145], v226 offset:2048
	ds_read_b128 v[146:149], v226 offset:3072
	s_add_i32 m0, s38, 0xc000
	s_waitcnt lgkmcnt(0)
	ds_read_b128 v[178:181], v227
	ds_read_b128 v[194:197], v227 offset:1024
	ds_read_b128 v[174:177], v227 offset:2048
	ds_read_b128 v[190:193], v227 offset:3072
	ds_read_b128 v[170:173], v227 offset:4096
	ds_read_b128 v[186:189], v227 offset:5120
	ds_read_b128 v[166:169], v227 offset:6144
	ds_read_b128 v[182:185], v227 offset:7168
	global_load_lds_dwordx4 v212, s[24:25]
	s_add_i32 m0, s38, 0xe000
	s_nop 0
	global_load_lds_dwordx4 v214, s[24:25]
	s_waitcnt vmcnt(8)
	s_waitcnt lgkmcnt(0)
	s_setprio 1
	s_barrier
	v_mfma_f32_16x16x32_bf16 v[66:69], v[150:153], v[178:181], v[66:69]
	v_mfma_f32_16x16x32_bf16 v[62:65], v[158:161], v[178:181], v[62:65]
	v_mfma_f32_16x16x32_bf16 v[50:53], v[150:153], v[174:177], v[50:53]
	v_mfma_f32_16x16x32_bf16 v[46:49], v[158:161], v[174:177], v[46:49]
	v_mfma_f32_16x16x32_bf16 v[34:37], v[150:153], v[170:173], v[34:37]
	v_mfma_f32_16x16x32_bf16 v[30:33], v[158:161], v[170:173], v[30:33]
	v_mfma_f32_16x16x32_bf16 v[18:21], v[150:153], v[166:169], v[18:21]
	v_mfma_f32_16x16x32_bf16 v[14:17], v[158:161], v[166:169], v[14:17]
	v_mfma_f32_16x16x32_bf16 v[66:69], v[154:157], v[194:197], v[66:69]
	v_mfma_f32_16x16x32_bf16 v[62:65], v[162:165], v[194:197], v[62:65]
	v_mfma_f32_16x16x32_bf16 v[50:53], v[154:157], v[190:193], v[50:53]
	v_mfma_f32_16x16x32_bf16 v[46:49], v[162:165], v[190:193], v[46:49]
	v_mfma_f32_16x16x32_bf16 v[34:37], v[154:157], v[186:189], v[34:37]
	v_mfma_f32_16x16x32_bf16 v[30:33], v[162:165], v[186:189], v[30:33]
	v_mfma_f32_16x16x32_bf16 v[18:21], v[154:157], v[182:185], v[18:21]
	v_mfma_f32_16x16x32_bf16 v[14:17], v[162:165], v[182:185], v[14:17]
	v_mfma_f32_16x16x32_bf16 v[58:61], v[134:137], v[178:181], v[58:61]
	v_mfma_f32_16x16x32_bf16 v[54:57], v[142:145], v[178:181], v[54:57]
	v_mfma_f32_16x16x32_bf16 v[42:45], v[134:137], v[174:177], v[42:45]
	v_mfma_f32_16x16x32_bf16 v[38:41], v[142:145], v[174:177], v[38:41]
	v_mfma_f32_16x16x32_bf16 v[26:29], v[134:137], v[170:173], v[26:29]
	v_mfma_f32_16x16x32_bf16 v[22:25], v[142:145], v[170:173], v[22:25]
	v_mfma_f32_16x16x32_bf16 v[10:13], v[134:137], v[166:169], v[10:13]
	v_mfma_f32_16x16x32_bf16 v[4:7], v[142:145], v[166:169], v[6:9]
	v_mfma_f32_16x16x32_bf16 v[58:61], v[138:141], v[194:197], v[58:61]
	v_mfma_f32_16x16x32_bf16 v[54:57], v[146:149], v[194:197], v[54:57]
	v_mfma_f32_16x16x32_bf16 v[42:45], v[138:141], v[190:193], v[42:45]
	v_mfma_f32_16x16x32_bf16 v[38:41], v[146:149], v[190:193], v[38:41]
	v_mfma_f32_16x16x32_bf16 v[26:29], v[138:141], v[186:189], v[26:29]
	v_mfma_f32_16x16x32_bf16 v[22:25], v[146:149], v[186:189], v[22:25]
	v_mfma_f32_16x16x32_bf16 v[10:13], v[138:141], v[182:185], v[10:13]
	v_mfma_f32_16x16x32_bf16 v[4:7], v[146:149], v[182:185], v[4:7]
	s_barrier
	s_setprio 0
	v_cmp_ne_u32_e64 s[8:9], 1, v228
	s_andn2_b64 vcc, exec, s[2:3]
	s_cbranch_vccnz .LBB0_262
	ds_read_b128 v[178:181], v227 offset:16384
	ds_read_b128 v[194:197], v227 offset:17408
	ds_read_b128 v[174:177], v227 offset:18432
	ds_read_b128 v[190:193], v227 offset:19456
	ds_read_b128 v[170:173], v227 offset:20480
	ds_read_b128 v[186:189], v227 offset:21504
	ds_read_b128 v[166:169], v227 offset:22528
	ds_read_b128 v[182:185], v227 offset:23552
.LBB0_262:
	s_add_u32 s26, s24, 0xffd50080
	s_addc_u32 s27, s25, -1
	s_cmp_eq_u32 s19, s65
	s_cselect_b32 s29, s21, s27
	s_cselect_b32 s28, s20, s26
	s_cselect_b32 s27, s23, s64
	s_cselect_b32 s26, s22, s63
	s_mov_b32 m0, s39
	s_add_u32 s66, s26, 0x2b0000
	global_load_lds_dwordx4 v202, s[26:27]
	s_mov_b32 m0, s40
	s_addc_u32 s67, s27, 0
	global_load_lds_dwordx4 v206, s[26:27]
	s_mov_b32 m0, s41
	s_nop 0
	global_load_lds_dwordx4 v202, s[66:67]
	s_mov_b32 m0, s42
	s_nop 0
	global_load_lds_dwordx4 v206, s[66:67]
	s_mov_b32 m0, s38
	s_and_b64 vcc, exec, s[8:9]
	global_load_lds_dwordx4 v200, s[28:29]
	s_mov_b32 m0, s43
	s_nop 0
	global_load_lds_dwordx4 v204, s[28:29]
	s_waitcnt vmcnt(8)
	s_waitcnt lgkmcnt(0)
	s_setprio 1
	s_barrier
	s_cbranch_vccnz .LBB0_264
	v_mfma_f32_16x16x32_bf16 v[130:133], v[150:153], v[178:181], v[130:133]
	v_mfma_f32_16x16x32_bf16 v[126:129], v[158:161], v[178:181], v[126:129]
	v_mfma_f32_16x16x32_bf16 v[118:121], v[150:153], v[174:177], v[118:121]
	v_mfma_f32_16x16x32_bf16 v[110:113], v[158:161], v[174:177], v[110:113]
	v_mfma_f32_16x16x32_bf16 v[102:105], v[150:153], v[170:173], v[102:105]
	v_mfma_f32_16x16x32_bf16 v[94:97], v[158:161], v[170:173], v[94:97]
	v_mfma_f32_16x16x32_bf16 v[86:89], v[150:153], v[166:169], v[86:89]
	v_mfma_f32_16x16x32_bf16 v[78:81], v[158:161], v[166:169], v[78:81]
	v_mfma_f32_16x16x32_bf16 v[130:133], v[154:157], v[194:197], v[130:133]
	v_mfma_f32_16x16x32_bf16 v[126:129], v[162:165], v[194:197], v[126:129]
	v_mfma_f32_16x16x32_bf16 v[118:121], v[154:157], v[190:193], v[118:121]
	v_mfma_f32_16x16x32_bf16 v[110:113], v[162:165], v[190:193], v[110:113]
	v_mfma_f32_16x16x32_bf16 v[102:105], v[154:157], v[186:189], v[102:105]
	v_mfma_f32_16x16x32_bf16 v[94:97], v[162:165], v[186:189], v[94:97]
	v_mfma_f32_16x16x32_bf16 v[86:89], v[154:157], v[182:185], v[86:89]
	v_mfma_f32_16x16x32_bf16 v[78:81], v[162:165], v[182:185], v[78:81]
	v_mfma_f32_16x16x32_bf16 v[122:125], v[134:137], v[178:181], v[122:125]
	v_mfma_f32_16x16x32_bf16 v[114:117], v[142:145], v[178:181], v[114:117]
	v_mfma_f32_16x16x32_bf16 v[106:109], v[134:137], v[174:177], v[106:109]
	v_mfma_f32_16x16x32_bf16 v[98:101], v[142:145], v[174:177], v[98:101]
	v_mfma_f32_16x16x32_bf16 v[90:93], v[134:137], v[170:173], v[90:93]
	v_mfma_f32_16x16x32_bf16 v[82:85], v[142:145], v[170:173], v[82:85]
	v_mfma_f32_16x16x32_bf16 v[74:77], v[134:137], v[166:169], v[74:77]
	v_mfma_f32_16x16x32_bf16 v[70:73], v[142:145], v[166:169], v[70:73]
	v_mfma_f32_16x16x32_bf16 v[122:125], v[138:141], v[194:197], v[122:125]
	v_mfma_f32_16x16x32_bf16 v[114:117], v[146:149], v[194:197], v[114:117]
	v_mfma_f32_16x16x32_bf16 v[106:109], v[138:141], v[190:193], v[106:109]
	v_mfma_f32_16x16x32_bf16 v[98:101], v[146:149], v[190:193], v[98:101]
	v_mfma_f32_16x16x32_bf16 v[90:93], v[138:141], v[186:189], v[90:93]
	v_mfma_f32_16x16x32_bf16 v[82:85], v[146:149], v[186:189], v[82:85]
	v_mfma_f32_16x16x32_bf16 v[74:77], v[138:141], v[182:185], v[74:77]
	v_mfma_f32_16x16x32_bf16 v[70:73], v[146:149], v[182:185], v[70:73]
; #define PG8_STAGE(bufoff, gbase, voff) do { _Pragma("unroll") for (int _i = 0; _i < 2; ++_i) \
;         __builtin_amdgcn_global_load_lds((const unsigned*)((const char*)(gbase) + (voff)[_i]), (PG8_LAS unsigned*)(lds + (bufoff) + ldsw + _i * 8192), 16, 0, 0); } while (0)
; #define PG8_LDA(dst, b, h) do { _Pragma("unroll") for (int m = 0; m < 4; ++m) _Pragma("unroll") for (int k = 0; k < 2; ++k) dst[m][k] = *(const PG8_LAS bf16x8*)(lds + PG8_SA(b, h) + aoff + m * 2048 + k * 1024); } while (0)
; #define PG8_LDB(dst, b, h) do { _Pragma("unroll") for (int n = 0; n < 2; ++n) _Pragma("unroll") for (int k = 0; k < 2; ++k) dst[n][k] = *(const PG8_LAS bf16x8*)(lds + PG8_SB(b, h) + boff + n * 2048 + k * 1024); } while (0)
; #define PG8_MMA(ai, bj, At, Bt) do { __builtin_amdgcn_s_setprio(1); _Pragma("unroll") for (int m = 0; m < 4; ++m) _Pragma("unroll") for (int n = 0; n < 2; ++n) _Pragma("unroll") for (int k = 0; k < 2; ++k) \
;         acc[ai][bj][m][n] = __builtin_amdgcn_mfma_f32_16x16x32_bf16(Bt[n][k], At[m][k], acc[ai][bj][m][n], 0, 0, 0); __builtin_amdgcn_s_setprio(0); } while (0)
; #define PG8_WAIT_V(n) asm volatile("s_waitcnt vmcnt(" #n ")" ::: "memory")
; #define PG8_WAIT_L(n) asm volatile("s_waitcnt lgkmcnt(" #n ")" ::: "memory")
; #define PG8_BAR __builtin_amdgcn_s_barrier()
; #define PG8_SCHED __builtin_amdgcn_sched_barrier(0)
; template <class Epi, class Sched, bool ALIGN_EPI = false, bool SP2 = true>
; __device__ __forceinline__ void gemm_phase(PG8_LAS unsigned char* lds, const Gemm g, const Sched& S, const Epi& E) {
;     ...
;             PG8_LDB(B0, 1, 0); PG8_LDB(B1, 1, 1); PG8_SCHED; PG8_LDA(At, 1, 0); PG8_STAGE(PG8_SA(0, 1), a2 + hstep, voffA);
;             PG8_WAIT_V(8); PG8_WAIT_L(0); PG8_BAR; PG8_MMA(0, 0, At, B0); PG8_MMA(0, 1, At, B1); PG8_BAR; PG8_SCHED;
;             if (full) { PG8_LDA(At, 1, 1); } PG8_STAGE(PG8_SB(1, 0), b3, voffB); PG8_STAGE(PG8_SB(1, 1), b3 + hstep, voffB); PG8_STAGE(PG8_SA(1, 0), a3, voffA);
;             PG8_WAIT_V(8); PG8_WAIT_L(0); PG8_BAR; if (full) { PG8_MMA(1, 0, At, B0); PG8_MMA(1, 1, At, B1); } PG8_BAR; PG8_SCHED;
.LBB0_264:
	s_barrier
	s_setprio 0
	v_add_u32_e32 v3, 0x18000, v199
	ds_read_b128 v[150:153], v3
	ds_read_b128 v[154:157], v3 offset:1024
	ds_read_b128 v[158:161], v3 offset:2048
	ds_read_b128 v[162:165], v3 offset:3072
	v_add_u32_e32 v3, 0x1c000, v199
	ds_read_b128 v[134:137], v3
	ds_read_b128 v[138:141], v3 offset:1024
	ds_read_b128 v[142:145], v3 offset:2048
	ds_read_b128 v[146:149], v3 offset:3072
	s_add_u32 s28, s28, 0x2b0000
	s_addc_u32 s29, s29, 0
	s_mov_b32 m0, s44
	s_waitcnt lgkmcnt(0)
	ds_read_b128 v[178:181], v227 offset:32768
	ds_read_b128 v[194:197], v227 offset:33792
	ds_read_b128 v[174:177], v227 offset:34816
	ds_read_b128 v[190:193], v227 offset:35840
	ds_read_b128 v[170:173], v227 offset:36864
	ds_read_b128 v[186:189], v227 offset:37888
	ds_read_b128 v[166:169], v227 offset:38912
	ds_read_b128 v[182:185], v227 offset:39936
	global_load_lds_dwordx4 v200, s[28:29]
	s_mov_b32 m0, s45
	s_nop 0
	global_load_lds_dwordx4 v204, s[28:29]
	s_waitcnt vmcnt(8)
	s_waitcnt lgkmcnt(0)
	s_setprio 1
	s_barrier
	v_mfma_f32_16x16x32_bf16 v[66:69], v[150:153], v[178:181], v[66:69]
	v_mfma_f32_16x16x32_bf16 v[62:65], v[158:161], v[178:181], v[62:65]
	v_mfma_f32_16x16x32_bf16 v[50:53], v[150:153], v[174:177], v[50:53]
	v_mfma_f32_16x16x32_bf16 v[46:49], v[158:161], v[174:177], v[46:49]
	v_mfma_f32_16x16x32_bf16 v[34:37], v[150:153], v[170:173], v[34:37]
	v_mfma_f32_16x16x32_bf16 v[30:33], v[158:161], v[170:173], v[30:33]
	v_mfma_f32_16x16x32_bf16 v[18:21], v[150:153], v[166:169], v[18:21]
	v_mfma_f32_16x16x32_bf16 v[14:17], v[158:161], v[166:169], v[14:17]
	v_mfma_f32_16x16x32_bf16 v[66:69], v[154:157], v[194:197], v[66:69]
	v_mfma_f32_16x16x32_bf16 v[62:65], v[162:165], v[194:197], v[62:65]
	v_mfma_f32_16x16x32_bf16 v[50:53], v[154:157], v[190:193], v[50:53]
	v_mfma_f32_16x16x32_bf16 v[46:49], v[162:165], v[190:193], v[46:49]
	v_mfma_f32_16x16x32_bf16 v[34:37], v[154:157], v[186:189], v[34:37]
	v_mfma_f32_16x16x32_bf16 v[30:33], v[162:165], v[186:189], v[30:33]
	v_mfma_f32_16x16x32_bf16 v[18:21], v[154:157], v[182:185], v[18:21]
	v_mfma_f32_16x16x32_bf16 v[14:17], v[162:165], v[182:185], v[14:17]
	v_mfma_f32_16x16x32_bf16 v[58:61], v[134:137], v[178:181], v[58:61]
	v_mfma_f32_16x16x32_bf16 v[54:57], v[142:145], v[178:181], v[54:57]
	v_mfma_f32_16x16x32_bf16 v[42:45], v[134:137], v[174:177], v[42:45]
	v_mfma_f32_16x16x32_bf16 v[38:41], v[142:145], v[174:177], v[38:41]
	v_mfma_f32_16x16x32_bf16 v[26:29], v[134:137], v[170:173], v[26:29]
	v_mfma_f32_16x16x32_bf16 v[22:25], v[142:145], v[170:173], v[22:25]
	v_mfma_f32_16x16x32_bf16 v[8:11], v[134:137], v[166:169], v[10:13]
	v_mfma_f32_16x16x32_bf16 v[4:7], v[142:145], v[166:169], v[4:7]
	v_mfma_f32_16x16x32_bf16 v[58:61], v[138:141], v[194:197], v[58:61]
	v_mfma_f32_16x16x32_bf16 v[54:57], v[146:149], v[194:197], v[54:57]
	v_mfma_f32_16x16x32_bf16 v[42:45], v[138:141], v[190:193], v[42:45]
	v_mfma_f32_16x16x32_bf16 v[38:41], v[146:149], v[190:193], v[38:41]
	v_mfma_f32_16x16x32_bf16 v[26:29], v[138:141], v[186:189], v[26:29]
	v_mfma_f32_16x16x32_bf16 v[22:25], v[146:149], v[186:189], v[22:25]
	v_mfma_f32_16x16x32_bf16 v[10:13], v[138:141], v[182:185], v[8:11]
	v_mfma_f32_16x16x32_bf16 v[6:9], v[146:149], v[182:185], v[4:7]
	s_barrier
	s_setprio 0
	s_and_b64 vcc, exec, s[8:9]
	s_cbranch_vccnz .LBB0_266
	ds_read_b128 v[178:181], v227 offset:49152
	ds_read_b128 v[194:197], v227 offset:50176
	ds_read_b128 v[174:177], v227 offset:51200
	ds_read_b128 v[190:193], v227 offset:52224
	ds_read_b128 v[170:173], v227 offset:53248
	ds_read_b128 v[186:189], v227 offset:54272
	ds_read_b128 v[166:169], v227 offset:55296
	ds_read_b128 v[182:185], v227 offset:56320
.LBB0_266:
	s_mov_b32 m0, s49
	s_add_u32 s98, s26, 0x80
	s_addc_u32 s99, s27, 0
	s_add_u32 s26, s26, 0x2b0080
	global_load_lds_dwordx4 v202, s[98:99]
	s_mov_b32 m0, s50
	s_addc_u32 s27, s27, 0
	global_load_lds_dwordx4 v206, s[98:99]
	s_mov_b32 m0, s53
	s_and_b64 vcc, exec, s[8:9]
	global_load_lds_dwordx4 v202, s[26:27]
	s_mov_b32 m0, s54
	s_nop 0
	global_load_lds_dwordx4 v206, s[26:27]
	s_mov_b32 m0, s51
	s_nop 0
	s_add_u32 s100, s28, 0xffd50080
	s_addc_u32 s101, s29, -1
	global_load_lds_dwordx4 v200, s[100:101]
	s_mov_b32 m0, s52
	s_nop 0
	global_load_lds_dwordx4 v204, s[100:101]
	s_waitcnt vmcnt(8)
	s_waitcnt lgkmcnt(0)
	s_setprio 1
	s_barrier
	s_cbranch_vccnz .LBB0_259
	v_mfma_f32_16x16x32_bf16 v[130:133], v[150:153], v[178:181], v[130:133]
	v_mfma_f32_16x16x32_bf16 v[126:129], v[158:161], v[178:181], v[126:129]
	v_mfma_f32_16x16x32_bf16 v[118:121], v[150:153], v[174:177], v[118:121]
	v_mfma_f32_16x16x32_bf16 v[110:113], v[158:161], v[174:177], v[110:113]
	v_mfma_f32_16x16x32_bf16 v[102:105], v[150:153], v[170:173], v[102:105]
	v_mfma_f32_16x16x32_bf16 v[94:97], v[158:161], v[170:173], v[94:97]
	v_mfma_f32_16x16x32_bf16 v[86:89], v[150:153], v[166:169], v[86:89]
	v_mfma_f32_16x16x32_bf16 v[78:81], v[158:161], v[166:169], v[78:81]
	v_mfma_f32_16x16x32_bf16 v[130:133], v[154:157], v[194:197], v[130:133]
	v_mfma_f32_16x16x32_bf16 v[126:129], v[162:165], v[194:197], v[126:129]
	v_mfma_f32_16x16x32_bf16 v[118:121], v[154:157], v[190:193], v[118:121]
	v_mfma_f32_16x16x32_bf16 v[110:113], v[162:165], v[190:193], v[110:113]
	v_mfma_f32_16x16x32_bf16 v[102:105], v[154:157], v[186:189], v[102:105]
	v_mfma_f32_16x16x32_bf16 v[94:97], v[162:165], v[186:189], v[94:97]
	v_mfma_f32_16x16x32_bf16 v[86:89], v[154:157], v[182:185], v[86:89]
	v_mfma_f32_16x16x32_bf16 v[78:81], v[162:165], v[182:185], v[78:81]
	v_mfma_f32_16x16x32_bf16 v[122:125], v[134:137], v[178:181], v[122:125]
	v_mfma_f32_16x16x32_bf16 v[114:117], v[142:145], v[178:181], v[114:117]
	v_mfma_f32_16x16x32_bf16 v[106:109], v[134:137], v[174:177], v[106:109]
	v_mfma_f32_16x16x32_bf16 v[98:101], v[142:145], v[174:177], v[98:101]
	v_mfma_f32_16x16x32_bf16 v[90:93], v[134:137], v[170:173], v[90:93]
	v_mfma_f32_16x16x32_bf16 v[82:85], v[142:145], v[170:173], v[82:85]
	v_mfma_f32_16x16x32_bf16 v[74:77], v[134:137], v[166:169], v[74:77]
	v_mfma_f32_16x16x32_bf16 v[70:73], v[142:145], v[166:169], v[70:73]
	v_mfma_f32_16x16x32_bf16 v[122:125], v[138:141], v[194:197], v[122:125]
	v_mfma_f32_16x16x32_bf16 v[114:117], v[146:149], v[194:197], v[114:117]
	v_mfma_f32_16x16x32_bf16 v[106:109], v[138:141], v[190:193], v[106:109]
	v_mfma_f32_16x16x32_bf16 v[98:101], v[146:149], v[190:193], v[98:101]
	v_mfma_f32_16x16x32_bf16 v[90:93], v[138:141], v[186:189], v[90:93]
	v_mfma_f32_16x16x32_bf16 v[82:85], v[146:149], v[186:189], v[82:85]
	v_mfma_f32_16x16x32_bf16 v[74:77], v[138:141], v[182:185], v[74:77]
	v_mfma_f32_16x16x32_bf16 v[70:73], v[146:149], v[182:185], v[70:73]
	s_branch .LBB0_259

; #define PG8_STAGE(bufoff, gbase, voff) do { _Pragma("unroll") for (int _i = 0; _i < 2; ++_i) \
;         __builtin_amdgcn_global_load_lds((const unsigned*)((const char*)(gbase) + (voff)[_i]), (PG8_LAS unsigned*)(lds + (bufoff) + ldsw + _i * 8192), 16, 0, 0); } while (0)
; #define PG8_LDA(dst, b, h) do { _Pragma("unroll") for (int m = 0; m < 4; ++m) _Pragma("unroll") for (int k = 0; k < 2; ++k) dst[m][k] = *(const PG8_LAS bf16x8*)(lds + PG8_SA(b, h) + aoff + m * 2048 + k * 1024); } while (0)
; #define PG8_LDB(dst, b, h) do { _Pragma("unroll") for (int n = 0; n < 2; ++n) _Pragma("unroll") for (int k = 0; k < 2; ++k) dst[n][k] = *(const PG8_LAS bf16x8*)(lds + PG8_SB(b, h) + boff + n * 2048 + k * 1024); } while (0)
; #define PG8_MMA(ai, bj, At, Bt) do { __builtin_amdgcn_s_setprio(1); _Pragma("unroll") for (int m = 0; m < 4; ++m) _Pragma("unroll") for (int n = 0; n < 2; ++n) _Pragma("unroll") for (int k = 0; k < 2; ++k) \
;         acc[ai][bj][m][n] = __builtin_amdgcn_mfma_f32_16x16x32_bf16(Bt[n][k], At[m][k], acc[ai][bj][m][n], 0, 0, 0); __builtin_amdgcn_s_setprio(0); } while (0)
; #define PG8_WAIT_V(n) asm volatile("s_waitcnt vmcnt(" #n ")" ::: "memory")
; #define PG8_WAIT_L(n) asm volatile("s_waitcnt lgkmcnt(" #n ")" ::: "memory")
; #define PG8_BAR __builtin_amdgcn_s_barrier()
; #define PG8_SCHED __builtin_amdgcn_sched_barrier(0)
; template <class Epi, class Sched, bool ALIGN_EPI = false, bool SP2 = true>
; __device__ __forceinline__ void gemm_phase(PG8_LAS unsigned char* lds, const Gemm g, const Sched& S, const Epi& E) {
;     ...
;             PG8_LDB(B0, 0, 0); PG8_LDB(B1, 0, 1); PG8_SCHED; PG8_LDA(At, 0, 0); PG8_STAGE(PG8_SA(1, 1), a1 + hstep, voffA);
;             PG8_WAIT_V(8); PG8_WAIT_L(0); PG8_BAR; PG8_MMA(0, 0, At, B0); PG8_MMA(0, 1, At, B1); PG8_BAR; PG8_SCHED;
;             if (full) { PG8_LDA(At, 0, 1); } PG8_STAGE(PG8_SB(0, 0), b2, voffB); PG8_STAGE(PG8_SB(0, 1), b2 + hstep, voffB); PG8_STAGE(PG8_SA(0, 0), a2, voffA);
;             PG8_WAIT_V(8); PG8_WAIT_L(0); PG8_BAR; if (full) { PG8_MMA(1, 0, At, B0); PG8_MMA(1, 1, At, B1); } PG8_BAR; PG8_SCHED;
.LBB0_503:
	ds_read_b128 v[150:153], v209
	ds_read_b128 v[154:157], v209 offset:1024
	ds_read_b128 v[158:161], v209 offset:2048
	ds_read_b128 v[162:165], v209 offset:3072
	ds_read_b128 v[134:137], v224
	ds_read_b128 v[138:141], v224 offset:1024
	ds_read_b128 v[142:145], v224 offset:2048
	ds_read_b128 v[146:149], v224 offset:3072
	s_add_i32 m0, s31, 0xc000
	s_waitcnt lgkmcnt(0)
	ds_read_b128 v[178:181], v225
	ds_read_b128 v[194:197], v225 offset:1024
	ds_read_b128 v[174:177], v225 offset:2048
	ds_read_b128 v[190:193], v225 offset:3072
	ds_read_b128 v[170:173], v225 offset:4096
	ds_read_b128 v[186:189], v225 offset:5120
	ds_read_b128 v[166:169], v225 offset:6144
	ds_read_b128 v[182:185], v225 offset:7168
	global_load_lds_dwordx4 v210, s[34:35]
	s_add_i32 m0, s31, 0xe000
	s_nop 0
	global_load_lds_dwordx4 v212, s[34:35]
	s_waitcnt vmcnt(8)
	s_waitcnt lgkmcnt(0)
	s_setprio 1
	s_barrier
	v_mfma_f32_16x16x32_bf16 v[130:133], v[150:153], v[178:181], v[130:133]
	v_mfma_f32_16x16x32_bf16 v[126:129], v[158:161], v[178:181], v[126:129]
	v_mfma_f32_16x16x32_bf16 v[114:117], v[150:153], v[174:177], v[114:117]
	v_mfma_f32_16x16x32_bf16 v[110:113], v[158:161], v[174:177], v[110:113]
	v_mfma_f32_16x16x32_bf16 v[98:101], v[150:153], v[170:173], v[98:101]
	v_mfma_f32_16x16x32_bf16 v[94:97], v[158:161], v[170:173], v[94:97]
	v_mfma_f32_16x16x32_bf16 v[82:85], v[150:153], v[166:169], v[82:85]
	v_mfma_f32_16x16x32_bf16 v[78:81], v[158:161], v[166:169], v[78:81]
	v_mfma_f32_16x16x32_bf16 v[130:133], v[154:157], v[194:197], v[130:133]
	v_mfma_f32_16x16x32_bf16 v[126:129], v[162:165], v[194:197], v[126:129]
	v_mfma_f32_16x16x32_bf16 v[114:117], v[154:157], v[190:193], v[114:117]
	v_mfma_f32_16x16x32_bf16 v[110:113], v[162:165], v[190:193], v[110:113]
	v_mfma_f32_16x16x32_bf16 v[98:101], v[154:157], v[186:189], v[98:101]
	v_mfma_f32_16x16x32_bf16 v[94:97], v[162:165], v[186:189], v[94:97]
	v_mfma_f32_16x16x32_bf16 v[82:85], v[154:157], v[182:185], v[82:85]
	v_mfma_f32_16x16x32_bf16 v[78:81], v[162:165], v[182:185], v[78:81]
	v_mfma_f32_16x16x32_bf16 v[122:125], v[134:137], v[178:181], v[122:125]
	v_mfma_f32_16x16x32_bf16 v[118:121], v[142:145], v[178:181], v[118:121]
	v_mfma_f32_16x16x32_bf16 v[106:109], v[134:137], v[174:177], v[106:109]
	v_mfma_f32_16x16x32_bf16 v[102:105], v[142:145], v[174:177], v[102:105]
	v_mfma_f32_16x16x32_bf16 v[90:93], v[134:137], v[170:173], v[90:93]
	v_mfma_f32_16x16x32_bf16 v[86:89], v[142:145], v[170:173], v[86:89]
	v_mfma_f32_16x16x32_bf16 v[74:77], v[134:137], v[166:169], v[74:77]
	v_mfma_f32_16x16x32_bf16 v[70:73], v[142:145], v[166:169], v[70:73]
	v_mfma_f32_16x16x32_bf16 v[122:125], v[138:141], v[194:197], v[122:125]
	v_mfma_f32_16x16x32_bf16 v[118:121], v[146:149], v[194:197], v[118:121]
	v_mfma_f32_16x16x32_bf16 v[106:109], v[138:141], v[190:193], v[106:109]
	v_mfma_f32_16x16x32_bf16 v[102:105], v[146:149], v[190:193], v[102:105]
	v_mfma_f32_16x16x32_bf16 v[90:93], v[138:141], v[186:189], v[90:93]
	v_mfma_f32_16x16x32_bf16 v[86:89], v[146:149], v[186:189], v[86:89]
	v_mfma_f32_16x16x32_bf16 v[74:77], v[138:141], v[182:185], v[74:77]
	v_mfma_f32_16x16x32_bf16 v[70:73], v[146:149], v[182:185], v[70:73]
	s_barrier
	s_setprio 0
	v_cmp_ne_u32_e64 s[0:1], 1, v215
	s_andn2_b64 vcc, exec, s[2:3]
	s_cbranch_vccnz .LBB0_505
	ds_read_b128 v[178:181], v225 offset:16384
	ds_read_b128 v[194:197], v225 offset:17408
	ds_read_b128 v[174:177], v225 offset:18432
	ds_read_b128 v[190:193], v225 offset:19456
	ds_read_b128 v[170:173], v225 offset:20480
	ds_read_b128 v[186:189], v225 offset:21504
	ds_read_b128 v[166:169], v225 offset:22528
	ds_read_b128 v[182:185], v225 offset:23552
.LBB0_505:
	s_add_u32 s33, s34, 0xfff00080
	s_addc_u32 s36, s35, -1
	s_cmp_eq_u32 s67, s66
	s_cselect_b32 s39, s19, s36
	s_cselect_b32 s37, s21, s69
	s_cselect_b32 s36, s65, s68
	s_mov_b32 m0, s47
	s_cselect_b32 s38, s23, s33
	s_add_u32 s70, s36, 0x100000
	global_load_lds_dwordx4 v202, s[36:37]
	s_mov_b32 m0, s48
	s_addc_u32 s71, s37, 0
	global_load_lds_dwordx4 v206, s[36:37]
	s_mov_b32 m0, s49
	s_nop 0
	global_load_lds_dwordx4 v202, s[70:71]
	s_mov_b32 m0, s50
	s_and_b64 vcc, exec, s[0:1]
	global_load_lds_dwordx4 v206, s[70:71]
	s_mov_b32 m0, s31
	s_nop 0
	global_load_lds_dwordx4 v200, s[38:39]
	s_mov_b32 m0, s51
	s_nop 0
	global_load_lds_dwordx4 v204, s[38:39]
	s_waitcnt vmcnt(8)
	s_waitcnt lgkmcnt(0)
	s_setprio 1
	s_barrier
	s_cbranch_vccnz .LBB0_507
	v_mfma_f32_16x16x32_bf16 v[66:69], v[150:153], v[178:181], v[66:69]
	v_mfma_f32_16x16x32_bf16 v[62:65], v[158:161], v[178:181], v[62:65]
	v_mfma_f32_16x16x32_bf16 v[50:53], v[150:153], v[174:177], v[50:53]
	v_mfma_f32_16x16x32_bf16 v[46:49], v[158:161], v[174:177], v[46:49]
	v_mfma_f32_16x16x32_bf16 v[34:37], v[150:153], v[170:173], v[34:37]
	v_mfma_f32_16x16x32_bf16 v[30:33], v[158:161], v[170:173], v[30:33]
	v_mfma_f32_16x16x32_bf16 v[18:21], v[150:153], v[166:169], v[18:21]
	v_mfma_f32_16x16x32_bf16 v[14:17], v[158:161], v[166:169], v[14:17]
	v_mfma_f32_16x16x32_bf16 v[66:69], v[154:157], v[194:197], v[66:69]
	v_mfma_f32_16x16x32_bf16 v[62:65], v[162:165], v[194:197], v[62:65]
	v_mfma_f32_16x16x32_bf16 v[50:53], v[154:157], v[190:193], v[50:53]
	v_mfma_f32_16x16x32_bf16 v[46:49], v[162:165], v[190:193], v[46:49]
	v_mfma_f32_16x16x32_bf16 v[34:37], v[154:157], v[186:189], v[34:37]
	v_mfma_f32_16x16x32_bf16 v[30:33], v[162:165], v[186:189], v[30:33]
	v_mfma_f32_16x16x32_bf16 v[18:21], v[154:157], v[182:185], v[18:21]
	v_mfma_f32_16x16x32_bf16 v[14:17], v[162:165], v[182:185], v[14:17]
	v_mfma_f32_16x16x32_bf16 v[58:61], v[134:137], v[178:181], v[58:61]
	v_mfma_f32_16x16x32_bf16 v[54:57], v[142:145], v[178:181], v[54:57]
	v_mfma_f32_16x16x32_bf16 v[42:45], v[134:137], v[174:177], v[42:45]
	v_mfma_f32_16x16x32_bf16 v[38:41], v[142:145], v[174:177], v[38:41]
	v_mfma_f32_16x16x32_bf16 v[26:29], v[134:137], v[170:173], v[26:29]
	v_mfma_f32_16x16x32_bf16 v[22:25], v[142:145], v[170:173], v[22:25]
	v_mfma_f32_16x16x32_bf16 v[10:13], v[134:137], v[166:169], v[10:13]
	v_mfma_f32_16x16x32_bf16 v[6:9], v[142:145], v[166:169], v[6:9]
	v_mfma_f32_16x16x32_bf16 v[58:61], v[138:141], v[194:197], v[58:61]
	v_mfma_f32_16x16x32_bf16 v[54:57], v[146:149], v[194:197], v[54:57]
	v_mfma_f32_16x16x32_bf16 v[42:45], v[138:141], v[190:193], v[42:45]
	v_mfma_f32_16x16x32_bf16 v[38:41], v[146:149], v[190:193], v[38:41]
	v_mfma_f32_16x16x32_bf16 v[26:29], v[138:141], v[186:189], v[26:29]
	v_mfma_f32_16x16x32_bf16 v[22:25], v[146:149], v[186:189], v[22:25]
	v_mfma_f32_16x16x32_bf16 v[10:13], v[138:141], v[182:185], v[10:13]
	v_mfma_f32_16x16x32_bf16 v[6:9], v[146:149], v[182:185], v[6:9]
; #define PG8_STAGE(bufoff, gbase, voff) do { _Pragma("unroll") for (int _i = 0; _i < 2; ++_i) \
;         __builtin_amdgcn_global_load_lds((const unsigned*)((const char*)(gbase) + (voff)[_i]), (PG8_LAS unsigned*)(lds + (bufoff) + ldsw + _i * 8192), 16, 0, 0); } while (0)
; #define PG8_LDA(dst, b, h) do { _Pragma("unroll") for (int m = 0; m < 4; ++m) _Pragma("unroll") for (int k = 0; k < 2; ++k) dst[m][k] = *(const PG8_LAS bf16x8*)(lds + PG8_SA(b, h) + aoff + m * 2048 + k * 1024); } while (0)
; #define PG8_LDB(dst, b, h) do { _Pragma("unroll") for (int n = 0; n < 2; ++n) _Pragma("unroll") for (int k = 0; k < 2; ++k) dst[n][k] = *(const PG8_LAS bf16x8*)(lds + PG8_SB(b, h) + boff + n * 2048 + k * 1024); } while (0)
; #define PG8_MMA(ai, bj, At, Bt) do { __builtin_amdgcn_s_setprio(1); _Pragma("unroll") for (int m = 0; m < 4; ++m) _Pragma("unroll") for (int n = 0; n < 2; ++n) _Pragma("unroll") for (int k = 0; k < 2; ++k) \
;         acc[ai][bj][m][n] = __builtin_amdgcn_mfma_f32_16x16x32_bf16(Bt[n][k], At[m][k], acc[ai][bj][m][n], 0, 0, 0); __builtin_amdgcn_s_setprio(0); } while (0)
; #define PG8_WAIT_V(n) asm volatile("s_waitcnt vmcnt(" #n ")" ::: "memory")
; #define PG8_WAIT_L(n) asm volatile("s_waitcnt lgkmcnt(" #n ")" ::: "memory")
; #define PG8_BAR __builtin_amdgcn_s_barrier()
; #define PG8_SCHED __builtin_amdgcn_sched_barrier(0)
; template <class Epi, class Sched, bool ALIGN_EPI = false, bool SP2 = true>
; __device__ __forceinline__ void gemm_phase(PG8_LAS unsigned char* lds, const Gemm g, const Sched& S, const Epi& E) {
;     ...
;             PG8_LDB(B0, 1, 0); PG8_LDB(B1, 1, 1); PG8_SCHED; PG8_LDA(At, 1, 0); PG8_STAGE(PG8_SA(0, 1), a2 + hstep, voffA);
;             PG8_WAIT_V(8); PG8_WAIT_L(0); PG8_BAR; PG8_MMA(0, 0, At, B0); PG8_MMA(0, 1, At, B1); PG8_BAR; PG8_SCHED;
;             if (full) { PG8_LDA(At, 1, 1); } PG8_STAGE(PG8_SB(1, 0), b3, voffB); PG8_STAGE(PG8_SB(1, 1), b3 + hstep, voffB); PG8_STAGE(PG8_SA(1, 0), a3, voffA);
;             PG8_WAIT_V(8); PG8_WAIT_L(0); PG8_BAR; if (full) { PG8_MMA(1, 0, At, B0); PG8_MMA(1, 1, At, B1); } PG8_BAR; PG8_SCHED;
.LBB0_507:
	s_barrier
	s_setprio 0
	v_add_u32_e32 v3, 0x18000, v199
	ds_read_b128 v[150:153], v3
	ds_read_b128 v[154:157], v3 offset:1024
	ds_read_b128 v[158:161], v3 offset:2048
	ds_read_b128 v[162:165], v3 offset:3072
	v_add_u32_e32 v3, 0x1c000, v199
	ds_read_b128 v[134:137], v3
	ds_read_b128 v[138:141], v3 offset:1024
	ds_read_b128 v[142:145], v3 offset:2048
	ds_read_b128 v[146:149], v3 offset:3072
	s_add_u32 s38, s38, 0x100000
	s_addc_u32 s39, s39, 0
	s_mov_b32 m0, s52
	s_waitcnt lgkmcnt(0)
	ds_read_b128 v[178:181], v225 offset:32768
	ds_read_b128 v[194:197], v225 offset:33792
	ds_read_b128 v[174:177], v225 offset:34816
	ds_read_b128 v[190:193], v225 offset:35840
	ds_read_b128 v[170:173], v225 offset:36864
	ds_read_b128 v[186:189], v225 offset:37888
	ds_read_b128 v[166:169], v225 offset:38912
	ds_read_b128 v[182:185], v225 offset:39936
	global_load_lds_dwordx4 v200, s[38:39]
	s_mov_b32 m0, s53
	s_nop 0
	global_load_lds_dwordx4 v204, s[38:39]
	s_waitcnt vmcnt(8)
	s_waitcnt lgkmcnt(0)
	s_setprio 1
	s_barrier
	v_mfma_f32_16x16x32_bf16 v[130:133], v[150:153], v[178:181], v[130:133]
	v_mfma_f32_16x16x32_bf16 v[126:129], v[158:161], v[178:181], v[126:129]
	v_mfma_f32_16x16x32_bf16 v[114:117], v[150:153], v[174:177], v[114:117]
	v_mfma_f32_16x16x32_bf16 v[110:113], v[158:161], v[174:177], v[110:113]
	v_mfma_f32_16x16x32_bf16 v[98:101], v[150:153], v[170:173], v[98:101]
	v_mfma_f32_16x16x32_bf16 v[94:97], v[158:161], v[170:173], v[94:97]
	v_mfma_f32_16x16x32_bf16 v[82:85], v[150:153], v[166:169], v[82:85]
	v_mfma_f32_16x16x32_bf16 v[78:81], v[158:161], v[166:169], v[78:81]
	v_mfma_f32_16x16x32_bf16 v[130:133], v[154:157], v[194:197], v[130:133]
	v_mfma_f32_16x16x32_bf16 v[126:129], v[162:165], v[194:197], v[126:129]
	v_mfma_f32_16x16x32_bf16 v[114:117], v[154:157], v[190:193], v[114:117]
	v_mfma_f32_16x16x32_bf16 v[110:113], v[162:165], v[190:193], v[110:113]
	v_mfma_f32_16x16x32_bf16 v[98:101], v[154:157], v[186:189], v[98:101]
	v_mfma_f32_16x16x32_bf16 v[94:97], v[162:165], v[186:189], v[94:97]
	v_mfma_f32_16x16x32_bf16 v[82:85], v[154:157], v[182:185], v[82:85]
	v_mfma_f32_16x16x32_bf16 v[78:81], v[162:165], v[182:185], v[78:81]
	v_mfma_f32_16x16x32_bf16 v[122:125], v[134:137], v[178:181], v[122:125]
	v_mfma_f32_16x16x32_bf16 v[118:121], v[142:145], v[178:181], v[118:121]
	v_mfma_f32_16x16x32_bf16 v[106:109], v[134:137], v[174:177], v[106:109]
	v_mfma_f32_16x16x32_bf16 v[102:105], v[142:145], v[174:177], v[102:105]
	v_mfma_f32_16x16x32_bf16 v[90:93], v[134:137], v[170:173], v[90:93]
	v_mfma_f32_16x16x32_bf16 v[86:89], v[142:145], v[170:173], v[86:89]
	v_mfma_f32_16x16x32_bf16 v[74:77], v[134:137], v[166:169], v[74:77]
	v_mfma_f32_16x16x32_bf16 v[70:73], v[142:145], v[166:169], v[70:73]
	v_mfma_f32_16x16x32_bf16 v[122:125], v[138:141], v[194:197], v[122:125]
	v_mfma_f32_16x16x32_bf16 v[118:121], v[146:149], v[194:197], v[118:121]
	v_mfma_f32_16x16x32_bf16 v[106:109], v[138:141], v[190:193], v[106:109]
	v_mfma_f32_16x16x32_bf16 v[102:105], v[146:149], v[190:193], v[102:105]
	v_mfma_f32_16x16x32_bf16 v[90:93], v[138:141], v[186:189], v[90:93]
	v_mfma_f32_16x16x32_bf16 v[86:89], v[146:149], v[186:189], v[86:89]
	v_mfma_f32_16x16x32_bf16 v[74:77], v[138:141], v[182:185], v[74:77]
	v_mfma_f32_16x16x32_bf16 v[70:73], v[146:149], v[182:185], v[70:73]
	s_barrier
	s_setprio 0
	s_and_b64 vcc, exec, s[0:1]
	s_cbranch_vccnz .LBB0_509
	ds_read_b128 v[178:181], v225 offset:49152
	ds_read_b128 v[194:197], v225 offset:50176
	ds_read_b128 v[174:177], v225 offset:51200
	ds_read_b128 v[190:193], v225 offset:52224
	ds_read_b128 v[170:173], v225 offset:53248
	ds_read_b128 v[186:189], v225 offset:54272
	ds_read_b128 v[166:169], v225 offset:55296
	ds_read_b128 v[182:185], v225 offset:56320
.LBB0_509:
	s_mov_b32 m0, s55
	s_add_u32 s98, s36, 0x80
	s_addc_u32 s99, s37, 0
	s_add_u32 s36, s36, 0x100080
	global_load_lds_dwordx4 v202, s[98:99]
	s_mov_b32 m0, s56
	s_addc_u32 s37, s37, 0
	global_load_lds_dwordx4 v206, s[98:99]
	s_mov_b32 m0, s59
	s_and_b64 vcc, exec, s[0:1]
	global_load_lds_dwordx4 v202, s[36:37]
	s_mov_b32 m0, s60
	s_nop 0
	global_load_lds_dwordx4 v206, s[36:37]
	s_mov_b32 m0, s57
	s_nop 0
	s_add_u32 s100, s38, 0xfff00080
	s_addc_u32 s101, s39, -1
	global_load_lds_dwordx4 v200, s[100:101]
	s_mov_b32 m0, s58
	s_nop 0
	global_load_lds_dwordx4 v204, s[100:101]
	s_waitcnt vmcnt(8)
	s_waitcnt lgkmcnt(0)
	s_setprio 1
	s_barrier
	s_cbranch_vccnz .LBB0_502
	v_mfma_f32_16x16x32_bf16 v[66:69], v[150:153], v[178:181], v[66:69]
	v_mfma_f32_16x16x32_bf16 v[62:65], v[158:161], v[178:181], v[62:65]
	v_mfma_f32_16x16x32_bf16 v[50:53], v[150:153], v[174:177], v[50:53]
	v_mfma_f32_16x16x32_bf16 v[46:49], v[158:161], v[174:177], v[46:49]
	v_mfma_f32_16x16x32_bf16 v[34:37], v[150:153], v[170:173], v[34:37]
	v_mfma_f32_16x16x32_bf16 v[30:33], v[158:161], v[170:173], v[30:33]
	v_mfma_f32_16x16x32_bf16 v[18:21], v[150:153], v[166:169], v[18:21]
	v_mfma_f32_16x16x32_bf16 v[14:17], v[158:161], v[166:169], v[14:17]
	v_mfma_f32_16x16x32_bf16 v[66:69], v[154:157], v[194:197], v[66:69]
	v_mfma_f32_16x16x32_bf16 v[62:65], v[162:165], v[194:197], v[62:65]
	v_mfma_f32_16x16x32_bf16 v[50:53], v[154:157], v[190:193], v[50:53]
	v_mfma_f32_16x16x32_bf16 v[46:49], v[162:165], v[190:193], v[46:49]
	v_mfma_f32_16x16x32_bf16 v[34:37], v[154:157], v[186:189], v[34:37]
	v_mfma_f32_16x16x32_bf16 v[30:33], v[162:165], v[186:189], v[30:33]
	v_mfma_f32_16x16x32_bf16 v[18:21], v[154:157], v[182:185], v[18:21]
	v_mfma_f32_16x16x32_bf16 v[14:17], v[162:165], v[182:185], v[14:17]
	v_mfma_f32_16x16x32_bf16 v[58:61], v[134:137], v[178:181], v[58:61]
	v_mfma_f32_16x16x32_bf16 v[54:57], v[142:145], v[178:181], v[54:57]
	v_mfma_f32_16x16x32_bf16 v[42:45], v[134:137], v[174:177], v[42:45]
	v_mfma_f32_16x16x32_bf16 v[38:41], v[142:145], v[174:177], v[38:41]
	v_mfma_f32_16x16x32_bf16 v[26:29], v[134:137], v[170:173], v[26:29]
	v_mfma_f32_16x16x32_bf16 v[22:25], v[142:145], v[170:173], v[22:25]
	v_mfma_f32_16x16x32_bf16 v[10:13], v[134:137], v[166:169], v[10:13]
	v_mfma_f32_16x16x32_bf16 v[4:7], v[142:145], v[166:169], v[6:9]
	v_mfma_f32_16x16x32_bf16 v[58:61], v[138:141], v[194:197], v[58:61]
	v_mfma_f32_16x16x32_bf16 v[54:57], v[146:149], v[194:197], v[54:57]
	v_mfma_f32_16x16x32_bf16 v[42:45], v[138:141], v[190:193], v[42:45]
	v_mfma_f32_16x16x32_bf16 v[38:41], v[146:149], v[190:193], v[38:41]
	v_mfma_f32_16x16x32_bf16 v[26:29], v[138:141], v[186:189], v[26:29]
	v_mfma_f32_16x16x32_bf16 v[22:25], v[146:149], v[186:189], v[22:25]
	v_mfma_f32_16x16x32_bf16 v[10:13], v[138:141], v[182:185], v[10:13]
	v_mfma_f32_16x16x32_bf16 v[6:9], v[146:149], v[182:185], v[4:7]
	s_branch .LBB0_502

; #define PG8_STAGE(bufoff, gbase, voff) do { _Pragma("unroll") for (int _i = 0; _i < 2; ++_i) \
;         __builtin_amdgcn_global_load_lds((const unsigned*)((const char*)(gbase) + (voff)[_i]), (PG8_LAS unsigned*)(lds + (bufoff) + ldsw + _i * 8192), 16, 0, 0); } while (0)
; #define PG8_LDA(dst, b, h) do { _Pragma("unroll") for (int m = 0; m < 4; ++m) _Pragma("unroll") for (int k = 0; k < 2; ++k) dst[m][k] = *(const PG8_LAS bf16x8*)(lds + PG8_SA(b, h) + aoff + m * 2048 + k * 1024); } while (0)
; #define PG8_LDB(dst, b, h) do { _Pragma("unroll") for (int n = 0; n < 2; ++n) _Pragma("unroll") for (int k = 0; k < 2; ++k) dst[n][k] = *(const PG8_LAS bf16x8*)(lds + PG8_SB(b, h) + boff + n * 2048 + k * 1024); } while (0)
; #define PG8_MMA(ai, bj, At, Bt) do { __builtin_amdgcn_s_setprio(1); _Pragma("unroll") for (int m = 0; m < 4; ++m) _Pragma("unroll") for (int n = 0; n < 2; ++n) _Pragma("unroll") for (int k = 0; k < 2; ++k) \
;         acc[ai][bj][m][n] = __builtin_amdgcn_mfma_f32_16x16x32_bf16(Bt[n][k], At[m][k], acc[ai][bj][m][n], 0, 0, 0); __builtin_amdgcn_s_setprio(0); } while (0)
; #define PG8_WAIT_V(n) asm volatile("s_waitcnt vmcnt(" #n ")" ::: "memory")
; #define PG8_WAIT_L(n) asm volatile("s_waitcnt lgkmcnt(" #n ")" ::: "memory")
; #define PG8_BAR __builtin_amdgcn_s_barrier()
; #define PG8_SCHED __builtin_amdgcn_sched_barrier(0)
; template <class Epi, class Sched, bool ALIGN_EPI = false, bool SP2 = true>
; __device__ __forceinline__ void gemm_phase(PG8_LAS unsigned char* lds, const Gemm g, const Sched& S, const Epi& E) {
;     ...
;             PG8_LDB(B0, 0, 0); PG8_LDB(B1, 0, 1); PG8_SCHED; PG8_LDA(At, 0, 0); PG8_STAGE(PG8_SA(1, 1), a1 + hstep, voffA);
;             PG8_WAIT_V(8); PG8_WAIT_L(0); PG8_BAR; PG8_MMA(0, 0, At, B0); PG8_MMA(0, 1, At, B1); PG8_BAR; PG8_SCHED;
;             if (full) { PG8_LDA(At, 0, 1); } PG8_STAGE(PG8_SB(0, 0), b2, voffB); PG8_STAGE(PG8_SB(0, 1), b2 + hstep, voffB); PG8_STAGE(PG8_SA(0, 0), a2, voffA);
;             PG8_WAIT_V(8); PG8_WAIT_L(0); PG8_BAR; if (full) { PG8_MMA(1, 0, At, B0); PG8_MMA(1, 1, At, B1); } PG8_BAR; PG8_SCHED;
.LBB0_918:
	ds_read_b128 v[150:153], v209
	ds_read_b128 v[154:157], v209 offset:1024
	ds_read_b128 v[158:161], v209 offset:2048
	ds_read_b128 v[162:165], v209 offset:3072
	ds_read_b128 v[134:137], v224
	ds_read_b128 v[138:141], v224 offset:1024
	ds_read_b128 v[142:145], v224 offset:2048
	ds_read_b128 v[146:149], v224 offset:3072
	s_add_i32 m0, s31, 0xc000
	s_waitcnt lgkmcnt(0)
	ds_read_b128 v[178:181], v225
	ds_read_b128 v[194:197], v225 offset:1024
	ds_read_b128 v[174:177], v225 offset:2048
	ds_read_b128 v[190:193], v225 offset:3072
	ds_read_b128 v[170:173], v225 offset:4096
	ds_read_b128 v[186:189], v225 offset:5120
	ds_read_b128 v[166:169], v225 offset:6144
	ds_read_b128 v[182:185], v225 offset:7168
	global_load_lds_dwordx4 v212, s[2:3]
	s_add_i32 m0, s31, 0xe000
	s_nop 0
	global_load_lds_dwordx4 v214, s[2:3]
	s_waitcnt vmcnt(8)
	s_waitcnt lgkmcnt(0)
	s_setprio 1
	s_barrier
	v_mfma_f32_16x16x32_bf16 v[130:133], v[150:153], v[178:181], v[130:133]
	v_mfma_f32_16x16x32_bf16 v[126:129], v[158:161], v[178:181], v[126:129]
	v_mfma_f32_16x16x32_bf16 v[114:117], v[150:153], v[174:177], v[114:117]
	v_mfma_f32_16x16x32_bf16 v[110:113], v[158:161], v[174:177], v[110:113]
	v_mfma_f32_16x16x32_bf16 v[98:101], v[150:153], v[170:173], v[98:101]
	v_mfma_f32_16x16x32_bf16 v[94:97], v[158:161], v[170:173], v[94:97]
	v_mfma_f32_16x16x32_bf16 v[82:85], v[150:153], v[166:169], v[82:85]
	v_mfma_f32_16x16x32_bf16 v[78:81], v[158:161], v[166:169], v[78:81]
	v_mfma_f32_16x16x32_bf16 v[130:133], v[154:157], v[194:197], v[130:133]
	v_mfma_f32_16x16x32_bf16 v[126:129], v[162:165], v[194:197], v[126:129]
	v_mfma_f32_16x16x32_bf16 v[114:117], v[154:157], v[190:193], v[114:117]
	v_mfma_f32_16x16x32_bf16 v[110:113], v[162:165], v[190:193], v[110:113]
	v_mfma_f32_16x16x32_bf16 v[98:101], v[154:157], v[186:189], v[98:101]
	v_mfma_f32_16x16x32_bf16 v[94:97], v[162:165], v[186:189], v[94:97]
	v_mfma_f32_16x16x32_bf16 v[82:85], v[154:157], v[182:185], v[82:85]
	v_mfma_f32_16x16x32_bf16 v[78:81], v[162:165], v[182:185], v[78:81]
	v_mfma_f32_16x16x32_bf16 v[122:125], v[134:137], v[178:181], v[122:125]
	v_mfma_f32_16x16x32_bf16 v[118:121], v[142:145], v[178:181], v[118:121]
	v_mfma_f32_16x16x32_bf16 v[106:109], v[134:137], v[174:177], v[106:109]
	v_mfma_f32_16x16x32_bf16 v[102:105], v[142:145], v[174:177], v[102:105]
	v_mfma_f32_16x16x32_bf16 v[90:93], v[134:137], v[170:173], v[90:93]
	v_mfma_f32_16x16x32_bf16 v[86:89], v[142:145], v[170:173], v[86:89]
	v_mfma_f32_16x16x32_bf16 v[74:77], v[134:137], v[166:169], v[74:77]
	v_mfma_f32_16x16x32_bf16 v[70:73], v[142:145], v[166:169], v[70:73]
	v_mfma_f32_16x16x32_bf16 v[122:125], v[138:141], v[194:197], v[122:125]
	v_mfma_f32_16x16x32_bf16 v[118:121], v[146:149], v[194:197], v[118:121]
	v_mfma_f32_16x16x32_bf16 v[106:109], v[138:141], v[190:193], v[106:109]
	v_mfma_f32_16x16x32_bf16 v[102:105], v[146:149], v[190:193], v[102:105]
	v_mfma_f32_16x16x32_bf16 v[90:93], v[138:141], v[186:189], v[90:93]
	v_mfma_f32_16x16x32_bf16 v[86:89], v[146:149], v[186:189], v[86:89]
	v_mfma_f32_16x16x32_bf16 v[74:77], v[138:141], v[182:185], v[74:77]
	v_mfma_f32_16x16x32_bf16 v[70:73], v[146:149], v[182:185], v[70:73]
	s_barrier
	s_setprio 0
	v_cmp_ne_u32_e64 s[4:5], 1, v226
	s_andn2_b64 vcc, exec, s[36:37]
	s_cbranch_vccnz .LBB0_920
	ds_read_b128 v[178:181], v225 offset:16384
	ds_read_b128 v[194:197], v225 offset:17408
	ds_read_b128 v[174:177], v225 offset:18432
	ds_read_b128 v[190:193], v225 offset:19456
	ds_read_b128 v[170:173], v225 offset:20480
	ds_read_b128 v[186:189], v225 offset:21504
	ds_read_b128 v[166:169], v225 offset:22528
	ds_read_b128 v[182:185], v225 offset:23552
.LBB0_920:
	s_add_u32 s38, s2, 0xfff80080
	s_addc_u32 s39, s3, -1
	s_cmp_eq_u32 s68, s71
	s_cselect_b32 s41, s19, s39
	s_cselect_b32 s40, s21, s38
	s_cselect_b32 s39, s23, s70
	s_cselect_b32 s38, s67, s69
	s_mov_b32 m0, s35
	s_add_u32 s72, s38, 0x80000
	global_load_lds_dwordx4 v202, s[38:39]
	s_mov_b32 m0, s49
	s_addc_u32 s73, s39, 0
	global_load_lds_dwordx4 v206, s[38:39]
	s_mov_b32 m0, s50
	s_nop 0
	global_load_lds_dwordx4 v202, s[72:73]
	s_mov_b32 m0, s51
	s_and_b64 vcc, exec, s[4:5]
	global_load_lds_dwordx4 v206, s[72:73]
	s_mov_b32 m0, s31
	s_nop 0
	global_load_lds_dwordx4 v200, s[40:41]
	s_mov_b32 m0, s52
	s_nop 0
	global_load_lds_dwordx4 v204, s[40:41]
	s_waitcnt vmcnt(8)
	s_waitcnt lgkmcnt(0)
	s_setprio 1
	s_barrier
	s_cbranch_vccnz .LBB0_922
	v_mfma_f32_16x16x32_bf16 v[66:69], v[150:153], v[178:181], v[66:69]
	v_mfma_f32_16x16x32_bf16 v[62:65], v[158:161], v[178:181], v[62:65]
	v_mfma_f32_16x16x32_bf16 v[50:53], v[150:153], v[174:177], v[50:53]
	v_mfma_f32_16x16x32_bf16 v[46:49], v[158:161], v[174:177], v[46:49]
	v_mfma_f32_16x16x32_bf16 v[34:37], v[150:153], v[170:173], v[34:37]
	v_mfma_f32_16x16x32_bf16 v[30:33], v[158:161], v[170:173], v[30:33]
	v_mfma_f32_16x16x32_bf16 v[18:21], v[150:153], v[166:169], v[18:21]
	v_mfma_f32_16x16x32_bf16 v[14:17], v[158:161], v[166:169], v[14:17]
	v_mfma_f32_16x16x32_bf16 v[66:69], v[154:157], v[194:197], v[66:69]
	v_mfma_f32_16x16x32_bf16 v[62:65], v[162:165], v[194:197], v[62:65]
	v_mfma_f32_16x16x32_bf16 v[50:53], v[154:157], v[190:193], v[50:53]
	v_mfma_f32_16x16x32_bf16 v[46:49], v[162:165], v[190:193], v[46:49]
	v_mfma_f32_16x16x32_bf16 v[34:37], v[154:157], v[186:189], v[34:37]
	v_mfma_f32_16x16x32_bf16 v[30:33], v[162:165], v[186:189], v[30:33]
	v_mfma_f32_16x16x32_bf16 v[18:21], v[154:157], v[182:185], v[18:21]
	v_mfma_f32_16x16x32_bf16 v[14:17], v[162:165], v[182:185], v[14:17]
	v_mfma_f32_16x16x32_bf16 v[58:61], v[134:137], v[178:181], v[58:61]
	v_mfma_f32_16x16x32_bf16 v[54:57], v[142:145], v[178:181], v[54:57]
	v_mfma_f32_16x16x32_bf16 v[42:45], v[134:137], v[174:177], v[42:45]
	v_mfma_f32_16x16x32_bf16 v[38:41], v[142:145], v[174:177], v[38:41]
	v_mfma_f32_16x16x32_bf16 v[26:29], v[134:137], v[170:173], v[26:29]
	v_mfma_f32_16x16x32_bf16 v[22:25], v[142:145], v[170:173], v[22:25]
	v_mfma_f32_16x16x32_bf16 v[10:13], v[134:137], v[166:169], v[10:13]
	v_mfma_f32_16x16x32_bf16 v[6:9], v[142:145], v[166:169], v[6:9]
	v_mfma_f32_16x16x32_bf16 v[58:61], v[138:141], v[194:197], v[58:61]
	v_mfma_f32_16x16x32_bf16 v[54:57], v[146:149], v[194:197], v[54:57]
	v_mfma_f32_16x16x32_bf16 v[42:45], v[138:141], v[190:193], v[42:45]
	v_mfma_f32_16x16x32_bf16 v[38:41], v[146:149], v[190:193], v[38:41]
	v_mfma_f32_16x16x32_bf16 v[26:29], v[138:141], v[186:189], v[26:29]
	v_mfma_f32_16x16x32_bf16 v[22:25], v[146:149], v[186:189], v[22:25]
	v_mfma_f32_16x16x32_bf16 v[10:13], v[138:141], v[182:185], v[10:13]
	v_mfma_f32_16x16x32_bf16 v[6:9], v[146:149], v[182:185], v[6:9]
; #define PG8_STAGE(bufoff, gbase, voff) do { _Pragma("unroll") for (int _i = 0; _i < 2; ++_i) \
;         __builtin_amdgcn_global_load_lds((const unsigned*)((const char*)(gbase) + (voff)[_i]), (PG8_LAS unsigned*)(lds + (bufoff) + ldsw + _i * 8192), 16, 0, 0); } while (0)
; #define PG8_LDA(dst, b, h) do { _Pragma("unroll") for (int m = 0; m < 4; ++m) _Pragma("unroll") for (int k = 0; k < 2; ++k) dst[m][k] = *(const PG8_LAS bf16x8*)(lds + PG8_SA(b, h) + aoff + m * 2048 + k * 1024); } while (0)
; #define PG8_LDB(dst, b, h) do { _Pragma("unroll") for (int n = 0; n < 2; ++n) _Pragma("unroll") for (int k = 0; k < 2; ++k) dst[n][k] = *(const PG8_LAS bf16x8*)(lds + PG8_SB(b, h) + boff + n * 2048 + k * 1024); } while (0)
; #define PG8_MMA(ai, bj, At, Bt) do { __builtin_amdgcn_s_setprio(1); _Pragma("unroll") for (int m = 0; m < 4; ++m) _Pragma("unroll") for (int n = 0; n < 2; ++n) _Pragma("unroll") for (int k = 0; k < 2; ++k) \
;         acc[ai][bj][m][n] = __builtin_amdgcn_mfma_f32_16x16x32_bf16(Bt[n][k], At[m][k], acc[ai][bj][m][n], 0, 0, 0); __builtin_amdgcn_s_setprio(0); } while (0)
; #define PG8_WAIT_V(n) asm volatile("s_waitcnt vmcnt(" #n ")" ::: "memory")
; #define PG8_WAIT_L(n) asm volatile("s_waitcnt lgkmcnt(" #n ")" ::: "memory")
; #define PG8_BAR __builtin_amdgcn_s_barrier()
; #define PG8_SCHED __builtin_amdgcn_sched_barrier(0)
; template <class Epi, class Sched, bool ALIGN_EPI = false, bool SP2 = true>
; __device__ __forceinline__ void gemm_phase(PG8_LAS unsigned char* lds, const Gemm g, const Sched& S, const Epi& E) {
;     ...
;             PG8_LDB(B0, 1, 0); PG8_LDB(B1, 1, 1); PG8_SCHED; PG8_LDA(At, 1, 0); PG8_STAGE(PG8_SA(0, 1), a2 + hstep, voffA);
;             PG8_WAIT_V(8); PG8_WAIT_L(0); PG8_BAR; PG8_MMA(0, 0, At, B0); PG8_MMA(0, 1, At, B1); PG8_BAR; PG8_SCHED;
;             if (full) { PG8_LDA(At, 1, 1); } PG8_STAGE(PG8_SB(1, 0), b3, voffB); PG8_STAGE(PG8_SB(1, 1), b3 + hstep, voffB); PG8_STAGE(PG8_SA(1, 0), a3, voffA);
;             PG8_WAIT_V(8); PG8_WAIT_L(0); PG8_BAR; if (full) { PG8_MMA(1, 0, At, B0); PG8_MMA(1, 1, At, B1); } PG8_BAR; PG8_SCHED;
.LBB0_922:
	s_barrier
	s_setprio 0
	v_add_u32_e32 v3, 0x18000, v199
	ds_read_b128 v[150:153], v3
	ds_read_b128 v[154:157], v3 offset:1024
	ds_read_b128 v[158:161], v3 offset:2048
	ds_read_b128 v[162:165], v3 offset:3072
	v_add_u32_e32 v3, 0x1c000, v199
	ds_read_b128 v[134:137], v3
	ds_read_b128 v[138:141], v3 offset:1024
	ds_read_b128 v[142:145], v3 offset:2048
	ds_read_b128 v[146:149], v3 offset:3072
	s_add_u32 s40, s40, 0x80000
	s_addc_u32 s41, s41, 0
	s_mov_b32 m0, s53
	s_waitcnt lgkmcnt(0)
	ds_read_b128 v[178:181], v225 offset:32768
	ds_read_b128 v[194:197], v225 offset:33792
	ds_read_b128 v[174:177], v225 offset:34816
	ds_read_b128 v[190:193], v225 offset:35840
	ds_read_b128 v[170:173], v225 offset:36864
	ds_read_b128 v[186:189], v225 offset:37888
	ds_read_b128 v[166:169], v225 offset:38912
	ds_read_b128 v[182:185], v225 offset:39936
	global_load_lds_dwordx4 v200, s[40:41]
	s_mov_b32 m0, s54
	s_nop 0
	global_load_lds_dwordx4 v204, s[40:41]
	s_waitcnt vmcnt(8)
	s_waitcnt lgkmcnt(0)
	s_setprio 1
	s_barrier
	v_mfma_f32_16x16x32_bf16 v[130:133], v[150:153], v[178:181], v[130:133]
	v_mfma_f32_16x16x32_bf16 v[126:129], v[158:161], v[178:181], v[126:129]
	v_mfma_f32_16x16x32_bf16 v[114:117], v[150:153], v[174:177], v[114:117]
	v_mfma_f32_16x16x32_bf16 v[110:113], v[158:161], v[174:177], v[110:113]
	v_mfma_f32_16x16x32_bf16 v[98:101], v[150:153], v[170:173], v[98:101]
	v_mfma_f32_16x16x32_bf16 v[94:97], v[158:161], v[170:173], v[94:97]
	v_mfma_f32_16x16x32_bf16 v[82:85], v[150:153], v[166:169], v[82:85]
	v_mfma_f32_16x16x32_bf16 v[78:81], v[158:161], v[166:169], v[78:81]
	v_mfma_f32_16x16x32_bf16 v[130:133], v[154:157], v[194:197], v[130:133]
	v_mfma_f32_16x16x32_bf16 v[126:129], v[162:165], v[194:197], v[126:129]
	v_mfma_f32_16x16x32_bf16 v[114:117], v[154:157], v[190:193], v[114:117]
	v_mfma_f32_16x16x32_bf16 v[110:113], v[162:165], v[190:193], v[110:113]
	v_mfma_f32_16x16x32_bf16 v[98:101], v[154:157], v[186:189], v[98:101]
	v_mfma_f32_16x16x32_bf16 v[94:97], v[162:165], v[186:189], v[94:97]
	v_mfma_f32_16x16x32_bf16 v[82:85], v[154:157], v[182:185], v[82:85]
	v_mfma_f32_16x16x32_bf16 v[78:81], v[162:165], v[182:185], v[78:81]
	v_mfma_f32_16x16x32_bf16 v[122:125], v[134:137], v[178:181], v[122:125]
	v_mfma_f32_16x16x32_bf16 v[118:121], v[142:145], v[178:181], v[118:121]
	v_mfma_f32_16x16x32_bf16 v[106:109], v[134:137], v[174:177], v[106:109]
	v_mfma_f32_16x16x32_bf16 v[102:105], v[142:145], v[174:177], v[102:105]
	v_mfma_f32_16x16x32_bf16 v[90:93], v[134:137], v[170:173], v[90:93]
	v_mfma_f32_16x16x32_bf16 v[86:89], v[142:145], v[170:173], v[86:89]
	v_mfma_f32_16x16x32_bf16 v[74:77], v[134:137], v[166:169], v[74:77]
	v_mfma_f32_16x16x32_bf16 v[70:73], v[142:145], v[166:169], v[70:73]
	v_mfma_f32_16x16x32_bf16 v[122:125], v[138:141], v[194:197], v[122:125]
	v_mfma_f32_16x16x32_bf16 v[118:121], v[146:149], v[194:197], v[118:121]
	v_mfma_f32_16x16x32_bf16 v[106:109], v[138:141], v[190:193], v[106:109]
	v_mfma_f32_16x16x32_bf16 v[102:105], v[146:149], v[190:193], v[102:105]
	v_mfma_f32_16x16x32_bf16 v[90:93], v[138:141], v[186:189], v[90:93]
	v_mfma_f32_16x16x32_bf16 v[86:89], v[146:149], v[186:189], v[86:89]
	v_mfma_f32_16x16x32_bf16 v[74:77], v[138:141], v[182:185], v[74:77]
	v_mfma_f32_16x16x32_bf16 v[70:73], v[146:149], v[182:185], v[70:73]
	s_barrier
	s_setprio 0
	s_and_b64 vcc, exec, s[4:5]
	s_cbranch_vccnz .LBB0_924
	ds_read_b128 v[178:181], v225 offset:49152
	ds_read_b128 v[194:197], v225 offset:50176
	ds_read_b128 v[174:177], v225 offset:51200
	ds_read_b128 v[190:193], v225 offset:52224
	ds_read_b128 v[170:173], v225 offset:53248
	ds_read_b128 v[186:189], v225 offset:54272
	ds_read_b128 v[166:169], v225 offset:55296
	ds_read_b128 v[182:185], v225 offset:56320
.LBB0_924:
	s_mov_b32 m0, s57
	s_add_u32 s98, s38, 0x80
	s_addc_u32 s99, s39, 0
	s_add_u32 s38, s38, 0x80080
	global_load_lds_dwordx4 v202, s[98:99]
	s_mov_b32 m0, s58
	s_addc_u32 s39, s39, 0
	global_load_lds_dwordx4 v206, s[98:99]
	s_mov_b32 m0, s61
	s_and_b64 vcc, exec, s[4:5]
	global_load_lds_dwordx4 v202, s[38:39]
	s_mov_b32 m0, s62
	s_nop 0
	global_load_lds_dwordx4 v206, s[38:39]
	s_mov_b32 m0, s59
	s_nop 0
	s_add_u32 s100, s40, 0xfff80080
	s_addc_u32 s101, s41, -1
	global_load_lds_dwordx4 v200, s[100:101]
	s_mov_b32 m0, s60
	s_nop 0
	global_load_lds_dwordx4 v204, s[100:101]
	s_waitcnt vmcnt(8)
	s_waitcnt lgkmcnt(0)
	s_setprio 1
	s_barrier
	s_cbranch_vccnz .LBB0_917
	v_mfma_f32_16x16x32_bf16 v[66:69], v[150:153], v[178:181], v[66:69]
	v_mfma_f32_16x16x32_bf16 v[62:65], v[158:161], v[178:181], v[62:65]
	v_mfma_f32_16x16x32_bf16 v[50:53], v[150:153], v[174:177], v[50:53]
	v_mfma_f32_16x16x32_bf16 v[46:49], v[158:161], v[174:177], v[46:49]
	v_mfma_f32_16x16x32_bf16 v[34:37], v[150:153], v[170:173], v[34:37]
	v_mfma_f32_16x16x32_bf16 v[30:33], v[158:161], v[170:173], v[30:33]
	v_mfma_f32_16x16x32_bf16 v[18:21], v[150:153], v[166:169], v[18:21]
	v_mfma_f32_16x16x32_bf16 v[14:17], v[158:161], v[166:169], v[14:17]
	v_mfma_f32_16x16x32_bf16 v[66:69], v[154:157], v[194:197], v[66:69]
	v_mfma_f32_16x16x32_bf16 v[62:65], v[162:165], v[194:197], v[62:65]
	v_mfma_f32_16x16x32_bf16 v[50:53], v[154:157], v[190:193], v[50:53]
	v_mfma_f32_16x16x32_bf16 v[46:49], v[162:165], v[190:193], v[46:49]
	v_mfma_f32_16x16x32_bf16 v[34:37], v[154:157], v[186:189], v[34:37]
	v_mfma_f32_16x16x32_bf16 v[30:33], v[162:165], v[186:189], v[30:33]
	v_mfma_f32_16x16x32_bf16 v[18:21], v[154:157], v[182:185], v[18:21]
	v_mfma_f32_16x16x32_bf16 v[14:17], v[162:165], v[182:185], v[14:17]
	v_mfma_f32_16x16x32_bf16 v[58:61], v[134:137], v[178:181], v[58:61]
	v_mfma_f32_16x16x32_bf16 v[54:57], v[142:145], v[178:181], v[54:57]
	v_mfma_f32_16x16x32_bf16 v[42:45], v[134:137], v[174:177], v[42:45]
	v_mfma_f32_16x16x32_bf16 v[38:41], v[142:145], v[174:177], v[38:41]
	v_mfma_f32_16x16x32_bf16 v[26:29], v[134:137], v[170:173], v[26:29]
	v_mfma_f32_16x16x32_bf16 v[22:25], v[142:145], v[170:173], v[22:25]
	v_mfma_f32_16x16x32_bf16 v[10:13], v[134:137], v[166:169], v[10:13]
	v_mfma_f32_16x16x32_bf16 v[4:7], v[142:145], v[166:169], v[6:9]
	v_mfma_f32_16x16x32_bf16 v[58:61], v[138:141], v[194:197], v[58:61]
	v_mfma_f32_16x16x32_bf16 v[54:57], v[146:149], v[194:197], v[54:57]
	v_mfma_f32_16x16x32_bf16 v[42:45], v[138:141], v[190:193], v[42:45]
	v_mfma_f32_16x16x32_bf16 v[38:41], v[146:149], v[190:193], v[38:41]
	v_mfma_f32_16x16x32_bf16 v[26:29], v[138:141], v[186:189], v[26:29]
	v_mfma_f32_16x16x32_bf16 v[22:25], v[146:149], v[186:189], v[22:25]
	v_mfma_f32_16x16x32_bf16 v[10:13], v[138:141], v[182:185], v[10:13]
	v_mfma_f32_16x16x32_bf16 v[6:9], v[146:149], v[182:185], v[4:7]
	s_branch .LBB0_917

; #define PG8_STAGE(bufoff, gbase, voff) do { _Pragma("unroll") for (int _i = 0; _i < 2; ++_i) \
;         __builtin_amdgcn_global_load_lds((const unsigned*)((const char*)(gbase) + (voff)[_i]), (PG8_LAS unsigned*)(lds + (bufoff) + ldsw + _i * 8192), 16, 0, 0); } while (0)
; #define PG8_LDA(dst, b, h) do { _Pragma("unroll") for (int m = 0; m < 4; ++m) _Pragma("unroll") for (int k = 0; k < 2; ++k) dst[m][k] = *(const PG8_LAS bf16x8*)(lds + PG8_SA(b, h) + aoff + m * 2048 + k * 1024); } while (0)
; #define PG8_LDB(dst, b, h) do { _Pragma("unroll") for (int n = 0; n < 2; ++n) _Pragma("unroll") for (int k = 0; k < 2; ++k) dst[n][k] = *(const PG8_LAS bf16x8*)(lds + PG8_SB(b, h) + boff + n * 2048 + k * 1024); } while (0)
; #define PG8_MMA(ai, bj, At, Bt) do { __builtin_amdgcn_s_setprio(1); _Pragma("unroll") for (int m = 0; m < 4; ++m) _Pragma("unroll") for (int n = 0; n < 2; ++n) _Pragma("unroll") for (int k = 0; k < 2; ++k) \
;         acc[ai][bj][m][n] = __builtin_amdgcn_mfma_f32_16x16x32_bf16(Bt[n][k], At[m][k], acc[ai][bj][m][n], 0, 0, 0); __builtin_amdgcn_s_setprio(0); } while (0)
; #define PG8_WAIT_V(n) asm volatile("s_waitcnt vmcnt(" #n ")" ::: "memory")
; #define PG8_WAIT_L(n) asm volatile("s_waitcnt lgkmcnt(" #n ")" ::: "memory")
; #define PG8_BAR __builtin_amdgcn_s_barrier()
; #define PG8_SCHED __builtin_amdgcn_sched_barrier(0)
; template <class Epi, class Sched, bool ALIGN_EPI = false, bool SP2 = true>
; __device__ __forceinline__ void gemm_phase(PG8_LAS unsigned char* lds, const Gemm g, const Sched& S, const Epi& E) {
;     ...
;             PG8_LDB(B0, 0, 0); PG8_LDB(B1, 0, 1); PG8_SCHED; PG8_LDA(At, 0, 0); PG8_STAGE(PG8_SA(1, 1), a1 + hstep, voffA);
;             PG8_WAIT_V(8); PG8_WAIT_L(0); PG8_BAR; PG8_MMA(0, 0, At, B0); PG8_MMA(0, 1, At, B1); PG8_BAR; PG8_SCHED;
;             if (full) { PG8_LDA(At, 0, 1); } PG8_STAGE(PG8_SB(0, 0), b2, voffB); PG8_STAGE(PG8_SB(0, 1), b2 + hstep, voffB); PG8_STAGE(PG8_SA(0, 0), a2, voffA);
;             PG8_WAIT_V(8); PG8_WAIT_L(0); PG8_BAR; if (full) { PG8_MMA(1, 0, At, B0); PG8_MMA(1, 1, At, B1); } PG8_BAR; PG8_SCHED;
.LBB0_1023:
	ds_read_b128 v[150:153], v209
	ds_read_b128 v[154:157], v209 offset:1024
	ds_read_b128 v[158:161], v209 offset:2048
	ds_read_b128 v[162:165], v209 offset:3072
	ds_read_b128 v[134:137], v230
	ds_read_b128 v[138:141], v230 offset:1024
	ds_read_b128 v[142:145], v230 offset:2048
	ds_read_b128 v[146:149], v230 offset:3072
	s_add_i32 m0, s43, 0xc000
	s_waitcnt lgkmcnt(0)
	ds_read_b128 v[178:181], v231
	ds_read_b128 v[194:197], v231 offset:1024
	ds_read_b128 v[174:177], v231 offset:2048
	ds_read_b128 v[190:193], v231 offset:3072
	ds_read_b128 v[170:173], v231 offset:4096
	ds_read_b128 v[186:189], v231 offset:5120
	ds_read_b128 v[166:169], v231 offset:6144
	ds_read_b128 v[182:185], v231 offset:7168
	global_load_lds_dwordx4 v218, s[44:45]
	s_add_i32 m0, s43, 0xe000
	s_nop 0
	global_load_lds_dwordx4 v220, s[44:45]
	s_waitcnt vmcnt(8)
	s_waitcnt lgkmcnt(0)
	s_setprio 1
	s_barrier
	v_mfma_f32_16x16x32_bf16 v[130:133], v[150:153], v[178:181], v[130:133]
	v_mfma_f32_16x16x32_bf16 v[126:129], v[158:161], v[178:181], v[126:129]
	v_mfma_f32_16x16x32_bf16 v[114:117], v[150:153], v[174:177], v[114:117]
	v_mfma_f32_16x16x32_bf16 v[110:113], v[158:161], v[174:177], v[110:113]
	v_mfma_f32_16x16x32_bf16 v[98:101], v[150:153], v[170:173], v[98:101]
	v_mfma_f32_16x16x32_bf16 v[94:97], v[158:161], v[170:173], v[94:97]
	v_mfma_f32_16x16x32_bf16 v[82:85], v[150:153], v[166:169], v[82:85]
	v_mfma_f32_16x16x32_bf16 v[78:81], v[158:161], v[166:169], v[78:81]
	v_mfma_f32_16x16x32_bf16 v[130:133], v[154:157], v[194:197], v[130:133]
	v_mfma_f32_16x16x32_bf16 v[126:129], v[162:165], v[194:197], v[126:129]
	v_mfma_f32_16x16x32_bf16 v[114:117], v[154:157], v[190:193], v[114:117]
	v_mfma_f32_16x16x32_bf16 v[110:113], v[162:165], v[190:193], v[110:113]
	v_mfma_f32_16x16x32_bf16 v[98:101], v[154:157], v[186:189], v[98:101]
	v_mfma_f32_16x16x32_bf16 v[94:97], v[162:165], v[186:189], v[94:97]
	v_mfma_f32_16x16x32_bf16 v[82:85], v[154:157], v[182:185], v[82:85]
	v_mfma_f32_16x16x32_bf16 v[78:81], v[162:165], v[182:185], v[78:81]
	v_mfma_f32_16x16x32_bf16 v[122:125], v[134:137], v[178:181], v[122:125]
	v_mfma_f32_16x16x32_bf16 v[118:121], v[142:145], v[178:181], v[118:121]
	v_mfma_f32_16x16x32_bf16 v[106:109], v[134:137], v[174:177], v[106:109]
	v_mfma_f32_16x16x32_bf16 v[102:105], v[142:145], v[174:177], v[102:105]
	v_mfma_f32_16x16x32_bf16 v[90:93], v[134:137], v[170:173], v[90:93]
	v_mfma_f32_16x16x32_bf16 v[86:89], v[142:145], v[170:173], v[86:89]
	v_mfma_f32_16x16x32_bf16 v[74:77], v[134:137], v[166:169], v[74:77]
	v_mfma_f32_16x16x32_bf16 v[70:73], v[142:145], v[166:169], v[70:73]
	v_mfma_f32_16x16x32_bf16 v[122:125], v[138:141], v[194:197], v[122:125]
	v_mfma_f32_16x16x32_bf16 v[118:121], v[146:149], v[194:197], v[118:121]
	v_mfma_f32_16x16x32_bf16 v[106:109], v[138:141], v[190:193], v[106:109]
	v_mfma_f32_16x16x32_bf16 v[102:105], v[146:149], v[190:193], v[102:105]
	v_mfma_f32_16x16x32_bf16 v[90:93], v[138:141], v[186:189], v[90:93]
	v_mfma_f32_16x16x32_bf16 v[86:89], v[146:149], v[186:189], v[86:89]
	v_mfma_f32_16x16x32_bf16 v[74:77], v[138:141], v[182:185], v[74:77]
	v_mfma_f32_16x16x32_bf16 v[70:73], v[146:149], v[182:185], v[70:73]
	s_barrier
	s_setprio 0
	v_cmp_ne_u32_e64 s[4:5], 1, v232
	s_andn2_b64 vcc, exec, s[2:3]
	s_cbranch_vccnz .LBB0_1025
	ds_read_b128 v[178:181], v231 offset:16384
	ds_read_b128 v[194:197], v231 offset:17408
	ds_read_b128 v[174:177], v231 offset:18432
	ds_read_b128 v[190:193], v231 offset:19456
	ds_read_b128 v[170:173], v231 offset:20480
	ds_read_b128 v[186:189], v231 offset:21504
	ds_read_b128 v[166:169], v231 offset:22528
	ds_read_b128 v[182:185], v231 offset:23552
.LBB0_1025:
	s_add_u32 s46, s44, 0xfff80080
	s_addc_u32 s47, s45, -1
	s_cmp_eq_u32 s78, s77
	s_cselect_b32 s49, s9, s47
	s_cselect_b32 s48, s31, s46
	s_cselect_b32 s47, s29, s80
	s_cselect_b32 s46, s35, s79
	s_mov_b32 m0, s57
	s_add_u32 s82, s46, 0x80000
	global_load_lds_dwordx4 v202, s[46:47]
	s_mov_b32 m0, s58
	s_addc_u32 s83, s47, 0
	global_load_lds_dwordx4 v206, s[46:47]
	s_mov_b32 m0, s59
	s_nop 0
	global_load_lds_dwordx4 v202, s[82:83]
	s_mov_b32 m0, s60
	s_and_b64 vcc, exec, s[4:5]
	global_load_lds_dwordx4 v206, s[82:83]
	s_mov_b32 m0, s43
	s_nop 0
	global_load_lds_dwordx4 v200, s[48:49]
	s_mov_b32 m0, s61
	s_nop 0
	global_load_lds_dwordx4 v204, s[48:49]
	s_waitcnt vmcnt(8)
	s_waitcnt lgkmcnt(0)
	s_setprio 1
	s_barrier
	s_cbranch_vccnz .LBB0_1027
	v_mfma_f32_16x16x32_bf16 v[62:65], v[150:153], v[178:181], v[62:65]
	v_mfma_f32_16x16x32_bf16 v[54:57], v[158:161], v[178:181], v[54:57]
	v_mfma_f32_16x16x32_bf16 v[46:49], v[150:153], v[174:177], v[46:49]
	v_mfma_f32_16x16x32_bf16 v[38:41], v[158:161], v[174:177], v[38:41]
	v_mfma_f32_16x16x32_bf16 v[30:33], v[150:153], v[170:173], v[30:33]
	v_mfma_f32_16x16x32_bf16 v[22:25], v[158:161], v[170:173], v[22:25]
	v_mfma_f32_16x16x32_bf16 v[14:17], v[150:153], v[166:169], v[14:17]
	v_mfma_f32_16x16x32_bf16 v[6:9], v[158:161], v[166:169], v[6:9]
	v_mfma_f32_16x16x32_bf16 v[62:65], v[154:157], v[194:197], v[62:65]
	v_mfma_f32_16x16x32_bf16 v[54:57], v[162:165], v[194:197], v[54:57]
	v_mfma_f32_16x16x32_bf16 v[46:49], v[154:157], v[190:193], v[46:49]
	v_mfma_f32_16x16x32_bf16 v[38:41], v[162:165], v[190:193], v[38:41]
	v_mfma_f32_16x16x32_bf16 v[30:33], v[154:157], v[186:189], v[30:33]
	v_mfma_f32_16x16x32_bf16 v[22:25], v[162:165], v[186:189], v[22:25]
	v_mfma_f32_16x16x32_bf16 v[14:17], v[154:157], v[182:185], v[14:17]
	v_mfma_f32_16x16x32_bf16 v[6:9], v[162:165], v[182:185], v[6:9]
	v_mfma_f32_16x16x32_bf16 v[66:69], v[134:137], v[178:181], v[66:69]
	v_mfma_f32_16x16x32_bf16 v[58:61], v[142:145], v[178:181], v[58:61]
	v_mfma_f32_16x16x32_bf16 v[50:53], v[134:137], v[174:177], v[50:53]
	v_mfma_f32_16x16x32_bf16 v[42:45], v[142:145], v[174:177], v[42:45]
	v_mfma_f32_16x16x32_bf16 v[34:37], v[134:137], v[170:173], v[34:37]
	v_mfma_f32_16x16x32_bf16 v[26:29], v[142:145], v[170:173], v[26:29]
	v_mfma_f32_16x16x32_bf16 v[18:21], v[134:137], v[166:169], v[18:21]
	v_mfma_f32_16x16x32_bf16 v[10:13], v[142:145], v[166:169], v[10:13]
	v_mfma_f32_16x16x32_bf16 v[66:69], v[138:141], v[194:197], v[66:69]
	v_mfma_f32_16x16x32_bf16 v[58:61], v[146:149], v[194:197], v[58:61]
	v_mfma_f32_16x16x32_bf16 v[50:53], v[138:141], v[190:193], v[50:53]
	v_mfma_f32_16x16x32_bf16 v[42:45], v[146:149], v[190:193], v[42:45]
	v_mfma_f32_16x16x32_bf16 v[34:37], v[138:141], v[186:189], v[34:37]
	v_mfma_f32_16x16x32_bf16 v[26:29], v[146:149], v[186:189], v[26:29]
	v_mfma_f32_16x16x32_bf16 v[18:21], v[138:141], v[182:185], v[18:21]
	v_mfma_f32_16x16x32_bf16 v[10:13], v[146:149], v[182:185], v[10:13]
; #define PG8_STAGE(bufoff, gbase, voff) do { _Pragma("unroll") for (int _i = 0; _i < 2; ++_i) \
;         __builtin_amdgcn_global_load_lds((const unsigned*)((const char*)(gbase) + (voff)[_i]), (PG8_LAS unsigned*)(lds + (bufoff) + ldsw + _i * 8192), 16, 0, 0); } while (0)
; #define PG8_LDA(dst, b, h) do { _Pragma("unroll") for (int m = 0; m < 4; ++m) _Pragma("unroll") for (int k = 0; k < 2; ++k) dst[m][k] = *(const PG8_LAS bf16x8*)(lds + PG8_SA(b, h) + aoff + m * 2048 + k * 1024); } while (0)
; #define PG8_LDB(dst, b, h) do { _Pragma("unroll") for (int n = 0; n < 2; ++n) _Pragma("unroll") for (int k = 0; k < 2; ++k) dst[n][k] = *(const PG8_LAS bf16x8*)(lds + PG8_SB(b, h) + boff + n * 2048 + k * 1024); } while (0)
; #define PG8_MMA(ai, bj, At, Bt) do { __builtin_amdgcn_s_setprio(1); _Pragma("unroll") for (int m = 0; m < 4; ++m) _Pragma("unroll") for (int n = 0; n < 2; ++n) _Pragma("unroll") for (int k = 0; k < 2; ++k) \
;         acc[ai][bj][m][n] = __builtin_amdgcn_mfma_f32_16x16x32_bf16(Bt[n][k], At[m][k], acc[ai][bj][m][n], 0, 0, 0); __builtin_amdgcn_s_setprio(0); } while (0)
; #define PG8_WAIT_V(n) asm volatile("s_waitcnt vmcnt(" #n ")" ::: "memory")
; #define PG8_WAIT_L(n) asm volatile("s_waitcnt lgkmcnt(" #n ")" ::: "memory")
; #define PG8_BAR __builtin_amdgcn_s_barrier()
; #define PG8_SCHED __builtin_amdgcn_sched_barrier(0)
; template <class Epi, class Sched, bool ALIGN_EPI = false, bool SP2 = true>
; __device__ __forceinline__ void gemm_phase(PG8_LAS unsigned char* lds, const Gemm g, const Sched& S, const Epi& E) {
;     ...
;             PG8_LDB(B0, 1, 0); PG8_LDB(B1, 1, 1); PG8_SCHED; PG8_LDA(At, 1, 0); PG8_STAGE(PG8_SA(0, 1), a2 + hstep, voffA);
;             PG8_WAIT_V(8); PG8_WAIT_L(0); PG8_BAR; PG8_MMA(0, 0, At, B0); PG8_MMA(0, 1, At, B1); PG8_BAR; PG8_SCHED;
;             if (full) { PG8_LDA(At, 1, 1); } PG8_STAGE(PG8_SB(1, 0), b3, voffB); PG8_STAGE(PG8_SB(1, 1), b3 + hstep, voffB); PG8_STAGE(PG8_SA(1, 0), a3, voffA);
;             PG8_WAIT_V(8); PG8_WAIT_L(0); PG8_BAR; if (full) { PG8_MMA(1, 0, At, B0); PG8_MMA(1, 1, At, B1); } PG8_BAR; PG8_SCHED;
.LBB0_1027:
	s_barrier
	s_setprio 0
	v_add_u32_e32 v3, 0x18000, v199
	ds_read_b128 v[150:153], v3
	ds_read_b128 v[154:157], v3 offset:1024
	ds_read_b128 v[158:161], v3 offset:2048
	ds_read_b128 v[162:165], v3 offset:3072
	v_add_u32_e32 v3, 0x1c000, v199
	ds_read_b128 v[134:137], v3
	ds_read_b128 v[138:141], v3 offset:1024
	ds_read_b128 v[142:145], v3 offset:2048
	ds_read_b128 v[146:149], v3 offset:3072
	s_add_u32 s48, s48, 0x80000
	s_addc_u32 s49, s49, 0
	s_mov_b32 m0, s62
	s_waitcnt lgkmcnt(0)
	ds_read_b128 v[178:181], v231 offset:32768
	ds_read_b128 v[194:197], v231 offset:33792
	ds_read_b128 v[174:177], v231 offset:34816
	ds_read_b128 v[190:193], v231 offset:35840
	ds_read_b128 v[170:173], v231 offset:36864
	ds_read_b128 v[186:189], v231 offset:37888
	ds_read_b128 v[166:169], v231 offset:38912
	ds_read_b128 v[182:185], v231 offset:39936
	global_load_lds_dwordx4 v200, s[48:49]
	s_mov_b32 m0, s63
	s_nop 0
	global_load_lds_dwordx4 v204, s[48:49]
	s_waitcnt vmcnt(8)
	s_waitcnt lgkmcnt(0)
	s_setprio 1
	s_barrier
	v_mfma_f32_16x16x32_bf16 v[130:133], v[150:153], v[178:181], v[130:133]
	v_mfma_f32_16x16x32_bf16 v[126:129], v[158:161], v[178:181], v[126:129]
	v_mfma_f32_16x16x32_bf16 v[114:117], v[150:153], v[174:177], v[114:117]
	v_mfma_f32_16x16x32_bf16 v[110:113], v[158:161], v[174:177], v[110:113]
	v_mfma_f32_16x16x32_bf16 v[98:101], v[150:153], v[170:173], v[98:101]
	v_mfma_f32_16x16x32_bf16 v[94:97], v[158:161], v[170:173], v[94:97]
	v_mfma_f32_16x16x32_bf16 v[82:85], v[150:153], v[166:169], v[82:85]
	v_mfma_f32_16x16x32_bf16 v[78:81], v[158:161], v[166:169], v[78:81]
	v_mfma_f32_16x16x32_bf16 v[130:133], v[154:157], v[194:197], v[130:133]
	v_mfma_f32_16x16x32_bf16 v[126:129], v[162:165], v[194:197], v[126:129]
	v_mfma_f32_16x16x32_bf16 v[114:117], v[154:157], v[190:193], v[114:117]
	v_mfma_f32_16x16x32_bf16 v[110:113], v[162:165], v[190:193], v[110:113]
	v_mfma_f32_16x16x32_bf16 v[98:101], v[154:157], v[186:189], v[98:101]
	v_mfma_f32_16x16x32_bf16 v[94:97], v[162:165], v[186:189], v[94:97]
	v_mfma_f32_16x16x32_bf16 v[82:85], v[154:157], v[182:185], v[82:85]
	v_mfma_f32_16x16x32_bf16 v[78:81], v[162:165], v[182:185], v[78:81]
	v_mfma_f32_16x16x32_bf16 v[122:125], v[134:137], v[178:181], v[122:125]
	v_mfma_f32_16x16x32_bf16 v[118:121], v[142:145], v[178:181], v[118:121]
	v_mfma_f32_16x16x32_bf16 v[106:109], v[134:137], v[174:177], v[106:109]
	v_mfma_f32_16x16x32_bf16 v[102:105], v[142:145], v[174:177], v[102:105]
	v_mfma_f32_16x16x32_bf16 v[90:93], v[134:137], v[170:173], v[90:93]
	v_mfma_f32_16x16x32_bf16 v[86:89], v[142:145], v[170:173], v[86:89]
	v_mfma_f32_16x16x32_bf16 v[74:77], v[134:137], v[166:169], v[74:77]
	v_mfma_f32_16x16x32_bf16 v[70:73], v[142:145], v[166:169], v[70:73]
	v_mfma_f32_16x16x32_bf16 v[122:125], v[138:141], v[194:197], v[122:125]
	v_mfma_f32_16x16x32_bf16 v[118:121], v[146:149], v[194:197], v[118:121]
	v_mfma_f32_16x16x32_bf16 v[106:109], v[138:141], v[190:193], v[106:109]
	v_mfma_f32_16x16x32_bf16 v[102:105], v[146:149], v[190:193], v[102:105]
	v_mfma_f32_16x16x32_bf16 v[90:93], v[138:141], v[186:189], v[90:93]
	v_mfma_f32_16x16x32_bf16 v[86:89], v[146:149], v[186:189], v[86:89]
	v_mfma_f32_16x16x32_bf16 v[74:77], v[138:141], v[182:185], v[74:77]
	v_mfma_f32_16x16x32_bf16 v[70:73], v[146:149], v[182:185], v[70:73]
	s_barrier
	s_setprio 0
	s_and_b64 vcc, exec, s[4:5]
	s_cbranch_vccnz .LBB0_1029
	ds_read_b128 v[178:181], v231 offset:49152
	ds_read_b128 v[194:197], v231 offset:50176
	ds_read_b128 v[174:177], v231 offset:51200
	ds_read_b128 v[190:193], v231 offset:52224
	ds_read_b128 v[170:173], v231 offset:53248
	ds_read_b128 v[186:189], v231 offset:54272
	ds_read_b128 v[166:169], v231 offset:55296
	ds_read_b128 v[182:185], v231 offset:56320
.LBB0_1029:
	s_mov_b32 m0, s66
	s_add_u32 s98, s46, 0x80
	s_addc_u32 s99, s47, 0
	s_add_u32 s46, s46, 0x80080
	global_load_lds_dwordx4 v202, s[98:99]
	s_mov_b32 m0, s67
	s_addc_u32 s47, s47, 0
	global_load_lds_dwordx4 v206, s[98:99]
	s_mov_b32 m0, s70
	s_and_b64 vcc, exec, s[4:5]
	global_load_lds_dwordx4 v202, s[46:47]
	s_mov_b32 m0, s71
	s_nop 0
	global_load_lds_dwordx4 v206, s[46:47]
	s_mov_b32 m0, s68
	s_nop 0
	s_add_u32 s100, s48, 0xfff80080
	s_addc_u32 s101, s49, -1
	global_load_lds_dwordx4 v200, s[100:101]
	s_mov_b32 m0, s69
	s_nop 0
	global_load_lds_dwordx4 v204, s[100:101]
	s_waitcnt vmcnt(8)
	s_waitcnt lgkmcnt(0)
	s_setprio 1
	s_barrier
	s_cbranch_vccnz .LBB0_1022
	v_mfma_f32_16x16x32_bf16 v[62:65], v[150:153], v[178:181], v[62:65]
	v_mfma_f32_16x16x32_bf16 v[54:57], v[158:161], v[178:181], v[54:57]
	v_mfma_f32_16x16x32_bf16 v[46:49], v[150:153], v[174:177], v[46:49]
	v_mfma_f32_16x16x32_bf16 v[38:41], v[158:161], v[174:177], v[38:41]
	v_mfma_f32_16x16x32_bf16 v[30:33], v[150:153], v[170:173], v[30:33]
	v_mfma_f32_16x16x32_bf16 v[22:25], v[158:161], v[170:173], v[22:25]
	v_mfma_f32_16x16x32_bf16 v[14:17], v[150:153], v[166:169], v[14:17]
	v_mfma_f32_16x16x32_bf16 v[4:7], v[158:161], v[166:169], v[6:9]
	v_mfma_f32_16x16x32_bf16 v[62:65], v[154:157], v[194:197], v[62:65]
	v_mfma_f32_16x16x32_bf16 v[54:57], v[162:165], v[194:197], v[54:57]
	v_mfma_f32_16x16x32_bf16 v[46:49], v[154:157], v[190:193], v[46:49]
	v_mfma_f32_16x16x32_bf16 v[38:41], v[162:165], v[190:193], v[38:41]
	v_mfma_f32_16x16x32_bf16 v[30:33], v[154:157], v[186:189], v[30:33]
	v_mfma_f32_16x16x32_bf16 v[22:25], v[162:165], v[186:189], v[22:25]
	v_mfma_f32_16x16x32_bf16 v[14:17], v[154:157], v[182:185], v[14:17]
	v_mfma_f32_16x16x32_bf16 v[6:9], v[162:165], v[182:185], v[4:7]
	v_mfma_f32_16x16x32_bf16 v[66:69], v[134:137], v[178:181], v[66:69]
	v_mfma_f32_16x16x32_bf16 v[58:61], v[142:145], v[178:181], v[58:61]
	v_mfma_f32_16x16x32_bf16 v[50:53], v[134:137], v[174:177], v[50:53]
	v_mfma_f32_16x16x32_bf16 v[42:45], v[142:145], v[174:177], v[42:45]
	v_mfma_f32_16x16x32_bf16 v[34:37], v[134:137], v[170:173], v[34:37]
	v_mfma_f32_16x16x32_bf16 v[26:29], v[142:145], v[170:173], v[26:29]
	v_mfma_f32_16x16x32_bf16 v[18:21], v[134:137], v[166:169], v[18:21]
	v_mfma_f32_16x16x32_bf16 v[10:13], v[142:145], v[166:169], v[10:13]
	v_mfma_f32_16x16x32_bf16 v[66:69], v[138:141], v[194:197], v[66:69]
	v_mfma_f32_16x16x32_bf16 v[58:61], v[146:149], v[194:197], v[58:61]
	v_mfma_f32_16x16x32_bf16 v[50:53], v[138:141], v[190:193], v[50:53]
	v_mfma_f32_16x16x32_bf16 v[42:45], v[146:149], v[190:193], v[42:45]
	v_mfma_f32_16x16x32_bf16 v[34:37], v[138:141], v[186:189], v[34:37]
	v_mfma_f32_16x16x32_bf16 v[26:29], v[146:149], v[186:189], v[26:29]
	v_mfma_f32_16x16x32_bf16 v[18:21], v[138:141], v[182:185], v[18:21]
	v_mfma_f32_16x16x32_bf16 v[10:13], v[146:149], v[182:185], v[10:13]
	s_branch .LBB0_1022

; #define PG8_STAGE(bufoff, gbase, voff) do { _Pragma("unroll") for (int _i = 0; _i < 2; ++_i) \
;         __builtin_amdgcn_global_load_lds((const unsigned*)((const char*)(gbase) + (voff)[_i]), (PG8_LAS unsigned*)(lds + (bufoff) + ldsw + _i * 8192), 16, 0, 0); } while (0)
; #define PG8_LDA(dst, b, h) do { _Pragma("unroll") for (int m = 0; m < 4; ++m) _Pragma("unroll") for (int k = 0; k < 2; ++k) dst[m][k] = *(const PG8_LAS bf16x8*)(lds + PG8_SA(b, h) + aoff + m * 2048 + k * 1024); } while (0)
; #define PG8_LDB(dst, b, h) do { _Pragma("unroll") for (int n = 0; n < 2; ++n) _Pragma("unroll") for (int k = 0; k < 2; ++k) dst[n][k] = *(const PG8_LAS bf16x8*)(lds + PG8_SB(b, h) + boff + n * 2048 + k * 1024); } while (0)
; #define PG8_MMA(ai, bj, At, Bt) do { __builtin_amdgcn_s_setprio(1); _Pragma("unroll") for (int m = 0; m < 4; ++m) _Pragma("unroll") for (int n = 0; n < 2; ++n) _Pragma("unroll") for (int k = 0; k < 2; ++k) \
;         acc[ai][bj][m][n] = __builtin_amdgcn_mfma_f32_16x16x32_bf16(Bt[n][k], At[m][k], acc[ai][bj][m][n], 0, 0, 0); __builtin_amdgcn_s_setprio(0); } while (0)
; #define PG8_WAIT_V(n) asm volatile("s_waitcnt vmcnt(" #n ")" ::: "memory")
; #define PG8_WAIT_L(n) asm volatile("s_waitcnt lgkmcnt(" #n ")" ::: "memory")
; #define PG8_BAR __builtin_amdgcn_s_barrier()
; #define PG8_SCHED __builtin_amdgcn_sched_barrier(0)
; template <class Epi, class Sched, bool ALIGN_EPI = false, bool SP2 = true>
; __device__ __forceinline__ void gemm_phase(PG8_LAS unsigned char* lds, const Gemm g, const Sched& S, const Epi& E) {
;     ...
;             PG8_LDB(B0, 0, 0); PG8_LDB(B1, 0, 1); PG8_SCHED; PG8_LDA(At, 0, 0); PG8_STAGE(PG8_SA(1, 1), a1 + hstep, voffA);
;             PG8_WAIT_V(8); PG8_WAIT_L(0); PG8_BAR; PG8_MMA(0, 0, At, B0); PG8_MMA(0, 1, At, B1); PG8_BAR; PG8_SCHED;
;             if (full) { PG8_LDA(At, 0, 1); } PG8_STAGE(PG8_SB(0, 0), b2, voffB); PG8_STAGE(PG8_SB(0, 1), b2 + hstep, voffB); PG8_STAGE(PG8_SA(0, 0), a2, voffA);
;             PG8_WAIT_V(8); PG8_WAIT_L(0); PG8_BAR; if (full) { PG8_MMA(1, 0, At, B0); PG8_MMA(1, 1, At, B1); } PG8_BAR; PG8_SCHED;
.LBB0_1161:
	ds_read_b128 v[150:153], v209
	ds_read_b128 v[154:157], v209 offset:1024
	ds_read_b128 v[158:161], v209 offset:2048
	ds_read_b128 v[162:165], v209 offset:3072
	ds_read_b128 v[134:137], v224
	ds_read_b128 v[138:141], v224 offset:1024
	ds_read_b128 v[142:145], v224 offset:2048
	ds_read_b128 v[146:149], v224 offset:3072
	s_add_i32 m0, s37, 0xc000
	s_waitcnt lgkmcnt(0)
	ds_read_b128 v[178:181], v225
	ds_read_b128 v[194:197], v225 offset:1024
	ds_read_b128 v[174:177], v225 offset:2048
	ds_read_b128 v[190:193], v225 offset:3072
	ds_read_b128 v[170:173], v225 offset:4096
	ds_read_b128 v[186:189], v225 offset:5120
	ds_read_b128 v[166:169], v225 offset:6144
	ds_read_b128 v[182:185], v225 offset:7168
	global_load_lds_dwordx4 v212, s[40:41]
	s_add_i32 m0, s37, 0xe000
	s_nop 0
	global_load_lds_dwordx4 v214, s[40:41]
	s_waitcnt vmcnt(8)
	s_waitcnt lgkmcnt(0)
	s_setprio 1
	s_barrier
	v_mfma_f32_16x16x32_bf16 v[130:133], v[150:153], v[178:181], v[130:133]
	v_mfma_f32_16x16x32_bf16 v[126:129], v[158:161], v[178:181], v[126:129]
	v_mfma_f32_16x16x32_bf16 v[114:117], v[150:153], v[174:177], v[114:117]
	v_mfma_f32_16x16x32_bf16 v[110:113], v[158:161], v[174:177], v[110:113]
	v_mfma_f32_16x16x32_bf16 v[98:101], v[150:153], v[170:173], v[98:101]
	v_mfma_f32_16x16x32_bf16 v[94:97], v[158:161], v[170:173], v[94:97]
	v_mfma_f32_16x16x32_bf16 v[82:85], v[150:153], v[166:169], v[82:85]
	v_mfma_f32_16x16x32_bf16 v[78:81], v[158:161], v[166:169], v[78:81]
	v_mfma_f32_16x16x32_bf16 v[130:133], v[154:157], v[194:197], v[130:133]
	v_mfma_f32_16x16x32_bf16 v[126:129], v[162:165], v[194:197], v[126:129]
	v_mfma_f32_16x16x32_bf16 v[114:117], v[154:157], v[190:193], v[114:117]
	v_mfma_f32_16x16x32_bf16 v[110:113], v[162:165], v[190:193], v[110:113]
	v_mfma_f32_16x16x32_bf16 v[98:101], v[154:157], v[186:189], v[98:101]
	v_mfma_f32_16x16x32_bf16 v[94:97], v[162:165], v[186:189], v[94:97]
	v_mfma_f32_16x16x32_bf16 v[82:85], v[154:157], v[182:185], v[82:85]
	v_mfma_f32_16x16x32_bf16 v[78:81], v[162:165], v[182:185], v[78:81]
	v_mfma_f32_16x16x32_bf16 v[122:125], v[134:137], v[178:181], v[122:125]
	v_mfma_f32_16x16x32_bf16 v[118:121], v[142:145], v[178:181], v[118:121]
	v_mfma_f32_16x16x32_bf16 v[106:109], v[134:137], v[174:177], v[106:109]
	v_mfma_f32_16x16x32_bf16 v[102:105], v[142:145], v[174:177], v[102:105]
	v_mfma_f32_16x16x32_bf16 v[90:93], v[134:137], v[170:173], v[90:93]
	v_mfma_f32_16x16x32_bf16 v[86:89], v[142:145], v[170:173], v[86:89]
	v_mfma_f32_16x16x32_bf16 v[74:77], v[134:137], v[166:169], v[74:77]
	v_mfma_f32_16x16x32_bf16 v[70:73], v[142:145], v[166:169], v[70:73]
	v_mfma_f32_16x16x32_bf16 v[122:125], v[138:141], v[194:197], v[122:125]
	v_mfma_f32_16x16x32_bf16 v[118:121], v[146:149], v[194:197], v[118:121]
	v_mfma_f32_16x16x32_bf16 v[106:109], v[138:141], v[190:193], v[106:109]
	v_mfma_f32_16x16x32_bf16 v[102:105], v[146:149], v[190:193], v[102:105]
	v_mfma_f32_16x16x32_bf16 v[90:93], v[138:141], v[186:189], v[90:93]
	v_mfma_f32_16x16x32_bf16 v[86:89], v[146:149], v[186:189], v[86:89]
	v_mfma_f32_16x16x32_bf16 v[74:77], v[138:141], v[182:185], v[74:77]
	v_mfma_f32_16x16x32_bf16 v[70:73], v[146:149], v[182:185], v[70:73]
	s_barrier
	s_setprio 0
	v_cmp_ne_u32_e64 s[8:9], 1, v226
	s_andn2_b64 vcc, exec, s[2:3]
	s_cbranch_vccnz .LBB0_1163
	ds_read_b128 v[178:181], v225 offset:16384
	ds_read_b128 v[194:197], v225 offset:17408
	ds_read_b128 v[174:177], v225 offset:18432
	ds_read_b128 v[190:193], v225 offset:19456
	ds_read_b128 v[170:173], v225 offset:20480
	ds_read_b128 v[186:189], v225 offset:21504
	ds_read_b128 v[166:169], v225 offset:22528
	ds_read_b128 v[182:185], v225 offset:23552
.LBB0_1163:
	s_add_u32 s42, s40, 0xfff00080
	s_addc_u32 s43, s41, -1
	s_cmp_eq_u32 s25, s72
	s_cselect_b32 s45, s31, s43
	s_cselect_b32 s44, s30, s42
	s_cselect_b32 s43, s35, s29
	s_cselect_b32 s42, s34, s27
	s_mov_b32 m0, s39
	s_add_u32 s74, s42, 0x100000
	global_load_lds_dwordx4 v202, s[42:43]
	s_mov_b32 m0, s51
	s_addc_u32 s75, s43, 0
	global_load_lds_dwordx4 v206, s[42:43]
	s_mov_b32 m0, s52
	s_nop 0
	global_load_lds_dwordx4 v202, s[74:75]
	s_mov_b32 m0, s53
	s_and_b64 vcc, exec, s[8:9]
	global_load_lds_dwordx4 v206, s[74:75]
	s_mov_b32 m0, s37
	s_nop 0
	global_load_lds_dwordx4 v200, s[44:45]
	s_mov_b32 m0, s54
	s_nop 0
	global_load_lds_dwordx4 v204, s[44:45]
	s_waitcnt vmcnt(8)
	s_waitcnt lgkmcnt(0)
	s_setprio 1
	s_barrier
	s_cbranch_vccnz .LBB0_1165
	v_mfma_f32_16x16x32_bf16 v[66:69], v[150:153], v[178:181], v[66:69]
	v_mfma_f32_16x16x32_bf16 v[62:65], v[158:161], v[178:181], v[62:65]
	v_mfma_f32_16x16x32_bf16 v[50:53], v[150:153], v[174:177], v[50:53]
	v_mfma_f32_16x16x32_bf16 v[46:49], v[158:161], v[174:177], v[46:49]
	v_mfma_f32_16x16x32_bf16 v[34:37], v[150:153], v[170:173], v[34:37]
	v_mfma_f32_16x16x32_bf16 v[30:33], v[158:161], v[170:173], v[30:33]
	v_mfma_f32_16x16x32_bf16 v[18:21], v[150:153], v[166:169], v[18:21]
	v_mfma_f32_16x16x32_bf16 v[14:17], v[158:161], v[166:169], v[14:17]
	v_mfma_f32_16x16x32_bf16 v[66:69], v[154:157], v[194:197], v[66:69]
	v_mfma_f32_16x16x32_bf16 v[62:65], v[162:165], v[194:197], v[62:65]
	v_mfma_f32_16x16x32_bf16 v[50:53], v[154:157], v[190:193], v[50:53]
	v_mfma_f32_16x16x32_bf16 v[46:49], v[162:165], v[190:193], v[46:49]
	v_mfma_f32_16x16x32_bf16 v[34:37], v[154:157], v[186:189], v[34:37]
	v_mfma_f32_16x16x32_bf16 v[30:33], v[162:165], v[186:189], v[30:33]
	v_mfma_f32_16x16x32_bf16 v[18:21], v[154:157], v[182:185], v[18:21]
	v_mfma_f32_16x16x32_bf16 v[14:17], v[162:165], v[182:185], v[14:17]
	v_mfma_f32_16x16x32_bf16 v[58:61], v[134:137], v[178:181], v[58:61]
	v_mfma_f32_16x16x32_bf16 v[54:57], v[142:145], v[178:181], v[54:57]
	v_mfma_f32_16x16x32_bf16 v[42:45], v[134:137], v[174:177], v[42:45]
	v_mfma_f32_16x16x32_bf16 v[38:41], v[142:145], v[174:177], v[38:41]
	v_mfma_f32_16x16x32_bf16 v[26:29], v[134:137], v[170:173], v[26:29]
	v_mfma_f32_16x16x32_bf16 v[22:25], v[142:145], v[170:173], v[22:25]
	v_mfma_f32_16x16x32_bf16 v[10:13], v[134:137], v[166:169], v[10:13]
	v_mfma_f32_16x16x32_bf16 v[6:9], v[142:145], v[166:169], v[6:9]
	v_mfma_f32_16x16x32_bf16 v[58:61], v[138:141], v[194:197], v[58:61]
	v_mfma_f32_16x16x32_bf16 v[54:57], v[146:149], v[194:197], v[54:57]
	v_mfma_f32_16x16x32_bf16 v[42:45], v[138:141], v[190:193], v[42:45]
	v_mfma_f32_16x16x32_bf16 v[38:41], v[146:149], v[190:193], v[38:41]
	v_mfma_f32_16x16x32_bf16 v[26:29], v[138:141], v[186:189], v[26:29]
	v_mfma_f32_16x16x32_bf16 v[22:25], v[146:149], v[186:189], v[22:25]
	v_mfma_f32_16x16x32_bf16 v[10:13], v[138:141], v[182:185], v[10:13]
	v_mfma_f32_16x16x32_bf16 v[6:9], v[146:149], v[182:185], v[6:9]
; #define PG8_STAGE(bufoff, gbase, voff) do { _Pragma("unroll") for (int _i = 0; _i < 2; ++_i) \
;         __builtin_amdgcn_global_load_lds((const unsigned*)((const char*)(gbase) + (voff)[_i]), (PG8_LAS unsigned*)(lds + (bufoff) + ldsw + _i * 8192), 16, 0, 0); } while (0)
; #define PG8_LDA(dst, b, h) do { _Pragma("unroll") for (int m = 0; m < 4; ++m) _Pragma("unroll") for (int k = 0; k < 2; ++k) dst[m][k] = *(const PG8_LAS bf16x8*)(lds + PG8_SA(b, h) + aoff + m * 2048 + k * 1024); } while (0)
; #define PG8_LDB(dst, b, h) do { _Pragma("unroll") for (int n = 0; n < 2; ++n) _Pragma("unroll") for (int k = 0; k < 2; ++k) dst[n][k] = *(const PG8_LAS bf16x8*)(lds + PG8_SB(b, h) + boff + n * 2048 + k * 1024); } while (0)
; #define PG8_MMA(ai, bj, At, Bt) do { __builtin_amdgcn_s_setprio(1); _Pragma("unroll") for (int m = 0; m < 4; ++m) _Pragma("unroll") for (int n = 0; n < 2; ++n) _Pragma("unroll") for (int k = 0; k < 2; ++k) \
;         acc[ai][bj][m][n] = __builtin_amdgcn_mfma_f32_16x16x32_bf16(Bt[n][k], At[m][k], acc[ai][bj][m][n], 0, 0, 0); __builtin_amdgcn_s_setprio(0); } while (0)
; #define PG8_WAIT_V(n) asm volatile("s_waitcnt vmcnt(" #n ")" ::: "memory")
; #define PG8_WAIT_L(n) asm volatile("s_waitcnt lgkmcnt(" #n ")" ::: "memory")
; #define PG8_BAR __builtin_amdgcn_s_barrier()
; #define PG8_SCHED __builtin_amdgcn_sched_barrier(0)
; template <class Epi, class Sched, bool ALIGN_EPI = false, bool SP2 = true>
; __device__ __forceinline__ void gemm_phase(PG8_LAS unsigned char* lds, const Gemm g, const Sched& S, const Epi& E) {
;     ...
;             PG8_LDB(B0, 1, 0); PG8_LDB(B1, 1, 1); PG8_SCHED; PG8_LDA(At, 1, 0); PG8_STAGE(PG8_SA(0, 1), a2 + hstep, voffA);
;             PG8_WAIT_V(8); PG8_WAIT_L(0); PG8_BAR; PG8_MMA(0, 0, At, B0); PG8_MMA(0, 1, At, B1); PG8_BAR; PG8_SCHED;
;             if (full) { PG8_LDA(At, 1, 1); } PG8_STAGE(PG8_SB(1, 0), b3, voffB); PG8_STAGE(PG8_SB(1, 1), b3 + hstep, voffB); PG8_STAGE(PG8_SA(1, 0), a3, voffA);
;             PG8_WAIT_V(8); PG8_WAIT_L(0); PG8_BAR; if (full) { PG8_MMA(1, 0, At, B0); PG8_MMA(1, 1, At, B1); } PG8_BAR; PG8_SCHED;
.LBB0_1165:
	s_barrier
	s_setprio 0
	v_add_u32_e32 v3, 0x18000, v199
	ds_read_b128 v[150:153], v3
	ds_read_b128 v[154:157], v3 offset:1024
	ds_read_b128 v[158:161], v3 offset:2048
	ds_read_b128 v[162:165], v3 offset:3072
	v_add_u32_e32 v3, 0x1c000, v199
	ds_read_b128 v[134:137], v3
	ds_read_b128 v[138:141], v3 offset:1024
	ds_read_b128 v[142:145], v3 offset:2048
	ds_read_b128 v[146:149], v3 offset:3072
	s_add_u32 s44, s44, 0x100000
	s_addc_u32 s45, s45, 0
	s_mov_b32 m0, s55
	s_waitcnt lgkmcnt(0)
	ds_read_b128 v[178:181], v225 offset:32768
	ds_read_b128 v[194:197], v225 offset:33792
	ds_read_b128 v[174:177], v225 offset:34816
	ds_read_b128 v[190:193], v225 offset:35840
	ds_read_b128 v[170:173], v225 offset:36864
	ds_read_b128 v[186:189], v225 offset:37888
	ds_read_b128 v[166:169], v225 offset:38912
	ds_read_b128 v[182:185], v225 offset:39936
	global_load_lds_dwordx4 v200, s[44:45]
	s_mov_b32 m0, s56
	s_nop 0
	global_load_lds_dwordx4 v204, s[44:45]
	s_waitcnt vmcnt(8)
	s_waitcnt lgkmcnt(0)
	s_setprio 1
	s_barrier
	v_mfma_f32_16x16x32_bf16 v[130:133], v[150:153], v[178:181], v[130:133]
	v_mfma_f32_16x16x32_bf16 v[126:129], v[158:161], v[178:181], v[126:129]
	v_mfma_f32_16x16x32_bf16 v[114:117], v[150:153], v[174:177], v[114:117]
	v_mfma_f32_16x16x32_bf16 v[110:113], v[158:161], v[174:177], v[110:113]
	v_mfma_f32_16x16x32_bf16 v[98:101], v[150:153], v[170:173], v[98:101]
	v_mfma_f32_16x16x32_bf16 v[94:97], v[158:161], v[170:173], v[94:97]
	v_mfma_f32_16x16x32_bf16 v[82:85], v[150:153], v[166:169], v[82:85]
	v_mfma_f32_16x16x32_bf16 v[78:81], v[158:161], v[166:169], v[78:81]
	v_mfma_f32_16x16x32_bf16 v[130:133], v[154:157], v[194:197], v[130:133]
	v_mfma_f32_16x16x32_bf16 v[126:129], v[162:165], v[194:197], v[126:129]
	v_mfma_f32_16x16x32_bf16 v[114:117], v[154:157], v[190:193], v[114:117]
	v_mfma_f32_16x16x32_bf16 v[110:113], v[162:165], v[190:193], v[110:113]
	v_mfma_f32_16x16x32_bf16 v[98:101], v[154:157], v[186:189], v[98:101]
	v_mfma_f32_16x16x32_bf16 v[94:97], v[162:165], v[186:189], v[94:97]
	v_mfma_f32_16x16x32_bf16 v[82:85], v[154:157], v[182:185], v[82:85]
	v_mfma_f32_16x16x32_bf16 v[78:81], v[162:165], v[182:185], v[78:81]
	v_mfma_f32_16x16x32_bf16 v[122:125], v[134:137], v[178:181], v[122:125]
	v_mfma_f32_16x16x32_bf16 v[118:121], v[142:145], v[178:181], v[118:121]
	v_mfma_f32_16x16x32_bf16 v[106:109], v[134:137], v[174:177], v[106:109]
	v_mfma_f32_16x16x32_bf16 v[102:105], v[142:145], v[174:177], v[102:105]
	v_mfma_f32_16x16x32_bf16 v[90:93], v[134:137], v[170:173], v[90:93]
	v_mfma_f32_16x16x32_bf16 v[86:89], v[142:145], v[170:173], v[86:89]
	v_mfma_f32_16x16x32_bf16 v[74:77], v[134:137], v[166:169], v[74:77]
	v_mfma_f32_16x16x32_bf16 v[70:73], v[142:145], v[166:169], v[70:73]
	v_mfma_f32_16x16x32_bf16 v[122:125], v[138:141], v[194:197], v[122:125]
	v_mfma_f32_16x16x32_bf16 v[118:121], v[146:149], v[194:197], v[118:121]
	v_mfma_f32_16x16x32_bf16 v[106:109], v[138:141], v[190:193], v[106:109]
	v_mfma_f32_16x16x32_bf16 v[102:105], v[146:149], v[190:193], v[102:105]
	v_mfma_f32_16x16x32_bf16 v[90:93], v[138:141], v[186:189], v[90:93]
	v_mfma_f32_16x16x32_bf16 v[86:89], v[146:149], v[186:189], v[86:89]
	v_mfma_f32_16x16x32_bf16 v[74:77], v[138:141], v[182:185], v[74:77]
	v_mfma_f32_16x16x32_bf16 v[70:73], v[146:149], v[182:185], v[70:73]
	s_barrier
	s_setprio 0
	s_and_b64 vcc, exec, s[8:9]
	s_cbranch_vccnz .LBB0_1167
	ds_read_b128 v[178:181], v225 offset:49152
	ds_read_b128 v[194:197], v225 offset:50176
	ds_read_b128 v[174:177], v225 offset:51200
	ds_read_b128 v[190:193], v225 offset:52224
	ds_read_b128 v[170:173], v225 offset:53248
	ds_read_b128 v[186:189], v225 offset:54272
	ds_read_b128 v[166:169], v225 offset:55296
	ds_read_b128 v[182:185], v225 offset:56320
.LBB0_1167:
	s_mov_b32 m0, s59
	s_add_u32 s98, s42, 0x80
	s_addc_u32 s99, s43, 0
	s_add_u32 s42, s42, 0x100080
	global_load_lds_dwordx4 v202, s[98:99]
	s_mov_b32 m0, s60
	s_addc_u32 s43, s43, 0
	global_load_lds_dwordx4 v206, s[98:99]
	s_mov_b32 m0, s63
	s_and_b64 vcc, exec, s[8:9]
	global_load_lds_dwordx4 v202, s[42:43]
	s_mov_b32 m0, s64
	s_nop 0
	global_load_lds_dwordx4 v206, s[42:43]
	s_mov_b32 m0, s61
	s_nop 0
	s_add_u32 s100, s44, 0xfff00080
	s_addc_u32 s101, s45, -1
	global_load_lds_dwordx4 v200, s[100:101]
	s_mov_b32 m0, s62
	s_nop 0
	global_load_lds_dwordx4 v204, s[100:101]
	s_waitcnt vmcnt(8)
	s_waitcnt lgkmcnt(0)
	s_setprio 1
	s_barrier
	s_cbranch_vccnz .LBB0_1160
	v_mfma_f32_16x16x32_bf16 v[66:69], v[150:153], v[178:181], v[66:69]
	v_mfma_f32_16x16x32_bf16 v[62:65], v[158:161], v[178:181], v[62:65]
	v_mfma_f32_16x16x32_bf16 v[50:53], v[150:153], v[174:177], v[50:53]
	v_mfma_f32_16x16x32_bf16 v[46:49], v[158:161], v[174:177], v[46:49]
	v_mfma_f32_16x16x32_bf16 v[34:37], v[150:153], v[170:173], v[34:37]
	v_mfma_f32_16x16x32_bf16 v[30:33], v[158:161], v[170:173], v[30:33]
	v_mfma_f32_16x16x32_bf16 v[18:21], v[150:153], v[166:169], v[18:21]
	v_mfma_f32_16x16x32_bf16 v[14:17], v[158:161], v[166:169], v[14:17]
	v_mfma_f32_16x16x32_bf16 v[66:69], v[154:157], v[194:197], v[66:69]
	v_mfma_f32_16x16x32_bf16 v[62:65], v[162:165], v[194:197], v[62:65]
	v_mfma_f32_16x16x32_bf16 v[50:53], v[154:157], v[190:193], v[50:53]
	v_mfma_f32_16x16x32_bf16 v[46:49], v[162:165], v[190:193], v[46:49]
	v_mfma_f32_16x16x32_bf16 v[34:37], v[154:157], v[186:189], v[34:37]
	v_mfma_f32_16x16x32_bf16 v[30:33], v[162:165], v[186:189], v[30:33]
	v_mfma_f32_16x16x32_bf16 v[18:21], v[154:157], v[182:185], v[18:21]
	v_mfma_f32_16x16x32_bf16 v[14:17], v[162:165], v[182:185], v[14:17]
	v_mfma_f32_16x16x32_bf16 v[58:61], v[134:137], v[178:181], v[58:61]
	v_mfma_f32_16x16x32_bf16 v[54:57], v[142:145], v[178:181], v[54:57]
	v_mfma_f32_16x16x32_bf16 v[42:45], v[134:137], v[174:177], v[42:45]
	v_mfma_f32_16x16x32_bf16 v[38:41], v[142:145], v[174:177], v[38:41]
	v_mfma_f32_16x16x32_bf16 v[26:29], v[134:137], v[170:173], v[26:29]
	v_mfma_f32_16x16x32_bf16 v[22:25], v[142:145], v[170:173], v[22:25]
	v_mfma_f32_16x16x32_bf16 v[10:13], v[134:137], v[166:169], v[10:13]
	v_mfma_f32_16x16x32_bf16 v[4:7], v[142:145], v[166:169], v[6:9]
	v_mfma_f32_16x16x32_bf16 v[58:61], v[138:141], v[194:197], v[58:61]
	v_mfma_f32_16x16x32_bf16 v[54:57], v[146:149], v[194:197], v[54:57]
	v_mfma_f32_16x16x32_bf16 v[42:45], v[138:141], v[190:193], v[42:45]
	v_mfma_f32_16x16x32_bf16 v[38:41], v[146:149], v[190:193], v[38:41]
	v_mfma_f32_16x16x32_bf16 v[26:29], v[138:141], v[186:189], v[26:29]
	v_mfma_f32_16x16x32_bf16 v[22:25], v[146:149], v[186:189], v[22:25]
	v_mfma_f32_16x16x32_bf16 v[10:13], v[138:141], v[182:185], v[10:13]
	v_mfma_f32_16x16x32_bf16 v[6:9], v[146:149], v[182:185], v[4:7]
	s_branch .LBB0_1160

; #define PG8_STAGE(bufoff, gbase, voff) do { _Pragma("unroll") for (int _i = 0; _i < 2; ++_i) \
;         __builtin_amdgcn_global_load_lds((const unsigned*)((const char*)(gbase) + (voff)[_i]), (PG8_LAS unsigned*)(lds + (bufoff) + ldsw + _i * 8192), 16, 0, 0); } while (0)
; #define PG8_LDA(dst, b, h) do { _Pragma("unroll") for (int m = 0; m < 4; ++m) _Pragma("unroll") for (int k = 0; k < 2; ++k) dst[m][k] = *(const PG8_LAS bf16x8*)(lds + PG8_SA(b, h) + aoff + m * 2048 + k * 1024); } while (0)
; #define PG8_LDB(dst, b, h) do { _Pragma("unroll") for (int n = 0; n < 2; ++n) _Pragma("unroll") for (int k = 0; k < 2; ++k) dst[n][k] = *(const PG8_LAS bf16x8*)(lds + PG8_SB(b, h) + boff + n * 2048 + k * 1024); } while (0)
; #define PG8_MMA(ai, bj, At, Bt) do { __builtin_amdgcn_s_setprio(1); _Pragma("unroll") for (int m = 0; m < 4; ++m) _Pragma("unroll") for (int n = 0; n < 2; ++n) _Pragma("unroll") for (int k = 0; k < 2; ++k) \
;         acc[ai][bj][m][n] = __builtin_amdgcn_mfma_f32_16x16x32_bf16(Bt[n][k], At[m][k], acc[ai][bj][m][n], 0, 0, 0); __builtin_amdgcn_s_setprio(0); } while (0)
; #define PG8_WAIT_V(n) asm volatile("s_waitcnt vmcnt(" #n ")" ::: "memory")
; #define PG8_WAIT_L(n) asm volatile("s_waitcnt lgkmcnt(" #n ")" ::: "memory")
; #define PG8_BAR __builtin_amdgcn_s_barrier()
; #define PG8_SCHED __builtin_amdgcn_sched_barrier(0)
; template <class Epi, class Sched, bool ALIGN_EPI = false, bool SP2 = true>
; __device__ __forceinline__ void gemm_phase(PG8_LAS unsigned char* lds, const Gemm g, const Sched& S, const Epi& E) {
;     ...
;             PG8_LDB(B0, 0, 0); PG8_LDB(B1, 0, 1); PG8_SCHED; PG8_LDA(At, 0, 0); PG8_STAGE(PG8_SA(1, 1), a1 + hstep, voffA);
;             PG8_WAIT_V(8); PG8_WAIT_L(0); PG8_BAR; PG8_MMA(0, 0, At, B0); PG8_MMA(0, 1, At, B1); PG8_BAR; PG8_SCHED;
;             if (full) { PG8_LDA(At, 0, 1); } PG8_STAGE(PG8_SB(0, 0), b2, voffB); PG8_STAGE(PG8_SB(0, 1), b2 + hstep, voffB); PG8_STAGE(PG8_SA(0, 0), a2, voffA);
;             PG8_WAIT_V(8); PG8_WAIT_L(0); PG8_BAR; if (full) { PG8_MMA(1, 0, At, B0); PG8_MMA(1, 1, At, B1); } PG8_BAR; PG8_SCHED;
.LBB0_1321:
	ds_read_b128 v[150:153], v221
	ds_read_b128 v[154:157], v221 offset:1024
	ds_read_b128 v[158:161], v221 offset:2048
	ds_read_b128 v[162:165], v221 offset:3072
	ds_read_b128 v[134:137], v222
	ds_read_b128 v[138:141], v222 offset:1024
	ds_read_b128 v[142:145], v222 offset:2048
	ds_read_b128 v[146:149], v222 offset:3072
	s_add_i32 m0, s39, 0xc000
	s_waitcnt lgkmcnt(0)
	ds_read_b128 v[178:181], v223
	ds_read_b128 v[194:197], v223 offset:1024
	ds_read_b128 v[174:177], v223 offset:2048
	ds_read_b128 v[190:193], v223 offset:3072
	ds_read_b128 v[170:173], v223 offset:4096
	ds_read_b128 v[186:189], v223 offset:5120
	ds_read_b128 v[166:169], v223 offset:6144
	ds_read_b128 v[182:185], v223 offset:7168
	global_load_lds_dwordx4 v208, s[28:29]
	s_add_i32 m0, s39, 0xe000
	s_nop 0
	global_load_lds_dwordx4 v210, s[28:29]
	s_waitcnt vmcnt(8)
	s_waitcnt lgkmcnt(0)
	s_setprio 1
	s_barrier
	v_mfma_f32_16x16x32_bf16 v[130:133], v[150:153], v[178:181], v[130:133]
	v_mfma_f32_16x16x32_bf16 v[126:129], v[158:161], v[178:181], v[126:129]
	v_mfma_f32_16x16x32_bf16 v[114:117], v[150:153], v[174:177], v[114:117]
	v_mfma_f32_16x16x32_bf16 v[110:113], v[158:161], v[174:177], v[110:113]
	v_mfma_f32_16x16x32_bf16 v[98:101], v[150:153], v[170:173], v[98:101]
	v_mfma_f32_16x16x32_bf16 v[94:97], v[158:161], v[170:173], v[94:97]
	v_mfma_f32_16x16x32_bf16 v[82:85], v[150:153], v[166:169], v[82:85]
	v_mfma_f32_16x16x32_bf16 v[78:81], v[158:161], v[166:169], v[78:81]
	v_mfma_f32_16x16x32_bf16 v[130:133], v[154:157], v[194:197], v[130:133]
	v_mfma_f32_16x16x32_bf16 v[126:129], v[162:165], v[194:197], v[126:129]
	v_mfma_f32_16x16x32_bf16 v[114:117], v[154:157], v[190:193], v[114:117]
	v_mfma_f32_16x16x32_bf16 v[110:113], v[162:165], v[190:193], v[110:113]
	v_mfma_f32_16x16x32_bf16 v[98:101], v[154:157], v[186:189], v[98:101]
	v_mfma_f32_16x16x32_bf16 v[94:97], v[162:165], v[186:189], v[94:97]
	v_mfma_f32_16x16x32_bf16 v[82:85], v[154:157], v[182:185], v[82:85]
	v_mfma_f32_16x16x32_bf16 v[78:81], v[162:165], v[182:185], v[78:81]
	v_mfma_f32_16x16x32_bf16 v[122:125], v[134:137], v[178:181], v[122:125]
	v_mfma_f32_16x16x32_bf16 v[118:121], v[142:145], v[178:181], v[118:121]
	v_mfma_f32_16x16x32_bf16 v[106:109], v[134:137], v[174:177], v[106:109]
	v_mfma_f32_16x16x32_bf16 v[102:105], v[142:145], v[174:177], v[102:105]
	v_mfma_f32_16x16x32_bf16 v[90:93], v[134:137], v[170:173], v[90:93]
	v_mfma_f32_16x16x32_bf16 v[86:89], v[142:145], v[170:173], v[86:89]
	v_mfma_f32_16x16x32_bf16 v[74:77], v[134:137], v[166:169], v[74:77]
	v_mfma_f32_16x16x32_bf16 v[70:73], v[142:145], v[166:169], v[70:73]
	v_mfma_f32_16x16x32_bf16 v[122:125], v[138:141], v[194:197], v[122:125]
	v_mfma_f32_16x16x32_bf16 v[118:121], v[146:149], v[194:197], v[118:121]
	v_mfma_f32_16x16x32_bf16 v[106:109], v[138:141], v[190:193], v[106:109]
	v_mfma_f32_16x16x32_bf16 v[102:105], v[146:149], v[190:193], v[102:105]
	v_mfma_f32_16x16x32_bf16 v[90:93], v[138:141], v[186:189], v[90:93]
	v_mfma_f32_16x16x32_bf16 v[86:89], v[146:149], v[186:189], v[86:89]
	v_mfma_f32_16x16x32_bf16 v[74:77], v[138:141], v[182:185], v[74:77]
	v_mfma_f32_16x16x32_bf16 v[70:73], v[146:149], v[182:185], v[70:73]
	s_barrier
	s_setprio 0
	v_cmp_ne_u32_e64 s[4:5], 1, v224
	s_andn2_b64 vcc, exec, s[26:27]
	s_cbranch_vccnz .LBB0_1323
	ds_read_b128 v[178:181], v223 offset:16384
	ds_read_b128 v[194:197], v223 offset:17408
	ds_read_b128 v[174:177], v223 offset:18432
	ds_read_b128 v[190:193], v223 offset:19456
	ds_read_b128 v[170:173], v223 offset:20480
	ds_read_b128 v[186:189], v223 offset:21504
	ds_read_b128 v[166:169], v223 offset:22528
	ds_read_b128 v[182:185], v223 offset:23552
.LBB0_1323:
	s_add_u32 s30, s28, 0xfff00080
	s_addc_u32 s31, s29, -1
	s_cmp_eq_u32 s61, 60
	s_cselect_b32 s35, s15, s31
	s_cselect_b32 s34, s19, s30
	s_cselect_b32 s31, s17, s60
	s_cselect_b32 s30, s58, s59
	s_mov_b32 m0, s40
	s_add_u32 s62, s30, 0x100000
	global_load_lds_dwordx4 v202, s[30:31]
	s_mov_b32 m0, s41
	s_addc_u32 s63, s31, 0
	global_load_lds_dwordx4 v206, s[30:31]
	s_mov_b32 m0, s42
	s_nop 0
	global_load_lds_dwordx4 v202, s[62:63]
	s_mov_b32 m0, s43
	s_and_b64 vcc, exec, s[4:5]
	global_load_lds_dwordx4 v206, s[62:63]
	s_mov_b32 m0, s39
	s_nop 0
	global_load_lds_dwordx4 v200, s[34:35]
	s_mov_b32 m0, s44
	s_nop 0
	global_load_lds_dwordx4 v204, s[34:35]
	s_waitcnt vmcnt(8)
	s_waitcnt lgkmcnt(0)
	s_setprio 1
	s_barrier
	s_cbranch_vccnz .LBB0_1325
	v_mfma_f32_16x16x32_bf16 v[66:69], v[150:153], v[178:181], v[66:69]
	v_mfma_f32_16x16x32_bf16 v[62:65], v[158:161], v[178:181], v[62:65]
	v_mfma_f32_16x16x32_bf16 v[50:53], v[150:153], v[174:177], v[50:53]
	v_mfma_f32_16x16x32_bf16 v[46:49], v[158:161], v[174:177], v[46:49]
	v_mfma_f32_16x16x32_bf16 v[34:37], v[150:153], v[170:173], v[34:37]
	v_mfma_f32_16x16x32_bf16 v[30:33], v[158:161], v[170:173], v[30:33]
	v_mfma_f32_16x16x32_bf16 v[18:21], v[150:153], v[166:169], v[18:21]
	v_mfma_f32_16x16x32_bf16 v[14:17], v[158:161], v[166:169], v[14:17]
	v_mfma_f32_16x16x32_bf16 v[66:69], v[154:157], v[194:197], v[66:69]
	v_mfma_f32_16x16x32_bf16 v[62:65], v[162:165], v[194:197], v[62:65]
	v_mfma_f32_16x16x32_bf16 v[50:53], v[154:157], v[190:193], v[50:53]
	v_mfma_f32_16x16x32_bf16 v[46:49], v[162:165], v[190:193], v[46:49]
	v_mfma_f32_16x16x32_bf16 v[34:37], v[154:157], v[186:189], v[34:37]
	v_mfma_f32_16x16x32_bf16 v[30:33], v[162:165], v[186:189], v[30:33]
	v_mfma_f32_16x16x32_bf16 v[18:21], v[154:157], v[182:185], v[18:21]
	v_mfma_f32_16x16x32_bf16 v[14:17], v[162:165], v[182:185], v[14:17]
	v_mfma_f32_16x16x32_bf16 v[58:61], v[134:137], v[178:181], v[58:61]
	v_mfma_f32_16x16x32_bf16 v[54:57], v[142:145], v[178:181], v[54:57]
	v_mfma_f32_16x16x32_bf16 v[42:45], v[134:137], v[174:177], v[42:45]
	v_mfma_f32_16x16x32_bf16 v[38:41], v[142:145], v[174:177], v[38:41]
	v_mfma_f32_16x16x32_bf16 v[26:29], v[134:137], v[170:173], v[26:29]
	v_mfma_f32_16x16x32_bf16 v[22:25], v[142:145], v[170:173], v[22:25]
	v_mfma_f32_16x16x32_bf16 v[10:13], v[134:137], v[166:169], v[10:13]
	v_mfma_f32_16x16x32_bf16 v[6:9], v[142:145], v[166:169], v[6:9]
	v_mfma_f32_16x16x32_bf16 v[58:61], v[138:141], v[194:197], v[58:61]
	v_mfma_f32_16x16x32_bf16 v[54:57], v[146:149], v[194:197], v[54:57]
	v_mfma_f32_16x16x32_bf16 v[42:45], v[138:141], v[190:193], v[42:45]
	v_mfma_f32_16x16x32_bf16 v[38:41], v[146:149], v[190:193], v[38:41]
	v_mfma_f32_16x16x32_bf16 v[26:29], v[138:141], v[186:189], v[26:29]
	v_mfma_f32_16x16x32_bf16 v[22:25], v[146:149], v[186:189], v[22:25]
	v_mfma_f32_16x16x32_bf16 v[10:13], v[138:141], v[182:185], v[10:13]
	v_mfma_f32_16x16x32_bf16 v[6:9], v[146:149], v[182:185], v[6:9]
; #define PG8_STAGE(bufoff, gbase, voff) do { _Pragma("unroll") for (int _i = 0; _i < 2; ++_i) \
;         __builtin_amdgcn_global_load_lds((const unsigned*)((const char*)(gbase) + (voff)[_i]), (PG8_LAS unsigned*)(lds + (bufoff) + ldsw + _i * 8192), 16, 0, 0); } while (0)
; #define PG8_LDA(dst, b, h) do { _Pragma("unroll") for (int m = 0; m < 4; ++m) _Pragma("unroll") for (int k = 0; k < 2; ++k) dst[m][k] = *(const PG8_LAS bf16x8*)(lds + PG8_SA(b, h) + aoff + m * 2048 + k * 1024); } while (0)
; #define PG8_LDB(dst, b, h) do { _Pragma("unroll") for (int n = 0; n < 2; ++n) _Pragma("unroll") for (int k = 0; k < 2; ++k) dst[n][k] = *(const PG8_LAS bf16x8*)(lds + PG8_SB(b, h) + boff + n * 2048 + k * 1024); } while (0)
; #define PG8_MMA(ai, bj, At, Bt) do { __builtin_amdgcn_s_setprio(1); _Pragma("unroll") for (int m = 0; m < 4; ++m) _Pragma("unroll") for (int n = 0; n < 2; ++n) _Pragma("unroll") for (int k = 0; k < 2; ++k) \
;         acc[ai][bj][m][n] = __builtin_amdgcn_mfma_f32_16x16x32_bf16(Bt[n][k], At[m][k], acc[ai][bj][m][n], 0, 0, 0); __builtin_amdgcn_s_setprio(0); } while (0)
; #define PG8_WAIT_V(n) asm volatile("s_waitcnt vmcnt(" #n ")" ::: "memory")
; #define PG8_WAIT_L(n) asm volatile("s_waitcnt lgkmcnt(" #n ")" ::: "memory")
; #define PG8_BAR __builtin_amdgcn_s_barrier()
; #define PG8_SCHED __builtin_amdgcn_sched_barrier(0)
; template <class Epi, class Sched, bool ALIGN_EPI = false, bool SP2 = true>
; __device__ __forceinline__ void gemm_phase(PG8_LAS unsigned char* lds, const Gemm g, const Sched& S, const Epi& E) {
;     ...
;             PG8_LDB(B0, 1, 0); PG8_LDB(B1, 1, 1); PG8_SCHED; PG8_LDA(At, 1, 0); PG8_STAGE(PG8_SA(0, 1), a2 + hstep, voffA);
;             PG8_WAIT_V(8); PG8_WAIT_L(0); PG8_BAR; PG8_MMA(0, 0, At, B0); PG8_MMA(0, 1, At, B1); PG8_BAR; PG8_SCHED;
;             if (full) { PG8_LDA(At, 1, 1); } PG8_STAGE(PG8_SB(1, 0), b3, voffB); PG8_STAGE(PG8_SB(1, 1), b3 + hstep, voffB); PG8_STAGE(PG8_SA(1, 0), a3, voffA);
;             PG8_WAIT_V(8); PG8_WAIT_L(0); PG8_BAR; if (full) { PG8_MMA(1, 0, At, B0); PG8_MMA(1, 1, At, B1); } PG8_BAR; PG8_SCHED;
.LBB0_1325:
	s_barrier
	s_setprio 0
	v_add_u32_e32 v3, 0x18000, v220
	ds_read_b128 v[150:153], v3
	ds_read_b128 v[154:157], v3 offset:1024
	ds_read_b128 v[158:161], v3 offset:2048
	ds_read_b128 v[162:165], v3 offset:3072
	v_add_u32_e32 v3, 0x1c000, v220
	ds_read_b128 v[134:137], v3
	ds_read_b128 v[138:141], v3 offset:1024
	ds_read_b128 v[142:145], v3 offset:2048
	ds_read_b128 v[146:149], v3 offset:3072
	s_add_u32 s34, s34, 0x100000
	s_addc_u32 s35, s35, 0
	s_mov_b32 m0, s45
	s_waitcnt lgkmcnt(0)
	ds_read_b128 v[178:181], v223 offset:32768
	ds_read_b128 v[194:197], v223 offset:33792
	ds_read_b128 v[174:177], v223 offset:34816
	ds_read_b128 v[190:193], v223 offset:35840
	ds_read_b128 v[170:173], v223 offset:36864
	ds_read_b128 v[186:189], v223 offset:37888
	ds_read_b128 v[166:169], v223 offset:38912
	ds_read_b128 v[182:185], v223 offset:39936
	global_load_lds_dwordx4 v200, s[34:35]
	s_mov_b32 m0, s46
	s_nop 0
	global_load_lds_dwordx4 v204, s[34:35]
	s_waitcnt vmcnt(8)
	s_waitcnt lgkmcnt(0)
	s_setprio 1
	s_barrier
	v_mfma_f32_16x16x32_bf16 v[130:133], v[150:153], v[178:181], v[130:133]
	v_mfma_f32_16x16x32_bf16 v[126:129], v[158:161], v[178:181], v[126:129]
	v_mfma_f32_16x16x32_bf16 v[114:117], v[150:153], v[174:177], v[114:117]
	v_mfma_f32_16x16x32_bf16 v[110:113], v[158:161], v[174:177], v[110:113]
	v_mfma_f32_16x16x32_bf16 v[98:101], v[150:153], v[170:173], v[98:101]
	v_mfma_f32_16x16x32_bf16 v[94:97], v[158:161], v[170:173], v[94:97]
	v_mfma_f32_16x16x32_bf16 v[82:85], v[150:153], v[166:169], v[82:85]
	v_mfma_f32_16x16x32_bf16 v[78:81], v[158:161], v[166:169], v[78:81]
	v_mfma_f32_16x16x32_bf16 v[130:133], v[154:157], v[194:197], v[130:133]
	v_mfma_f32_16x16x32_bf16 v[126:129], v[162:165], v[194:197], v[126:129]
	v_mfma_f32_16x16x32_bf16 v[114:117], v[154:157], v[190:193], v[114:117]
	v_mfma_f32_16x16x32_bf16 v[110:113], v[162:165], v[190:193], v[110:113]
	v_mfma_f32_16x16x32_bf16 v[98:101], v[154:157], v[186:189], v[98:101]
	v_mfma_f32_16x16x32_bf16 v[94:97], v[162:165], v[186:189], v[94:97]
	v_mfma_f32_16x16x32_bf16 v[82:85], v[154:157], v[182:185], v[82:85]
	v_mfma_f32_16x16x32_bf16 v[78:81], v[162:165], v[182:185], v[78:81]
	v_mfma_f32_16x16x32_bf16 v[122:125], v[134:137], v[178:181], v[122:125]
	v_mfma_f32_16x16x32_bf16 v[118:121], v[142:145], v[178:181], v[118:121]
	v_mfma_f32_16x16x32_bf16 v[106:109], v[134:137], v[174:177], v[106:109]
	v_mfma_f32_16x16x32_bf16 v[102:105], v[142:145], v[174:177], v[102:105]
	v_mfma_f32_16x16x32_bf16 v[90:93], v[134:137], v[170:173], v[90:93]
	v_mfma_f32_16x16x32_bf16 v[86:89], v[142:145], v[170:173], v[86:89]
	v_mfma_f32_16x16x32_bf16 v[74:77], v[134:137], v[166:169], v[74:77]
	v_mfma_f32_16x16x32_bf16 v[70:73], v[142:145], v[166:169], v[70:73]
	v_mfma_f32_16x16x32_bf16 v[122:125], v[138:141], v[194:197], v[122:125]
	v_mfma_f32_16x16x32_bf16 v[118:121], v[146:149], v[194:197], v[118:121]
	v_mfma_f32_16x16x32_bf16 v[106:109], v[138:141], v[190:193], v[106:109]
	v_mfma_f32_16x16x32_bf16 v[102:105], v[146:149], v[190:193], v[102:105]
	v_mfma_f32_16x16x32_bf16 v[90:93], v[138:141], v[186:189], v[90:93]
	v_mfma_f32_16x16x32_bf16 v[86:89], v[146:149], v[186:189], v[86:89]
	v_mfma_f32_16x16x32_bf16 v[74:77], v[138:141], v[182:185], v[74:77]
	v_mfma_f32_16x16x32_bf16 v[70:73], v[146:149], v[182:185], v[70:73]
	s_barrier
	s_setprio 0
	s_and_b64 vcc, exec, s[4:5]
	s_cbranch_vccnz .LBB0_1327
	ds_read_b128 v[178:181], v223 offset:49152
	ds_read_b128 v[194:197], v223 offset:50176
	ds_read_b128 v[174:177], v223 offset:51200
	ds_read_b128 v[190:193], v223 offset:52224
	ds_read_b128 v[170:173], v223 offset:53248
	ds_read_b128 v[186:189], v223 offset:54272
	ds_read_b128 v[166:169], v223 offset:55296
	ds_read_b128 v[182:185], v223 offset:56320
.LBB0_1327:
	s_mov_b32 m0, s48
	s_add_u32 s98, s30, 0x80
	s_addc_u32 s99, s31, 0
	s_add_u32 s30, s30, 0x100080
	global_load_lds_dwordx4 v202, s[98:99]
	s_mov_b32 m0, s49
	s_addc_u32 s31, s31, 0
	global_load_lds_dwordx4 v206, s[98:99]
	s_mov_b32 m0, s52
	s_and_b64 vcc, exec, s[4:5]
	global_load_lds_dwordx4 v202, s[30:31]
	s_mov_b32 m0, s53
	s_nop 0
	global_load_lds_dwordx4 v206, s[30:31]
	s_mov_b32 m0, s50
	s_nop 0
	s_add_u32 s100, s34, 0xfff00080
	s_addc_u32 s101, s35, -1
	global_load_lds_dwordx4 v200, s[100:101]
	s_mov_b32 m0, s51
	s_nop 0
	global_load_lds_dwordx4 v204, s[100:101]
	s_waitcnt vmcnt(8)
	s_waitcnt lgkmcnt(0)
	s_setprio 1
	s_barrier
	s_cbranch_vccnz .LBB0_1320
	v_mfma_f32_16x16x32_bf16 v[66:69], v[150:153], v[178:181], v[66:69]
	v_mfma_f32_16x16x32_bf16 v[62:65], v[158:161], v[178:181], v[62:65]
	v_mfma_f32_16x16x32_bf16 v[50:53], v[150:153], v[174:177], v[50:53]
	v_mfma_f32_16x16x32_bf16 v[46:49], v[158:161], v[174:177], v[46:49]
	v_mfma_f32_16x16x32_bf16 v[34:37], v[150:153], v[170:173], v[34:37]
	v_mfma_f32_16x16x32_bf16 v[30:33], v[158:161], v[170:173], v[30:33]
	v_mfma_f32_16x16x32_bf16 v[18:21], v[150:153], v[166:169], v[18:21]
	v_mfma_f32_16x16x32_bf16 v[14:17], v[158:161], v[166:169], v[14:17]
	v_mfma_f32_16x16x32_bf16 v[66:69], v[154:157], v[194:197], v[66:69]
	v_mfma_f32_16x16x32_bf16 v[62:65], v[162:165], v[194:197], v[62:65]
	v_mfma_f32_16x16x32_bf16 v[50:53], v[154:157], v[190:193], v[50:53]
	v_mfma_f32_16x16x32_bf16 v[46:49], v[162:165], v[190:193], v[46:49]
	v_mfma_f32_16x16x32_bf16 v[34:37], v[154:157], v[186:189], v[34:37]
	v_mfma_f32_16x16x32_bf16 v[30:33], v[162:165], v[186:189], v[30:33]
	v_mfma_f32_16x16x32_bf16 v[18:21], v[154:157], v[182:185], v[18:21]
	v_mfma_f32_16x16x32_bf16 v[14:17], v[162:165], v[182:185], v[14:17]
	v_mfma_f32_16x16x32_bf16 v[58:61], v[134:137], v[178:181], v[58:61]
	v_mfma_f32_16x16x32_bf16 v[54:57], v[142:145], v[178:181], v[54:57]
	v_mfma_f32_16x16x32_bf16 v[42:45], v[134:137], v[174:177], v[42:45]
	v_mfma_f32_16x16x32_bf16 v[38:41], v[142:145], v[174:177], v[38:41]
	v_mfma_f32_16x16x32_bf16 v[26:29], v[134:137], v[170:173], v[26:29]
	v_mfma_f32_16x16x32_bf16 v[22:25], v[142:145], v[170:173], v[22:25]
	v_mfma_f32_16x16x32_bf16 v[10:13], v[134:137], v[166:169], v[10:13]
	v_mfma_f32_16x16x32_bf16 v[4:7], v[142:145], v[166:169], v[6:9]
	v_mfma_f32_16x16x32_bf16 v[58:61], v[138:141], v[194:197], v[58:61]
	v_mfma_f32_16x16x32_bf16 v[54:57], v[146:149], v[194:197], v[54:57]
	v_mfma_f32_16x16x32_bf16 v[42:45], v[138:141], v[190:193], v[42:45]
	v_mfma_f32_16x16x32_bf16 v[38:41], v[146:149], v[190:193], v[38:41]
	v_mfma_f32_16x16x32_bf16 v[26:29], v[138:141], v[186:189], v[26:29]
	v_mfma_f32_16x16x32_bf16 v[22:25], v[146:149], v[186:189], v[22:25]
	v_mfma_f32_16x16x32_bf16 v[10:13], v[138:141], v[182:185], v[10:13]
	v_mfma_f32_16x16x32_bf16 v[6:9], v[146:149], v[182:185], v[4:7]
	s_branch .LBB0_1320

; #define PG8_STAGE(bufoff, gbase, voff) do { _Pragma("unroll") for (int _i = 0; _i < 2; ++_i) \
;         __builtin_amdgcn_global_load_lds((const unsigned*)((const char*)(gbase) + (voff)[_i]), (PG8_LAS unsigned*)(lds + (bufoff) + ldsw + _i * 8192), 16, 0, 0); } while (0)
; #define PG8_LDA(dst, b, h) do { _Pragma("unroll") for (int m = 0; m < 4; ++m) _Pragma("unroll") for (int k = 0; k < 2; ++k) dst[m][k] = *(const PG8_LAS bf16x8*)(lds + PG8_SA(b, h) + aoff + m * 2048 + k * 1024); } while (0)
; #define PG8_LDB(dst, b, h) do { _Pragma("unroll") for (int n = 0; n < 2; ++n) _Pragma("unroll") for (int k = 0; k < 2; ++k) dst[n][k] = *(const PG8_LAS bf16x8*)(lds + PG8_SB(b, h) + boff + n * 2048 + k * 1024); } while (0)
; #define PG8_MMA(ai, bj, At, Bt) do { __builtin_amdgcn_s_setprio(1); _Pragma("unroll") for (int m = 0; m < 4; ++m) _Pragma("unroll") for (int n = 0; n < 2; ++n) _Pragma("unroll") for (int k = 0; k < 2; ++k) \
;         acc[ai][bj][m][n] = __builtin_amdgcn_mfma_f32_16x16x32_bf16(Bt[n][k], At[m][k], acc[ai][bj][m][n], 0, 0, 0); __builtin_amdgcn_s_setprio(0); } while (0)
; #define PG8_WAIT_V(n) asm volatile("s_waitcnt vmcnt(" #n ")" ::: "memory")
; #define PG8_BAR __builtin_amdgcn_s_barrier()
; template <class Epi, class Sched, bool ALIGN_EPI = false, bool SP2 = true>
; __device__ __forceinline__ void gemm_phase(PG8_LAS unsigned char* lds, const Gemm g, const Sched& S, const Epi& E) {
;     ...
;         for (int t = 0; t < nt; t += 2) {
;             const bool last = (t == nt - 2);
;             const char* a1 = cA + (size_t)(t + 1) * kstep;
;             const char* a2 = last ? nA : cA + (size_t)(t + 2) * kstep; const char* b2 = last ? nB : cB + (size_t)(t + 2) * kstep;
;             const char* a3 = a2 + kstep; const char* b3 = b2 + kstep;
;             if (last && has_next) S.a_ready(nxt);
;             if constexpr (SP2) {
;             PG8_LDB(B0, 0, 0); PG8_LDB(B1, 0, 1); PG8_SCHED; PG8_LDA(At, 0, 0); PG8_STAGE(PG8_SA(1, 1), a1 + hstep, voffA);
;             PG8_WAIT_V(8); PG8_WAIT_L(0); PG8_BAR; PG8_MMA(0, 0, At, B0); PG8_MMA(0, 1, At, B1); PG8_BAR; PG8_SCHED;
;             if (full) { PG8_LDA(At, 0, 1); } PG8_STAGE(PG8_SB(0, 0), b2, voffB); PG8_STAGE(PG8_SB(0, 1), b2 + hstep, voffB); PG8_STAGE(PG8_SA(0, 0), a2, voffA);
;             PG8_WAIT_V(8); PG8_WAIT_L(0); PG8_BAR; if (full) { PG8_MMA(1, 0, At, B0); PG8_MMA(1, 1, At, B1); } PG8_BAR; PG8_SCHED;
.LBB0_1427:
	ds_read_b128 v[150:153], v224
	ds_read_b128 v[154:157], v224 offset:1024
	ds_read_b128 v[158:161], v224 offset:2048
	ds_read_b128 v[162:165], v224 offset:3072
	ds_read_b128 v[134:137], v225
	ds_read_b128 v[138:141], v225 offset:1024
	ds_read_b128 v[142:145], v225 offset:2048
	ds_read_b128 v[146:149], v225 offset:3072
	s_add_i32 m0, s41, 0xc000
	s_waitcnt lgkmcnt(0)
	ds_read_b128 v[178:181], v226
	ds_read_b128 v[194:197], v226 offset:1024
	ds_read_b128 v[174:177], v226 offset:2048
	ds_read_b128 v[190:193], v226 offset:3072
	ds_read_b128 v[170:173], v226 offset:4096
	ds_read_b128 v[186:189], v226 offset:5120
	ds_read_b128 v[166:169], v226 offset:6144
	ds_read_b128 v[182:185], v226 offset:7168
	global_load_lds_dwordx4 v210, s[28:29]
	s_add_i32 m0, s41, 0xe000
	s_nop 0
	global_load_lds_dwordx4 v212, s[28:29]
	s_waitcnt vmcnt(8)
	s_waitcnt lgkmcnt(0)
	s_setprio 1
	s_barrier
	v_mfma_f32_16x16x32_bf16 v[66:69], v[150:153], v[178:181], v[66:69]
	v_mfma_f32_16x16x32_bf16 v[62:65], v[158:161], v[178:181], v[62:65]
	v_mfma_f32_16x16x32_bf16 v[50:53], v[150:153], v[174:177], v[50:53]
	v_mfma_f32_16x16x32_bf16 v[46:49], v[158:161], v[174:177], v[46:49]
	v_mfma_f32_16x16x32_bf16 v[34:37], v[150:153], v[170:173], v[34:37]
	v_mfma_f32_16x16x32_bf16 v[30:33], v[158:161], v[170:173], v[30:33]
	v_mfma_f32_16x16x32_bf16 v[18:21], v[150:153], v[166:169], v[18:21]
	v_mfma_f32_16x16x32_bf16 v[14:17], v[158:161], v[166:169], v[14:17]
	v_mfma_f32_16x16x32_bf16 v[66:69], v[154:157], v[194:197], v[66:69]
	v_mfma_f32_16x16x32_bf16 v[62:65], v[162:165], v[194:197], v[62:65]
	v_mfma_f32_16x16x32_bf16 v[50:53], v[154:157], v[190:193], v[50:53]
	v_mfma_f32_16x16x32_bf16 v[46:49], v[162:165], v[190:193], v[46:49]
	v_mfma_f32_16x16x32_bf16 v[34:37], v[154:157], v[186:189], v[34:37]
	v_mfma_f32_16x16x32_bf16 v[30:33], v[162:165], v[186:189], v[30:33]
	v_mfma_f32_16x16x32_bf16 v[18:21], v[154:157], v[182:185], v[18:21]
	v_mfma_f32_16x16x32_bf16 v[14:17], v[162:165], v[182:185], v[14:17]
	v_mfma_f32_16x16x32_bf16 v[58:61], v[134:137], v[178:181], v[58:61]
	v_mfma_f32_16x16x32_bf16 v[54:57], v[142:145], v[178:181], v[54:57]
	v_mfma_f32_16x16x32_bf16 v[42:45], v[134:137], v[174:177], v[42:45]
	v_mfma_f32_16x16x32_bf16 v[38:41], v[142:145], v[174:177], v[38:41]
	v_mfma_f32_16x16x32_bf16 v[26:29], v[134:137], v[170:173], v[26:29]
	v_mfma_f32_16x16x32_bf16 v[22:25], v[142:145], v[170:173], v[22:25]
	v_mfma_f32_16x16x32_bf16 v[10:13], v[134:137], v[166:169], v[10:13]
	v_mfma_f32_16x16x32_bf16 v[4:7], v[142:145], v[166:169], v[6:9]
	v_mfma_f32_16x16x32_bf16 v[58:61], v[138:141], v[194:197], v[58:61]
	v_mfma_f32_16x16x32_bf16 v[54:57], v[146:149], v[194:197], v[54:57]
	v_mfma_f32_16x16x32_bf16 v[42:45], v[138:141], v[190:193], v[42:45]
	v_mfma_f32_16x16x32_bf16 v[38:41], v[146:149], v[190:193], v[38:41]
	v_mfma_f32_16x16x32_bf16 v[26:29], v[138:141], v[186:189], v[26:29]
	v_mfma_f32_16x16x32_bf16 v[22:25], v[146:149], v[186:189], v[22:25]
	v_mfma_f32_16x16x32_bf16 v[10:13], v[138:141], v[182:185], v[10:13]
	v_mfma_f32_16x16x32_bf16 v[4:7], v[146:149], v[182:185], v[4:7]
	s_barrier
	s_setprio 0
	v_cmp_ne_u32_e64 s[8:9], 1, v227
	s_andn2_b64 vcc, exec, s[2:3]
	s_cbranch_vccnz .LBB0_1429
	ds_read_b128 v[178:181], v226 offset:16384
	ds_read_b128 v[194:197], v226 offset:17408
	ds_read_b128 v[174:177], v226 offset:18432
	ds_read_b128 v[190:193], v226 offset:19456
	ds_read_b128 v[170:173], v226 offset:20480
	ds_read_b128 v[186:189], v226 offset:21504
	ds_read_b128 v[166:169], v226 offset:22528
	ds_read_b128 v[182:185], v226 offset:23552
.LBB0_1429:
	s_add_u32 s30, s28, 0xffd50080
	s_addc_u32 s31, s29, -1
	s_cmp_eq_u32 s23, s70
	s_cselect_b32 s35, s25, s31
	s_cselect_b32 s34, s24, s30
	s_cselect_b32 s31, s27, s69
	s_cselect_b32 s30, s26, s68
	s_mov_b32 m0, s42
	s_add_u32 s72, s30, 0x2b0000
	global_load_lds_dwordx4 v202, s[30:31]
	s_mov_b32 m0, s43
	s_addc_u32 s73, s31, 0
	global_load_lds_dwordx4 v206, s[30:31]
	s_mov_b32 m0, s44
	s_nop 0
	global_load_lds_dwordx4 v202, s[72:73]
	s_mov_b32 m0, s45
	s_nop 0
	global_load_lds_dwordx4 v206, s[72:73]
	s_mov_b32 m0, s41
	s_and_b64 vcc, exec, s[8:9]
	global_load_lds_dwordx4 v200, s[34:35]
	s_mov_b32 m0, s46
	s_nop 0
	global_load_lds_dwordx4 v204, s[34:35]
	s_waitcnt vmcnt(8)
	s_waitcnt lgkmcnt(0)
	s_setprio 1
	s_barrier
	s_cbranch_vccnz .LBB0_1431
	v_mfma_f32_16x16x32_bf16 v[130:133], v[150:153], v[178:181], v[130:133]
	v_mfma_f32_16x16x32_bf16 v[126:129], v[158:161], v[178:181], v[126:129]
	v_mfma_f32_16x16x32_bf16 v[118:121], v[150:153], v[174:177], v[118:121]
	v_mfma_f32_16x16x32_bf16 v[110:113], v[158:161], v[174:177], v[110:113]
	v_mfma_f32_16x16x32_bf16 v[102:105], v[150:153], v[170:173], v[102:105]
	v_mfma_f32_16x16x32_bf16 v[94:97], v[158:161], v[170:173], v[94:97]
	v_mfma_f32_16x16x32_bf16 v[86:89], v[150:153], v[166:169], v[86:89]
	v_mfma_f32_16x16x32_bf16 v[78:81], v[158:161], v[166:169], v[78:81]
	v_mfma_f32_16x16x32_bf16 v[130:133], v[154:157], v[194:197], v[130:133]
	v_mfma_f32_16x16x32_bf16 v[126:129], v[162:165], v[194:197], v[126:129]
	v_mfma_f32_16x16x32_bf16 v[118:121], v[154:157], v[190:193], v[118:121]
	v_mfma_f32_16x16x32_bf16 v[110:113], v[162:165], v[190:193], v[110:113]
	v_mfma_f32_16x16x32_bf16 v[102:105], v[154:157], v[186:189], v[102:105]
	v_mfma_f32_16x16x32_bf16 v[94:97], v[162:165], v[186:189], v[94:97]
	v_mfma_f32_16x16x32_bf16 v[86:89], v[154:157], v[182:185], v[86:89]
	v_mfma_f32_16x16x32_bf16 v[78:81], v[162:165], v[182:185], v[78:81]
	v_mfma_f32_16x16x32_bf16 v[122:125], v[134:137], v[178:181], v[122:125]
	v_mfma_f32_16x16x32_bf16 v[114:117], v[142:145], v[178:181], v[114:117]
	v_mfma_f32_16x16x32_bf16 v[106:109], v[134:137], v[174:177], v[106:109]
	v_mfma_f32_16x16x32_bf16 v[98:101], v[142:145], v[174:177], v[98:101]
	v_mfma_f32_16x16x32_bf16 v[90:93], v[134:137], v[170:173], v[90:93]
	v_mfma_f32_16x16x32_bf16 v[82:85], v[142:145], v[170:173], v[82:85]
	v_mfma_f32_16x16x32_bf16 v[74:77], v[134:137], v[166:169], v[74:77]
	v_mfma_f32_16x16x32_bf16 v[70:73], v[142:145], v[166:169], v[70:73]
	v_mfma_f32_16x16x32_bf16 v[122:125], v[138:141], v[194:197], v[122:125]
	v_mfma_f32_16x16x32_bf16 v[114:117], v[146:149], v[194:197], v[114:117]
	v_mfma_f32_16x16x32_bf16 v[106:109], v[138:141], v[190:193], v[106:109]
	v_mfma_f32_16x16x32_bf16 v[98:101], v[146:149], v[190:193], v[98:101]
	v_mfma_f32_16x16x32_bf16 v[90:93], v[138:141], v[186:189], v[90:93]
	v_mfma_f32_16x16x32_bf16 v[82:85], v[146:149], v[186:189], v[82:85]
	v_mfma_f32_16x16x32_bf16 v[74:77], v[138:141], v[182:185], v[74:77]
	v_mfma_f32_16x16x32_bf16 v[70:73], v[146:149], v[182:185], v[70:73]
; #define PG8_STAGE(bufoff, gbase, voff) do { _Pragma("unroll") for (int _i = 0; _i < 2; ++_i) \
;         __builtin_amdgcn_global_load_lds((const unsigned*)((const char*)(gbase) + (voff)[_i]), (PG8_LAS unsigned*)(lds + (bufoff) + ldsw + _i * 8192), 16, 0, 0); } while (0)
; #define PG8_LDA(dst, b, h) do { _Pragma("unroll") for (int m = 0; m < 4; ++m) _Pragma("unroll") for (int k = 0; k < 2; ++k) dst[m][k] = *(const PG8_LAS bf16x8*)(lds + PG8_SA(b, h) + aoff + m * 2048 + k * 1024); } while (0)
; #define PG8_LDB(dst, b, h) do { _Pragma("unroll") for (int n = 0; n < 2; ++n) _Pragma("unroll") for (int k = 0; k < 2; ++k) dst[n][k] = *(const PG8_LAS bf16x8*)(lds + PG8_SB(b, h) + boff + n * 2048 + k * 1024); } while (0)
; #define PG8_WAIT_V(n) asm volatile("s_waitcnt vmcnt(" #n ")" ::: "memory")
; #define PG8_WAIT_L(n) asm volatile("s_waitcnt lgkmcnt(" #n ")" ::: "memory")
; #define PG8_BAR __builtin_amdgcn_s_barrier()
; template <class Epi, class Sched, bool ALIGN_EPI = false, bool SP2 = true>
; __device__ __forceinline__ void gemm_phase(PG8_LAS unsigned char* lds, const Gemm g, const Sched& S, const Epi& E) {
;     ...
;             const char* a3 = a2 + kstep; const char* b3 = b2 + kstep;
;             if (last && has_next) S.a_ready(nxt);
;             if constexpr (SP2) {
;             PG8_LDB(B0, 0, 0); PG8_LDB(B1, 0, 1); PG8_SCHED; PG8_LDA(At, 0, 0); PG8_STAGE(PG8_SA(1, 1), a1 + hstep, voffA);
;             PG8_WAIT_V(8); PG8_WAIT_L(0); PG8_BAR; PG8_MMA(0, 0, At, B0); PG8_MMA(0, 1, At, B1); PG8_BAR; PG8_SCHED;
;             if (full) { PG8_LDA(At, 0, 1); } PG8_STAGE(PG8_SB(0, 0), b2, voffB); PG8_STAGE(PG8_SB(0, 1), b2 + hstep, voffB); PG8_STAGE(PG8_SA(0, 0), a2, voffA);
;             PG8_WAIT_V(8); PG8_WAIT_L(0); PG8_BAR; if (full) { PG8_MMA(1, 0, At, B0); PG8_MMA(1, 1, At, B1); } PG8_BAR; PG8_SCHED;
;             PG8_LDB(B0, 1, 0); PG8_LDB(B1, 1, 1); PG8_SCHED; PG8_LDA(At, 1, 0); PG8_STAGE(PG8_SA(0, 1), a2 + hstep, voffA);
;             PG8_WAIT_V(8); PG8_WAIT_L(0); PG8_BAR; PG8_MMA(0, 0, At, B0); PG8_MMA(0, 1, At, B1); PG8_BAR; PG8_SCHED;
;             if (full) { PG8_LDA(At, 1, 1); } PG8_STAGE(PG8_SB(1, 0), b3, voffB); PG8_STAGE(PG8_SB(1, 1), b3 + hstep, voffB); PG8_STAGE(PG8_SA(1, 0), a3, voffA);
;             PG8_WAIT_V(8); PG8_WAIT_L(0); PG8_BAR; if (full) { PG8_MMA(1, 0, At, B0); PG8_MMA(1, 1, At, B1); } PG8_BAR; PG8_SCHED;
.LBB0_1431:
	s_barrier
	s_setprio 0
	v_add_u32_e32 v3, 0x18000, v199
	ds_read_b128 v[150:153], v3
	ds_read_b128 v[154:157], v3 offset:1024
	ds_read_b128 v[158:161], v3 offset:2048
	ds_read_b128 v[162:165], v3 offset:3072
	v_add_u32_e32 v3, 0x1c000, v199
	ds_read_b128 v[134:137], v3
	ds_read_b128 v[138:141], v3 offset:1024
	ds_read_b128 v[142:145], v3 offset:2048
	ds_read_b128 v[146:149], v3 offset:3072
	s_add_u32 s34, s34, 0x2b0000
	s_addc_u32 s35, s35, 0
	s_mov_b32 m0, s47
	s_waitcnt lgkmcnt(0)
	ds_read_b128 v[178:181], v226 offset:32768
	ds_read_b128 v[194:197], v226 offset:33792
	ds_read_b128 v[174:177], v226 offset:34816
	ds_read_b128 v[190:193], v226 offset:35840
	ds_read_b128 v[170:173], v226 offset:36864
	ds_read_b128 v[186:189], v226 offset:37888
	ds_read_b128 v[166:169], v226 offset:38912
	ds_read_b128 v[182:185], v226 offset:39936
	global_load_lds_dwordx4 v200, s[34:35]
	s_mov_b32 m0, s48
	s_nop 0
	global_load_lds_dwordx4 v204, s[34:35]
	s_waitcnt vmcnt(8)
	s_waitcnt lgkmcnt(0)
	s_setprio 1
	s_barrier
	v_mfma_f32_16x16x32_bf16 v[66:69], v[150:153], v[178:181], v[66:69]
	v_mfma_f32_16x16x32_bf16 v[62:65], v[158:161], v[178:181], v[62:65]
	v_mfma_f32_16x16x32_bf16 v[50:53], v[150:153], v[174:177], v[50:53]
	v_mfma_f32_16x16x32_bf16 v[46:49], v[158:161], v[174:177], v[46:49]
	v_mfma_f32_16x16x32_bf16 v[34:37], v[150:153], v[170:173], v[34:37]
	v_mfma_f32_16x16x32_bf16 v[30:33], v[158:161], v[170:173], v[30:33]
	v_mfma_f32_16x16x32_bf16 v[18:21], v[150:153], v[166:169], v[18:21]
	v_mfma_f32_16x16x32_bf16 v[14:17], v[158:161], v[166:169], v[14:17]
	v_mfma_f32_16x16x32_bf16 v[66:69], v[154:157], v[194:197], v[66:69]
	v_mfma_f32_16x16x32_bf16 v[62:65], v[162:165], v[194:197], v[62:65]
	v_mfma_f32_16x16x32_bf16 v[50:53], v[154:157], v[190:193], v[50:53]
	v_mfma_f32_16x16x32_bf16 v[46:49], v[162:165], v[190:193], v[46:49]
	v_mfma_f32_16x16x32_bf16 v[34:37], v[154:157], v[186:189], v[34:37]
	v_mfma_f32_16x16x32_bf16 v[30:33], v[162:165], v[186:189], v[30:33]
	v_mfma_f32_16x16x32_bf16 v[18:21], v[154:157], v[182:185], v[18:21]
	v_mfma_f32_16x16x32_bf16 v[14:17], v[162:165], v[182:185], v[14:17]
	v_mfma_f32_16x16x32_bf16 v[58:61], v[134:137], v[178:181], v[58:61]
	v_mfma_f32_16x16x32_bf16 v[54:57], v[142:145], v[178:181], v[54:57]
	v_mfma_f32_16x16x32_bf16 v[42:45], v[134:137], v[174:177], v[42:45]
	v_mfma_f32_16x16x32_bf16 v[38:41], v[142:145], v[174:177], v[38:41]
	v_mfma_f32_16x16x32_bf16 v[26:29], v[134:137], v[170:173], v[26:29]
	v_mfma_f32_16x16x32_bf16 v[22:25], v[142:145], v[170:173], v[22:25]
	v_mfma_f32_16x16x32_bf16 v[8:11], v[134:137], v[166:169], v[10:13]
	v_mfma_f32_16x16x32_bf16 v[4:7], v[142:145], v[166:169], v[4:7]
	v_mfma_f32_16x16x32_bf16 v[58:61], v[138:141], v[194:197], v[58:61]
	v_mfma_f32_16x16x32_bf16 v[54:57], v[146:149], v[194:197], v[54:57]
	v_mfma_f32_16x16x32_bf16 v[42:45], v[138:141], v[190:193], v[42:45]
	v_mfma_f32_16x16x32_bf16 v[38:41], v[146:149], v[190:193], v[38:41]
	v_mfma_f32_16x16x32_bf16 v[26:29], v[138:141], v[186:189], v[26:29]
	v_mfma_f32_16x16x32_bf16 v[22:25], v[146:149], v[186:189], v[22:25]
	v_mfma_f32_16x16x32_bf16 v[10:13], v[138:141], v[182:185], v[8:11]
	v_mfma_f32_16x16x32_bf16 v[6:9], v[146:149], v[182:185], v[4:7]
	s_barrier
	s_setprio 0
	s_and_b64 vcc, exec, s[8:9]
	s_cbranch_vccnz .LBB0_1433
	ds_read_b128 v[178:181], v226 offset:49152
	ds_read_b128 v[194:197], v226 offset:50176
	ds_read_b128 v[174:177], v226 offset:51200
	ds_read_b128 v[190:193], v226 offset:52224
	ds_read_b128 v[170:173], v226 offset:53248
	ds_read_b128 v[186:189], v226 offset:54272
	ds_read_b128 v[166:169], v226 offset:55296
	ds_read_b128 v[182:185], v226 offset:56320
.LBB0_1433:
	s_mov_b32 m0, s51
	s_add_u32 s98, s30, 0x80
	s_addc_u32 s99, s31, 0
	s_add_u32 s30, s30, 0x2b0080
	global_load_lds_dwordx4 v202, s[98:99]
	s_mov_b32 m0, s52
	s_addc_u32 s31, s31, 0
	global_load_lds_dwordx4 v206, s[98:99]
	s_mov_b32 m0, s55
	s_and_b64 vcc, exec, s[8:9]
	global_load_lds_dwordx4 v202, s[30:31]
	s_mov_b32 m0, s56
	s_nop 0
	global_load_lds_dwordx4 v206, s[30:31]
	s_mov_b32 m0, s53
	s_nop 0
	s_add_u32 s100, s34, 0xffd50080
	s_addc_u32 s101, s35, -1
	global_load_lds_dwordx4 v200, s[100:101]
	s_mov_b32 m0, s54
	s_nop 0
	global_load_lds_dwordx4 v204, s[100:101]
	s_waitcnt vmcnt(8)
	s_waitcnt lgkmcnt(0)
	s_setprio 1
	s_barrier
	s_cbranch_vccnz .LBB0_1426
	v_mfma_f32_16x16x32_bf16 v[130:133], v[150:153], v[178:181], v[130:133]
	v_mfma_f32_16x16x32_bf16 v[126:129], v[158:161], v[178:181], v[126:129]
	v_mfma_f32_16x16x32_bf16 v[118:121], v[150:153], v[174:177], v[118:121]
	v_mfma_f32_16x16x32_bf16 v[110:113], v[158:161], v[174:177], v[110:113]
	v_mfma_f32_16x16x32_bf16 v[102:105], v[150:153], v[170:173], v[102:105]
	v_mfma_f32_16x16x32_bf16 v[94:97], v[158:161], v[170:173], v[94:97]
	v_mfma_f32_16x16x32_bf16 v[86:89], v[150:153], v[166:169], v[86:89]
	v_mfma_f32_16x16x32_bf16 v[78:81], v[158:161], v[166:169], v[78:81]
	v_mfma_f32_16x16x32_bf16 v[130:133], v[154:157], v[194:197], v[130:133]
	v_mfma_f32_16x16x32_bf16 v[126:129], v[162:165], v[194:197], v[126:129]
	v_mfma_f32_16x16x32_bf16 v[118:121], v[154:157], v[190:193], v[118:121]
	v_mfma_f32_16x16x32_bf16 v[110:113], v[162:165], v[190:193], v[110:113]
	v_mfma_f32_16x16x32_bf16 v[102:105], v[154:157], v[186:189], v[102:105]
	v_mfma_f32_16x16x32_bf16 v[94:97], v[162:165], v[186:189], v[94:97]
	v_mfma_f32_16x16x32_bf16 v[86:89], v[154:157], v[182:185], v[86:89]
	v_mfma_f32_16x16x32_bf16 v[78:81], v[162:165], v[182:185], v[78:81]
	v_mfma_f32_16x16x32_bf16 v[122:125], v[134:137], v[178:181], v[122:125]
	v_mfma_f32_16x16x32_bf16 v[114:117], v[142:145], v[178:181], v[114:117]
	v_mfma_f32_16x16x32_bf16 v[106:109], v[134:137], v[174:177], v[106:109]
	v_mfma_f32_16x16x32_bf16 v[98:101], v[142:145], v[174:177], v[98:101]
	v_mfma_f32_16x16x32_bf16 v[90:93], v[134:137], v[170:173], v[90:93]
	v_mfma_f32_16x16x32_bf16 v[82:85], v[142:145], v[170:173], v[82:85]
	v_mfma_f32_16x16x32_bf16 v[74:77], v[134:137], v[166:169], v[74:77]
	v_mfma_f32_16x16x32_bf16 v[70:73], v[142:145], v[166:169], v[70:73]
	v_mfma_f32_16x16x32_bf16 v[122:125], v[138:141], v[194:197], v[122:125]
	v_mfma_f32_16x16x32_bf16 v[114:117], v[146:149], v[194:197], v[114:117]
	v_mfma_f32_16x16x32_bf16 v[106:109], v[138:141], v[190:193], v[106:109]
	v_mfma_f32_16x16x32_bf16 v[98:101], v[146:149], v[190:193], v[98:101]
	v_mfma_f32_16x16x32_bf16 v[90:93], v[138:141], v[186:189], v[90:93]
	v_mfma_f32_16x16x32_bf16 v[82:85], v[146:149], v[186:189], v[82:85]
	v_mfma_f32_16x16x32_bf16 v[74:77], v[138:141], v[182:185], v[74:77]
	v_mfma_f32_16x16x32_bf16 v[70:73], v[146:149], v[182:185], v[70:73]
	s_branch .LBB0_1426

; __global__ void __launch_bounds__(NWAVES * 64, 2) mk_fwd(Args args) {
;     extern __shared__ __attribute__((aligned(16))) unsigned char lds[];
	.amdhsa_kernel _Z6mk_fwd4Args
		.amdhsa_group_segment_fixed_size 0
		.amdhsa_private_segment_fixed_size 0
		.amdhsa_kernarg_size 512
		.amdhsa_user_sgpr_count 2
		.amdhsa_user_sgpr_dispatch_ptr 0
		.amdhsa_user_sgpr_queue_ptr 0
		.amdhsa_user_sgpr_kernarg_segment_ptr 1
		.amdhsa_user_sgpr_dispatch_id 0
		.amdhsa_user_sgpr_kernarg_preload_length 0
		.amdhsa_user_sgpr_kernarg_preload_offset 0
		.amdhsa_user_sgpr_private_segment_size 0
		.amdhsa_uses_dynamic_stack 0
		.amdhsa_enable_private_segment 0
		.amdhsa_system_sgpr_workgroup_id_x 1
		.amdhsa_system_sgpr_workgroup_id_y 0
		.amdhsa_system_sgpr_workgroup_id_z 0
		.amdhsa_system_sgpr_workgroup_info 0
		.amdhsa_system_vgpr_workitem_id 0
		.amdhsa_next_free_vgpr 237
		.amdhsa_next_free_sgpr 102
		.amdhsa_accum_offset 240
		.amdhsa_reserve_vcc 1
		.amdhsa_float_round_mode_32 0
		.amdhsa_float_round_mode_16_64 0
		.amdhsa_float_denorm_mode_32 3
		.amdhsa_float_denorm_mode_16_64 3
		.amdhsa_dx10_clamp 1
		.amdhsa_ieee_mode 1
		.amdhsa_fp16_overflow 0
		.amdhsa_tg_split 0
		.amdhsa_exception_fp_ieee_invalid_op 0
		.amdhsa_exception_fp_denorm_src 0
		.amdhsa_exception_fp_ieee_div_zero 0
		.amdhsa_exception_fp_ieee_overflow 0
		.amdhsa_exception_fp_ieee_underflow 0
		.amdhsa_exception_fp_ieee_inexact 0
		.amdhsa_exception_int_div_zero 0
	.end_amdhsa_kernel
